# GEMM template A/B: all per-segment s_setprio flips deleted from the k-loops (attention static raise kept)
# speedup vs baseline: 1.0164x; 1.0164x over previous
; #define PG8_STAGE(bufoff, gbase, voff) do { _Pragma("unroll") for (int _i = 0; _i < 2; ++_i) \
;         __builtin_amdgcn_global_load_lds((const unsigned*)((const char*)(gbase) + (voff)[_i]), (LAS unsigned*)(lds + (bufoff) + ldsw + _i * 8192), 16, 0, 0); } while (0)
; #define PG8_LDA(dst, b, h) do { _Pragma("unroll") for (int m = 0; m < 4; ++m) _Pragma("unroll") for (int k = 0; k < 2; ++k) dst[m][k] = *(const LAS bf16x8*)(lds + PG8_SA(b, h) + aoff + m * 2048 + k * 1024); } while (0)
; #define PG8_LDB(dst, b, h) do { _Pragma("unroll") for (int n = 0; n < 2; ++n) _Pragma("unroll") for (int k = 0; k < 2; ++k) dst[n][k] = *(const LAS bf16x8*)(lds + PG8_SB(b, h) + boff + n * 2048 + k * 1024); } while (0)
; #define PG8_MMA(ai, bj, At, Bt) do { __builtin_amdgcn_s_setprio(1); _Pragma("unroll") for (int m = 0; m < 4; ++m) _Pragma("unroll") for (int n = 0; n < 2; ++n) _Pragma("unroll") for (int k = 0; k < 2; ++k) \
;         acc[ai][bj][m][n] = __builtin_amdgcn_mfma_f32_16x16x32_bf16(Bt[n][k], At[m][k], acc[ai][bj][m][n], 0, 0, 0); __builtin_amdgcn_s_setprio(0); } while (0)
; #define PG8_WAIT_V(n) asm volatile("s_waitcnt vmcnt(" #n ")" ::: "memory")
; #define PG8_WAIT_L(n) asm volatile("s_waitcnt lgkmcnt(" #n ")" ::: "memory")
; #define PG8_BAR __builtin_amdgcn_s_barrier()
; #define PG8_SCHED __builtin_amdgcn_sched_barrier(0)
; template <class Epi, class Sched>
; __device__ __forceinline__ void gemm_phase(LAS unsigned char* lds, const int K, const int lda, const int ldb, const Sched& S, const Epi& E) {
;     ...
;         for (int t = 0; t < nt; t += 2) {
;             const bool last = (t == nt - 2);
;             const char* a1 = cA + (size_t)(t + 1) * kstep;
;             const char* a2 = last ? nA : cA + (size_t)(t + 2) * kstep; const char* b2 = last ? nB : cB + (size_t)(t + 2) * kstep;
;             const char* a3 = a2 + kstep; const char* b3 = b2 + kstep;
;             PG8_LDB(B0, 0, 0); PG8_LDB(B1, 0, 1); PG8_SCHED; PG8_LDA(At, 0, 0); PG8_STAGE(PG8_SA(1, 1), a1 + hA, voffA);
;             PG8_WAIT_V(8); PG8_WAIT_L(0); PG8_BAR; PG8_MMA(0, 0, At, B0); PG8_MMA(0, 1, At, B1); PG8_BAR; PG8_SCHED;
;             PG8_LDA(At, 0, 1); PG8_STAGE(PG8_SB(0, 0), b2, voffB); PG8_STAGE(PG8_SB(0, 1), b2 + hB, voffB); PG8_STAGE(PG8_SA(0, 0), a2, voffA);
.LBB0_209:
	ds_read_b128 v[174:177], v188
	ds_read_b128 v[178:181], v147
	ds_read_b128 v[190:193], v188 offset:2048
	ds_read_b128 v[194:197], v147 offset:2048
	ds_read_b128 v[198:201], v189
	ds_read_b128 v[202:205], v149
	ds_read_b128 v[206:209], v189 offset:2048
	ds_read_b128 v[210:213], v149 offset:2048
	s_add_u32 s49, s54, 0xfff80080
	s_addc_u32 s56, s55, -1
	s_cmp_eq_u32 s47, 28
	s_cselect_b32 s59, s7, s56
	s_cselect_b32 s58, s18, s49
	s_cselect_b32 s57, s19, s45
	s_cselect_b32 s56, s20, s43
	v_lshl_add_u64 v[182:183], s[54:55], 0, v[140:141]
	s_add_i32 m0, s1, 0xc000
	ds_read_b128 v[214:217], v163
	ds_read_b128 v[218:221], v145
	ds_read_b128 v[222:225], v163 offset:2048
	ds_read_b128 v[226:229], v145 offset:2048
	ds_read_b128 v[230:233], v163 offset:4096
	ds_read_b128 v[236:239], v145 offset:4096
	ds_read_b128 v[240:243], v163 offset:6144
	ds_read_b128 v[244:247], v145 offset:6144
	global_load_lds_dwordx4 v[182:183], off
	v_lshl_add_u64 v[182:183], s[54:55], 0, v[138:139]
	s_add_i32 m0, s1, 0xe000
	s_nop 0
	global_load_lds_dwordx4 v[182:183], off
	s_waitcnt vmcnt(8)
	s_waitcnt lgkmcnt(0)
	s_barrier
	s_waitcnt lgkmcnt(0)
	v_mfma_f32_16x16x32_bf16 v[124:127], v[214:217], v[174:177], v[124:127]
	v_mfma_f32_16x16x32_bf16 v[120:123], v[214:217], v[190:193], v[120:123]
	v_mfma_f32_16x16x32_bf16 v[108:111], v[222:225], v[174:177], v[108:111]
	v_mfma_f32_16x16x32_bf16 v[104:107], v[222:225], v[190:193], v[104:107]
	v_mfma_f32_16x16x32_bf16 v[92:95], v[230:233], v[174:177], v[92:95]
	v_mfma_f32_16x16x32_bf16 v[88:91], v[230:233], v[190:193], v[88:91]
	v_mfma_f32_16x16x32_bf16 v[76:79], v[240:243], v[174:177], v[76:79]
	v_mfma_f32_16x16x32_bf16 v[72:75], v[240:243], v[190:193], v[72:75]
	v_mfma_f32_16x16x32_bf16 v[124:127], v[218:221], v[178:181], v[124:127]
	v_mfma_f32_16x16x32_bf16 v[120:123], v[218:221], v[194:197], v[120:123]
	v_mfma_f32_16x16x32_bf16 v[108:111], v[226:229], v[178:181], v[108:111]
	v_mfma_f32_16x16x32_bf16 v[104:107], v[226:229], v[194:197], v[104:107]
	v_mfma_f32_16x16x32_bf16 v[92:95], v[236:239], v[178:181], v[92:95]
	v_mfma_f32_16x16x32_bf16 v[88:91], v[236:239], v[194:197], v[88:91]
	v_mfma_f32_16x16x32_bf16 v[76:79], v[244:247], v[178:181], v[76:79]
	v_mfma_f32_16x16x32_bf16 v[72:75], v[244:247], v[194:197], v[72:75]
	v_mfma_f32_16x16x32_bf16 v[116:119], v[214:217], v[198:201], v[116:119]
	v_mfma_f32_16x16x32_bf16 v[112:115], v[214:217], v[206:209], v[112:115]
	v_mfma_f32_16x16x32_bf16 v[100:103], v[222:225], v[198:201], v[100:103]
	v_mfma_f32_16x16x32_bf16 v[96:99], v[222:225], v[206:209], v[96:99]
	v_mfma_f32_16x16x32_bf16 v[84:87], v[230:233], v[198:201], v[84:87]
	v_mfma_f32_16x16x32_bf16 v[80:83], v[230:233], v[206:209], v[80:83]
	v_mfma_f32_16x16x32_bf16 v[68:71], v[240:243], v[198:201], v[68:71]
	v_mfma_f32_16x16x32_bf16 v[64:67], v[240:243], v[206:209], v[64:67]
	v_mfma_f32_16x16x32_bf16 v[116:119], v[218:221], v[202:205], v[116:119]
	v_mfma_f32_16x16x32_bf16 v[112:115], v[218:221], v[210:213], v[112:115]
	v_mfma_f32_16x16x32_bf16 v[100:103], v[226:229], v[202:205], v[100:103]
	v_mfma_f32_16x16x32_bf16 v[96:99], v[226:229], v[210:213], v[96:99]
	v_mfma_f32_16x16x32_bf16 v[84:87], v[236:239], v[202:205], v[84:87]
	v_mfma_f32_16x16x32_bf16 v[80:83], v[236:239], v[210:213], v[80:83]
	v_mfma_f32_16x16x32_bf16 v[68:71], v[244:247], v[202:205], v[68:71]
	v_mfma_f32_16x16x32_bf16 v[64:67], v[244:247], v[210:213], v[64:67]
	s_barrier
	s_add_i32 s49, s68, s2
	v_lshl_add_u64 v[182:183], s[56:57], 0, v[132:133]
	s_mov_b32 m0, s49
	ds_read_b128 v[214:217], v163 offset:16384
	ds_read_b128 v[218:221], v145 offset:16384
	ds_read_b128 v[222:225], v163 offset:18432
	ds_read_b128 v[226:229], v145 offset:18432
	ds_read_b128 v[230:233], v163 offset:20480
	ds_read_b128 v[236:239], v145 offset:20480
	ds_read_b128 v[240:243], v163 offset:22528
	ds_read_b128 v[244:247], v145 offset:22528
	global_load_lds_dwordx4 v[182:183], off
	s_add_i32 m0, s49, 0x2000
	s_add_u32 s60, s56, 0x80000
	v_lshl_add_u64 v[248:249], s[56:57], 0, v[128:129]
	s_addc_u32 s61, s57, 0
	s_add_i32 s49, s69, s2
	global_load_lds_dwordx4 v[248:249], off
	v_lshl_add_u64 v[250:251], s[60:61], 0, v[132:133]
	s_mov_b32 m0, s49
	v_lshl_add_u64 v[252:253], s[58:59], 0, v[130:131]
	global_load_lds_dwordx4 v[250:251], off
	v_lshl_add_u64 v[250:251], s[60:61], 0, v[128:129]
	s_add_i32 m0, s49, 0x2000
	s_nop 0
	global_load_lds_dwordx4 v[250:251], off
	v_lshl_add_u64 v[250:251], s[58:59], 0, v[134:135]
	s_mov_b32 m0, s1
	s_nop 0
	global_load_lds_dwordx4 v[250:251], off
	s_mov_b32 m0, s17
	s_nop 0
	global_load_lds_dwordx4 v[252:253], off
	s_waitcnt vmcnt(8)
	s_waitcnt lgkmcnt(0)
	s_barrier
; #define PG8_STAGE(bufoff, gbase, voff) do { _Pragma("unroll") for (int _i = 0; _i < 2; ++_i) \
;         __builtin_amdgcn_global_load_lds((const unsigned*)((const char*)(gbase) + (voff)[_i]), (LAS unsigned*)(lds + (bufoff) + ldsw + _i * 8192), 16, 0, 0); } while (0)
; #define PG8_LDA(dst, b, h) do { _Pragma("unroll") for (int m = 0; m < 4; ++m) _Pragma("unroll") for (int k = 0; k < 2; ++k) dst[m][k] = *(const LAS bf16x8*)(lds + PG8_SA(b, h) + aoff + m * 2048 + k * 1024); } while (0)
; #define PG8_LDB(dst, b, h) do { _Pragma("unroll") for (int n = 0; n < 2; ++n) _Pragma("unroll") for (int k = 0; k < 2; ++k) dst[n][k] = *(const LAS bf16x8*)(lds + PG8_SB(b, h) + boff + n * 2048 + k * 1024); } while (0)
; #define PG8_MMA(ai, bj, At, Bt) do { __builtin_amdgcn_s_setprio(1); _Pragma("unroll") for (int m = 0; m < 4; ++m) _Pragma("unroll") for (int n = 0; n < 2; ++n) _Pragma("unroll") for (int k = 0; k < 2; ++k) \
;         acc[ai][bj][m][n] = __builtin_amdgcn_mfma_f32_16x16x32_bf16(Bt[n][k], At[m][k], acc[ai][bj][m][n], 0, 0, 0); __builtin_amdgcn_s_setprio(0); } while (0)
; #define PG8_WAIT_V(n) asm volatile("s_waitcnt vmcnt(" #n ")" ::: "memory")
; #define PG8_WAIT_L(n) asm volatile("s_waitcnt lgkmcnt(" #n ")" ::: "memory")
; #define PG8_BAR __builtin_amdgcn_s_barrier()
; #define PG8_SCHED __builtin_amdgcn_sched_barrier(0)
; template <class Epi, class Sched>
; __device__ __forceinline__ void gemm_phase(LAS unsigned char* lds, const int K, const int lda, const int ldb, const Sched& S, const Epi& E) {
;     ...
;             PG8_WAIT_V(8); PG8_WAIT_L(0); PG8_BAR; PG8_MMA(1, 0, At, B0); PG8_MMA(1, 1, At, B1); PG8_BAR; PG8_SCHED;
;             PG8_LDB(B0, 1, 0); PG8_LDB(B1, 1, 1); PG8_SCHED; PG8_LDA(At, 1, 0); PG8_STAGE(PG8_SA(0, 1), a2 + hA, voffA);
;             PG8_WAIT_V(8); PG8_WAIT_L(0); PG8_BAR; PG8_MMA(0, 0, At, B0); PG8_MMA(0, 1, At, B1); PG8_BAR; PG8_SCHED;
	s_waitcnt lgkmcnt(0)
	v_mfma_f32_16x16x32_bf16 v[60:63], v[214:217], v[174:177], v[60:63]
	v_mfma_f32_16x16x32_bf16 v[56:59], v[214:217], v[190:193], v[56:59]
	v_mfma_f32_16x16x32_bf16 v[44:47], v[222:225], v[174:177], v[44:47]
	v_mfma_f32_16x16x32_bf16 v[40:43], v[222:225], v[190:193], v[40:43]
	v_mfma_f32_16x16x32_bf16 v[28:31], v[230:233], v[174:177], v[28:31]
	v_mfma_f32_16x16x32_bf16 v[24:27], v[230:233], v[190:193], v[24:27]
	v_mfma_f32_16x16x32_bf16 v[12:15], v[240:243], v[174:177], v[12:15]
	v_mfma_f32_16x16x32_bf16 v[8:11], v[240:243], v[190:193], v[8:11]
	v_mfma_f32_16x16x32_bf16 v[60:63], v[218:221], v[178:181], v[60:63]
	v_mfma_f32_16x16x32_bf16 v[56:59], v[218:221], v[194:197], v[56:59]
	v_mfma_f32_16x16x32_bf16 v[44:47], v[226:229], v[178:181], v[44:47]
	v_mfma_f32_16x16x32_bf16 v[40:43], v[226:229], v[194:197], v[40:43]
	v_mfma_f32_16x16x32_bf16 v[28:31], v[236:239], v[178:181], v[28:31]
	v_mfma_f32_16x16x32_bf16 v[24:27], v[236:239], v[194:197], v[24:27]
	v_mfma_f32_16x16x32_bf16 v[12:15], v[244:247], v[178:181], v[12:15]
	v_mfma_f32_16x16x32_bf16 v[8:11], v[244:247], v[194:197], v[8:11]
	v_mfma_f32_16x16x32_bf16 v[52:55], v[214:217], v[198:201], v[52:55]
	v_mfma_f32_16x16x32_bf16 v[48:51], v[214:217], v[206:209], v[48:51]
	v_mfma_f32_16x16x32_bf16 v[36:39], v[222:225], v[198:201], v[36:39]
	v_mfma_f32_16x16x32_bf16 v[32:35], v[222:225], v[206:209], v[32:35]
	v_mfma_f32_16x16x32_bf16 v[20:23], v[230:233], v[198:201], v[20:23]
	v_mfma_f32_16x16x32_bf16 v[16:19], v[230:233], v[206:209], v[16:19]
	v_mfma_f32_16x16x32_bf16 v[4:7], v[240:243], v[198:201], v[4:7]
	v_mfma_f32_16x16x32_bf16 v[0:3], v[240:243], v[206:209], v[0:3]
	v_mfma_f32_16x16x32_bf16 v[52:55], v[218:221], v[202:205], v[52:55]
	v_mfma_f32_16x16x32_bf16 v[48:51], v[218:221], v[210:213], v[48:51]
	v_mfma_f32_16x16x32_bf16 v[36:39], v[226:229], v[202:205], v[36:39]
	v_mfma_f32_16x16x32_bf16 v[32:35], v[226:229], v[210:213], v[32:35]
	v_mfma_f32_16x16x32_bf16 v[20:23], v[236:239], v[202:205], v[20:23]
	v_mfma_f32_16x16x32_bf16 v[16:19], v[236:239], v[210:213], v[16:19]
	v_mfma_f32_16x16x32_bf16 v[4:7], v[244:247], v[202:205], v[4:7]
	v_mfma_f32_16x16x32_bf16 v[0:3], v[244:247], v[210:213], v[0:3]
	s_barrier
	s_add_i32 s49, 0, 0x18000
	v_add_u32_e32 v143, s49, v161
	v_add_u32_e32 v158, s49, v151
	s_add_i32 s60, 0, 0x1c000
	ds_read_b128 v[174:177], v143
	ds_read_b128 v[178:181], v158
	ds_read_b128 v[190:193], v143 offset:2048
	ds_read_b128 v[194:197], v158 offset:2048
	v_add_u32_e32 v143, 0x19000, v161
	v_add_u32_e32 v158, 0x19000, v151
	ds_read_b128 v[198:201], v143
	ds_read_b128 v[202:205], v158
	ds_read_b128 v[206:209], v143 offset:2048
	ds_read_b128 v[210:213], v158 offset:2048
	s_add_u32 s58, s58, 0x80000
	s_addc_u32 s59, s59, 0
	s_mov_b32 m0, s29
	v_lshl_add_u64 v[234:235], s[58:59], 0, v[134:135]
	ds_read_b128 v[214:217], v163 offset:32768
	ds_read_b128 v[218:221], v145 offset:32768
	ds_read_b128 v[222:225], v163 offset:34816
	ds_read_b128 v[226:229], v145 offset:34816
	ds_read_b128 v[230:233], v163 offset:36864
	ds_read_b128 v[236:239], v145 offset:36864
	ds_read_b128 v[240:243], v163 offset:38912
	ds_read_b128 v[244:247], v145 offset:38912
	global_load_lds_dwordx4 v[234:235], off
	v_lshl_add_u64 v[234:235], s[58:59], 0, v[130:131]
	s_mov_b32 m0, s34
	s_nop 0
	global_load_lds_dwordx4 v[234:235], off
	s_waitcnt vmcnt(8)
	s_waitcnt lgkmcnt(0)
	s_barrier
	s_waitcnt lgkmcnt(0)
	v_mfma_f32_16x16x32_bf16 v[124:127], v[214:217], v[174:177], v[124:127]
	v_mfma_f32_16x16x32_bf16 v[120:123], v[214:217], v[190:193], v[120:123]
	v_mfma_f32_16x16x32_bf16 v[108:111], v[222:225], v[174:177], v[108:111]
	v_mfma_f32_16x16x32_bf16 v[104:107], v[222:225], v[190:193], v[104:107]
	v_mfma_f32_16x16x32_bf16 v[92:95], v[230:233], v[174:177], v[92:95]
	v_mfma_f32_16x16x32_bf16 v[88:91], v[230:233], v[190:193], v[88:91]
	v_mfma_f32_16x16x32_bf16 v[76:79], v[240:243], v[174:177], v[76:79]
	v_mfma_f32_16x16x32_bf16 v[72:75], v[240:243], v[190:193], v[72:75]
	v_mfma_f32_16x16x32_bf16 v[124:127], v[218:221], v[178:181], v[124:127]
	v_mfma_f32_16x16x32_bf16 v[120:123], v[218:221], v[194:197], v[120:123]
	v_mfma_f32_16x16x32_bf16 v[108:111], v[226:229], v[178:181], v[108:111]
	v_mfma_f32_16x16x32_bf16 v[104:107], v[226:229], v[194:197], v[104:107]
	v_mfma_f32_16x16x32_bf16 v[92:95], v[236:239], v[178:181], v[92:95]
	v_mfma_f32_16x16x32_bf16 v[88:91], v[236:239], v[194:197], v[88:91]
	v_mfma_f32_16x16x32_bf16 v[76:79], v[244:247], v[178:181], v[76:79]
	v_mfma_f32_16x16x32_bf16 v[72:75], v[244:247], v[194:197], v[72:75]
	v_mfma_f32_16x16x32_bf16 v[116:119], v[214:217], v[198:201], v[116:119]
	v_mfma_f32_16x16x32_bf16 v[112:115], v[214:217], v[206:209], v[112:115]
	v_mfma_f32_16x16x32_bf16 v[100:103], v[222:225], v[198:201], v[100:103]
	v_mfma_f32_16x16x32_bf16 v[96:99], v[222:225], v[206:209], v[96:99]
	v_mfma_f32_16x16x32_bf16 v[84:87], v[230:233], v[198:201], v[84:87]
	v_mfma_f32_16x16x32_bf16 v[80:83], v[230:233], v[206:209], v[80:83]
	v_mfma_f32_16x16x32_bf16 v[68:71], v[240:243], v[198:201], v[68:71]
	v_mfma_f32_16x16x32_bf16 v[64:67], v[240:243], v[206:209], v[64:67]
	v_mfma_f32_16x16x32_bf16 v[116:119], v[218:221], v[202:205], v[116:119]
	v_mfma_f32_16x16x32_bf16 v[112:115], v[218:221], v[210:213], v[112:115]
	v_mfma_f32_16x16x32_bf16 v[100:103], v[226:229], v[202:205], v[100:103]
	v_mfma_f32_16x16x32_bf16 v[96:99], v[226:229], v[210:213], v[96:99]
	v_mfma_f32_16x16x32_bf16 v[84:87], v[236:239], v[202:205], v[84:87]
	v_mfma_f32_16x16x32_bf16 v[80:83], v[236:239], v[210:213], v[80:83]
	v_mfma_f32_16x16x32_bf16 v[68:71], v[244:247], v[202:205], v[68:71]
	v_mfma_f32_16x16x32_bf16 v[64:67], v[244:247], v[210:213], v[64:67]
	s_barrier
; #define PG8_STAGE(bufoff, gbase, voff) do { _Pragma("unroll") for (int _i = 0; _i < 2; ++_i) \
;         __builtin_amdgcn_global_load_lds((const unsigned*)((const char*)(gbase) + (voff)[_i]), (LAS unsigned*)(lds + (bufoff) + ldsw + _i * 8192), 16, 0, 0); } while (0)
; #define PG8_LDA(dst, b, h) do { _Pragma("unroll") for (int m = 0; m < 4; ++m) _Pragma("unroll") for (int k = 0; k < 2; ++k) dst[m][k] = *(const LAS bf16x8*)(lds + PG8_SA(b, h) + aoff + m * 2048 + k * 1024); } while (0)
; #define PG8_MMA(ai, bj, At, Bt) do { __builtin_amdgcn_s_setprio(1); _Pragma("unroll") for (int m = 0; m < 4; ++m) _Pragma("unroll") for (int n = 0; n < 2; ++n) _Pragma("unroll") for (int k = 0; k < 2; ++k) \
;         acc[ai][bj][m][n] = __builtin_amdgcn_mfma_f32_16x16x32_bf16(Bt[n][k], At[m][k], acc[ai][bj][m][n], 0, 0, 0); __builtin_amdgcn_s_setprio(0); } while (0)
; #define PG8_WAIT_V(n) asm volatile("s_waitcnt vmcnt(" #n ")" ::: "memory")
; #define PG8_WAIT_L(n) asm volatile("s_waitcnt lgkmcnt(" #n ")" ::: "memory")
; #define PG8_BAR __builtin_amdgcn_s_barrier()
; #define PG8_SCHED __builtin_amdgcn_sched_barrier(0)
; template <class Epi, class Sched>
; __device__ __forceinline__ void gemm_phase(LAS unsigned char* lds, const int K, const int lda, const int ldb, const Sched& S, const Epi& E) {
;     ...
;             PG8_LDA(At, 1, 1); PG8_STAGE(PG8_SB(1, 0), b3, voffB); PG8_STAGE(PG8_SB(1, 1), b3 + hB, voffB); PG8_STAGE(PG8_SA(1, 0), a3, voffA);
;             PG8_WAIT_V(8); PG8_WAIT_L(0); PG8_BAR; PG8_MMA(1, 0, At, B0); PG8_MMA(1, 1, At, B1); PG8_BAR; PG8_SCHED;
;         }
;         if (wr == 0) PG8_BAR;
	s_add_i32 s49, s49, s2
	v_lshl_add_u64 v[182:183], v[182:183], 0, s[22:23]
	s_mov_b32 m0, s49
	ds_read_b128 v[214:217], v163 offset:49152
	ds_read_b128 v[218:221], v145 offset:49152
	ds_read_b128 v[222:225], v163 offset:51200
	ds_read_b128 v[226:229], v145 offset:51200
	ds_read_b128 v[230:233], v163 offset:53248
	ds_read_b128 v[236:239], v145 offset:53248
	ds_read_b128 v[240:243], v163 offset:55296
	ds_read_b128 v[244:247], v145 offset:55296
	global_load_lds_dwordx4 v[182:183], off
	s_add_i32 m0, s49, 0x2000
	s_add_u32 s56, s56, 0x80080
	v_lshl_add_u64 v[182:183], v[248:249], 0, s[22:23]
	s_addc_u32 s57, s57, 0
	s_add_i32 s49, s60, s2
	global_load_lds_dwordx4 v[182:183], off
	v_lshl_add_u64 v[182:183], s[56:57], 0, v[132:133]
	s_mov_b32 m0, s49
	s_nop 0
	global_load_lds_dwordx4 v[182:183], off
	v_lshl_add_u64 v[182:183], s[56:57], 0, v[128:129]
	s_add_i32 m0, s49, 0x2000
	s_nop 0
	global_load_lds_dwordx4 v[182:183], off
	v_lshl_add_u64 v[182:183], v[250:251], 0, s[22:23]
	s_mov_b32 m0, s38
	s_nop 0
	global_load_lds_dwordx4 v[182:183], off
	v_lshl_add_u64 v[182:183], v[252:253], 0, s[22:23]
	s_mov_b32 m0, s39
	s_nop 0
	global_load_lds_dwordx4 v[182:183], off
	s_waitcnt vmcnt(8)
	s_waitcnt lgkmcnt(0)
	s_barrier
	s_waitcnt lgkmcnt(0)
	v_mfma_f32_16x16x32_bf16 v[60:63], v[214:217], v[174:177], v[60:63]
	v_mfma_f32_16x16x32_bf16 v[56:59], v[214:217], v[190:193], v[56:59]
	v_mfma_f32_16x16x32_bf16 v[44:47], v[222:225], v[174:177], v[44:47]
	v_mfma_f32_16x16x32_bf16 v[40:43], v[222:225], v[190:193], v[40:43]
	v_mfma_f32_16x16x32_bf16 v[28:31], v[230:233], v[174:177], v[28:31]
	v_mfma_f32_16x16x32_bf16 v[24:27], v[230:233], v[190:193], v[24:27]
	v_mfma_f32_16x16x32_bf16 v[12:15], v[240:243], v[174:177], v[12:15]
	v_mfma_f32_16x16x32_bf16 v[8:11], v[240:243], v[190:193], v[8:11]
	v_mfma_f32_16x16x32_bf16 v[60:63], v[218:221], v[178:181], v[60:63]
	v_mfma_f32_16x16x32_bf16 v[56:59], v[218:221], v[194:197], v[56:59]
	v_mfma_f32_16x16x32_bf16 v[44:47], v[226:229], v[178:181], v[44:47]
	v_mfma_f32_16x16x32_bf16 v[40:43], v[226:229], v[194:197], v[40:43]
	v_mfma_f32_16x16x32_bf16 v[28:31], v[236:239], v[178:181], v[28:31]
	v_mfma_f32_16x16x32_bf16 v[24:27], v[236:239], v[194:197], v[24:27]
	v_mfma_f32_16x16x32_bf16 v[12:15], v[244:247], v[178:181], v[12:15]
	v_mfma_f32_16x16x32_bf16 v[8:11], v[244:247], v[194:197], v[8:11]
	v_mfma_f32_16x16x32_bf16 v[52:55], v[214:217], v[198:201], v[52:55]
	v_mfma_f32_16x16x32_bf16 v[48:51], v[214:217], v[206:209], v[48:51]
	v_mfma_f32_16x16x32_bf16 v[36:39], v[222:225], v[198:201], v[36:39]
	v_mfma_f32_16x16x32_bf16 v[32:35], v[222:225], v[206:209], v[32:35]
	v_mfma_f32_16x16x32_bf16 v[20:23], v[230:233], v[198:201], v[20:23]
	v_mfma_f32_16x16x32_bf16 v[16:19], v[230:233], v[206:209], v[16:19]
	v_mfma_f32_16x16x32_bf16 v[4:7], v[240:243], v[198:201], v[4:7]
	v_mfma_f32_16x16x32_bf16 v[0:3], v[240:243], v[206:209], v[0:3]
	v_mfma_f32_16x16x32_bf16 v[52:55], v[218:221], v[202:205], v[52:55]
	v_mfma_f32_16x16x32_bf16 v[48:51], v[218:221], v[210:213], v[48:51]
	v_mfma_f32_16x16x32_bf16 v[36:39], v[226:229], v[202:205], v[36:39]
	v_mfma_f32_16x16x32_bf16 v[32:35], v[226:229], v[210:213], v[32:35]
	v_mfma_f32_16x16x32_bf16 v[20:23], v[236:239], v[202:205], v[20:23]
	v_mfma_f32_16x16x32_bf16 v[16:19], v[236:239], v[210:213], v[16:19]
	v_mfma_f32_16x16x32_bf16 v[4:7], v[244:247], v[202:205], v[4:7]
	v_mfma_f32_16x16x32_bf16 v[0:3], v[244:247], v[210:213], v[0:3]
	s_barrier
	s_add_i32 s47, s47, 2
	s_add_u32 s43, s43, 0x100
	s_addc_u32 s45, s45, 0
	s_add_u32 s54, s54, 0x100
	s_addc_u32 s55, s55, 0
	s_cmp_gt_u32 s47, 29
	s_cbranch_scc0 .LBB0_209
	s_and_b64 vcc, exec, s[24:25]
	s_cbranch_vccz .LBB0_212
	s_barrier

; #define PG8_STAGE(bufoff, gbase, voff) do { _Pragma("unroll") for (int _i = 0; _i < 2; ++_i) \
;         __builtin_amdgcn_global_load_lds((const unsigned*)((const char*)(gbase) + (voff)[_i]), (LAS unsigned*)(lds + (bufoff) + ldsw + _i * 8192), 16, 0, 0); } while (0)
; #define PG8_LDA(dst, b, h) do { _Pragma("unroll") for (int m = 0; m < 4; ++m) _Pragma("unroll") for (int k = 0; k < 2; ++k) dst[m][k] = *(const LAS bf16x8*)(lds + PG8_SA(b, h) + aoff + m * 2048 + k * 1024); } while (0)
; #define PG8_LDB(dst, b, h) do { _Pragma("unroll") for (int n = 0; n < 2; ++n) _Pragma("unroll") for (int k = 0; k < 2; ++k) dst[n][k] = *(const LAS bf16x8*)(lds + PG8_SB(b, h) + boff + n * 2048 + k * 1024); } while (0)
; #define PG8_MMA(ai, bj, At, Bt) do { __builtin_amdgcn_s_setprio(1); _Pragma("unroll") for (int m = 0; m < 4; ++m) _Pragma("unroll") for (int n = 0; n < 2; ++n) _Pragma("unroll") for (int k = 0; k < 2; ++k) \
;         acc[ai][bj][m][n] = __builtin_amdgcn_mfma_f32_16x16x32_bf16(Bt[n][k], At[m][k], acc[ai][bj][m][n], 0, 0, 0); __builtin_amdgcn_s_setprio(0); } while (0)
; #define PG8_WAIT_V(n) asm volatile("s_waitcnt vmcnt(" #n ")" ::: "memory")
; #define PG8_WAIT_L(n) asm volatile("s_waitcnt lgkmcnt(" #n ")" ::: "memory")
; #define PG8_BAR __builtin_amdgcn_s_barrier()
; #define PG8_SCHED __builtin_amdgcn_sched_barrier(0)
; template <class Epi, class Sched>
; __device__ __forceinline__ void gemm_phase(LAS unsigned char* lds, const int K, const int lda, const int ldb, const Sched& S, const Epi& E) {
;     ...
;         for (int t = 0; t < nt; t += 2) {
;             const bool last = (t == nt - 2);
;             const char* a1 = cA + (size_t)(t + 1) * kstep;
;             const char* a2 = last ? nA : cA + (size_t)(t + 2) * kstep; const char* b2 = last ? nB : cB + (size_t)(t + 2) * kstep;
;             const char* a3 = a2 + kstep; const char* b3 = b2 + kstep;
;             PG8_LDB(B0, 0, 0); PG8_LDB(B1, 0, 1); PG8_SCHED; PG8_LDA(At, 0, 0); PG8_STAGE(PG8_SA(1, 1), a1 + hA, voffA);
;             PG8_WAIT_V(8); PG8_WAIT_L(0); PG8_BAR; PG8_MMA(0, 0, At, B0); PG8_MMA(0, 1, At, B1); PG8_BAR; PG8_SCHED;
;             PG8_LDA(At, 0, 1); PG8_STAGE(PG8_SB(0, 0), b2, voffB); PG8_STAGE(PG8_SB(0, 1), b2 + hB, voffB); PG8_STAGE(PG8_SA(0, 0), a2, voffA);
.LBB0_427:
	ds_read_b128 v[156:159], v151
	ds_read_b128 v[160:163], v151 offset:1024
	ds_read_b128 v[164:167], v151 offset:2048
	ds_read_b128 v[168:171], v151 offset:3072
	ds_read_b128 v[172:175], v152
	ds_read_b128 v[176:179], v152 offset:1024
	ds_read_b128 v[180:183], v152 offset:2048
	ds_read_b128 v[184:187], v152 offset:3072
	s_add_u32 s60, s8, 0xfff00080
	s_addc_u32 s61, s9, -1
	s_cmp_eq_u32 s78, 28
	s_cselect_b32 s63, s51, s61
	s_cselect_b32 s62, s50, s60
	s_cselect_b32 s61, s57, s59
	s_cselect_b32 s60, s56, s55
	v_lshl_add_u64 v[146:147], s[8:9], 0, v[140:141]
	s_add_i32 m0, s21, 0xc000
	ds_read_b128 v[188:191], v153
	ds_read_b128 v[192:195], v153 offset:1024
	ds_read_b128 v[196:199], v153 offset:2048
	ds_read_b128 v[200:203], v153 offset:3072
	ds_read_b128 v[204:207], v153 offset:4096
	ds_read_b128 v[208:211], v153 offset:5120
	ds_read_b128 v[212:215], v153 offset:6144
	ds_read_b128 v[216:219], v153 offset:7168
	global_load_lds_dwordx4 v[146:147], off
	v_lshl_add_u64 v[146:147], s[8:9], 0, v[138:139]
	s_add_i32 m0, s21, 0xe000
	s_nop 0
	global_load_lds_dwordx4 v[146:147], off
	s_waitcnt vmcnt(8)
	s_waitcnt lgkmcnt(0)
	s_barrier
	s_waitcnt lgkmcnt(0)
	v_mfma_f32_16x16x32_bf16 v[124:127], v[156:159], v[188:191], v[124:127]
	v_mfma_f32_16x16x32_bf16 v[120:123], v[164:167], v[188:191], v[120:123]
	v_mfma_f32_16x16x32_bf16 v[108:111], v[156:159], v[196:199], v[108:111]
	v_mfma_f32_16x16x32_bf16 v[104:107], v[164:167], v[196:199], v[104:107]
	v_mfma_f32_16x16x32_bf16 v[92:95], v[156:159], v[204:207], v[92:95]
	v_mfma_f32_16x16x32_bf16 v[88:91], v[164:167], v[204:207], v[88:91]
	v_mfma_f32_16x16x32_bf16 v[76:79], v[156:159], v[212:215], v[76:79]
	v_mfma_f32_16x16x32_bf16 v[72:75], v[164:167], v[212:215], v[72:75]
	v_mfma_f32_16x16x32_bf16 v[124:127], v[160:163], v[192:195], v[124:127]
	v_mfma_f32_16x16x32_bf16 v[120:123], v[168:171], v[192:195], v[120:123]
	v_mfma_f32_16x16x32_bf16 v[108:111], v[160:163], v[200:203], v[108:111]
	v_mfma_f32_16x16x32_bf16 v[104:107], v[168:171], v[200:203], v[104:107]
	v_mfma_f32_16x16x32_bf16 v[92:95], v[160:163], v[208:211], v[92:95]
	v_mfma_f32_16x16x32_bf16 v[88:91], v[168:171], v[208:211], v[88:91]
	v_mfma_f32_16x16x32_bf16 v[76:79], v[160:163], v[216:219], v[76:79]
	v_mfma_f32_16x16x32_bf16 v[72:75], v[168:171], v[216:219], v[72:75]
	v_mfma_f32_16x16x32_bf16 v[116:119], v[172:175], v[188:191], v[116:119]
	v_mfma_f32_16x16x32_bf16 v[112:115], v[180:183], v[188:191], v[112:115]
	v_mfma_f32_16x16x32_bf16 v[100:103], v[172:175], v[196:199], v[100:103]
	v_mfma_f32_16x16x32_bf16 v[96:99], v[180:183], v[196:199], v[96:99]
	v_mfma_f32_16x16x32_bf16 v[84:87], v[172:175], v[204:207], v[84:87]
	v_mfma_f32_16x16x32_bf16 v[80:83], v[180:183], v[204:207], v[80:83]
	v_mfma_f32_16x16x32_bf16 v[68:71], v[172:175], v[212:215], v[68:71]
	v_mfma_f32_16x16x32_bf16 v[64:67], v[180:183], v[212:215], v[64:67]
	v_mfma_f32_16x16x32_bf16 v[116:119], v[176:179], v[192:195], v[116:119]
	v_mfma_f32_16x16x32_bf16 v[112:115], v[184:187], v[192:195], v[112:115]
	v_mfma_f32_16x16x32_bf16 v[100:103], v[176:179], v[200:203], v[100:103]
	v_mfma_f32_16x16x32_bf16 v[96:99], v[184:187], v[200:203], v[96:99]
	v_mfma_f32_16x16x32_bf16 v[84:87], v[176:179], v[208:211], v[84:87]
	v_mfma_f32_16x16x32_bf16 v[80:83], v[184:187], v[208:211], v[80:83]
	v_mfma_f32_16x16x32_bf16 v[68:71], v[176:179], v[216:219], v[68:71]
	v_mfma_f32_16x16x32_bf16 v[64:67], v[184:187], v[216:219], v[64:67]
	s_barrier
	s_add_i32 s79, s0, s25
	v_lshl_add_u64 v[146:147], s[60:61], 0, v[132:133]
	s_mov_b32 m0, s79
	ds_read_b128 v[188:191], v153 offset:16384
	ds_read_b128 v[192:195], v153 offset:17408
	ds_read_b128 v[196:199], v153 offset:18432
	ds_read_b128 v[200:203], v153 offset:19456
	ds_read_b128 v[204:207], v153 offset:20480
	ds_read_b128 v[208:211], v153 offset:21504
	ds_read_b128 v[212:215], v153 offset:22528
	ds_read_b128 v[216:219], v153 offset:23552
	global_load_lds_dwordx4 v[146:147], off
	s_add_i32 m0, s79, 0x2000
	s_add_u32 s80, s60, 0x400000
	v_lshl_add_u64 v[220:221], s[60:61], 0, v[128:129]
	s_addc_u32 s81, s61, 0
	s_add_i32 s79, s64, s25
	global_load_lds_dwordx4 v[220:221], off
	v_lshl_add_u64 v[222:223], s[80:81], 0, v[132:133]
	s_mov_b32 m0, s79
	v_lshl_add_u64 v[224:225], s[62:63], 0, v[130:131]
	global_load_lds_dwordx4 v[222:223], off
	v_lshl_add_u64 v[222:223], s[80:81], 0, v[128:129]
	s_add_i32 m0, s79, 0x2000
	s_nop 0
	global_load_lds_dwordx4 v[222:223], off
	v_lshl_add_u64 v[222:223], s[62:63], 0, v[134:135]
	s_mov_b32 m0, s21
	s_nop 0
	global_load_lds_dwordx4 v[222:223], off
	s_mov_b32 m0, s22
	s_nop 0
	global_load_lds_dwordx4 v[224:225], off
	s_waitcnt vmcnt(8)
	s_waitcnt lgkmcnt(0)
	s_barrier
; #define PG8_STAGE(bufoff, gbase, voff) do { _Pragma("unroll") for (int _i = 0; _i < 2; ++_i) \
;         __builtin_amdgcn_global_load_lds((const unsigned*)((const char*)(gbase) + (voff)[_i]), (LAS unsigned*)(lds + (bufoff) + ldsw + _i * 8192), 16, 0, 0); } while (0)
; #define PG8_LDA(dst, b, h) do { _Pragma("unroll") for (int m = 0; m < 4; ++m) _Pragma("unroll") for (int k = 0; k < 2; ++k) dst[m][k] = *(const LAS bf16x8*)(lds + PG8_SA(b, h) + aoff + m * 2048 + k * 1024); } while (0)
; #define PG8_LDB(dst, b, h) do { _Pragma("unroll") for (int n = 0; n < 2; ++n) _Pragma("unroll") for (int k = 0; k < 2; ++k) dst[n][k] = *(const LAS bf16x8*)(lds + PG8_SB(b, h) + boff + n * 2048 + k * 1024); } while (0)
; #define PG8_MMA(ai, bj, At, Bt) do { __builtin_amdgcn_s_setprio(1); _Pragma("unroll") for (int m = 0; m < 4; ++m) _Pragma("unroll") for (int n = 0; n < 2; ++n) _Pragma("unroll") for (int k = 0; k < 2; ++k) \
;         acc[ai][bj][m][n] = __builtin_amdgcn_mfma_f32_16x16x32_bf16(Bt[n][k], At[m][k], acc[ai][bj][m][n], 0, 0, 0); __builtin_amdgcn_s_setprio(0); } while (0)
; #define PG8_WAIT_V(n) asm volatile("s_waitcnt vmcnt(" #n ")" ::: "memory")
; #define PG8_WAIT_L(n) asm volatile("s_waitcnt lgkmcnt(" #n ")" ::: "memory")
; #define PG8_BAR __builtin_amdgcn_s_barrier()
; #define PG8_SCHED __builtin_amdgcn_sched_barrier(0)
; template <class Epi, class Sched>
; __device__ __forceinline__ void gemm_phase(LAS unsigned char* lds, const int K, const int lda, const int ldb, const Sched& S, const Epi& E) {
;     ...
;             PG8_WAIT_V(8); PG8_WAIT_L(0); PG8_BAR; PG8_MMA(1, 0, At, B0); PG8_MMA(1, 1, At, B1); PG8_BAR; PG8_SCHED;
;             PG8_LDB(B0, 1, 0); PG8_LDB(B1, 1, 1); PG8_SCHED; PG8_LDA(At, 1, 0); PG8_STAGE(PG8_SA(0, 1), a2 + hA, voffA);
;             PG8_WAIT_V(8); PG8_WAIT_L(0); PG8_BAR; PG8_MMA(0, 0, At, B0); PG8_MMA(0, 1, At, B1); PG8_BAR; PG8_SCHED;
	s_waitcnt lgkmcnt(0)
	v_mfma_f32_16x16x32_bf16 v[60:63], v[156:159], v[188:191], v[60:63]
	v_mfma_f32_16x16x32_bf16 v[56:59], v[164:167], v[188:191], v[56:59]
	v_mfma_f32_16x16x32_bf16 v[44:47], v[156:159], v[196:199], v[44:47]
	v_mfma_f32_16x16x32_bf16 v[40:43], v[164:167], v[196:199], v[40:43]
	v_mfma_f32_16x16x32_bf16 v[28:31], v[156:159], v[204:207], v[28:31]
	v_mfma_f32_16x16x32_bf16 v[24:27], v[164:167], v[204:207], v[24:27]
	v_mfma_f32_16x16x32_bf16 v[12:15], v[156:159], v[212:215], v[12:15]
	v_mfma_f32_16x16x32_bf16 v[8:11], v[164:167], v[212:215], v[8:11]
	v_mfma_f32_16x16x32_bf16 v[60:63], v[160:163], v[192:195], v[60:63]
	v_mfma_f32_16x16x32_bf16 v[56:59], v[168:171], v[192:195], v[56:59]
	v_mfma_f32_16x16x32_bf16 v[44:47], v[160:163], v[200:203], v[44:47]
	v_mfma_f32_16x16x32_bf16 v[40:43], v[168:171], v[200:203], v[40:43]
	v_mfma_f32_16x16x32_bf16 v[28:31], v[160:163], v[208:211], v[28:31]
	v_mfma_f32_16x16x32_bf16 v[24:27], v[168:171], v[208:211], v[24:27]
	v_mfma_f32_16x16x32_bf16 v[12:15], v[160:163], v[216:219], v[12:15]
	v_mfma_f32_16x16x32_bf16 v[8:11], v[168:171], v[216:219], v[8:11]
	v_mfma_f32_16x16x32_bf16 v[52:55], v[172:175], v[188:191], v[52:55]
	v_mfma_f32_16x16x32_bf16 v[48:51], v[180:183], v[188:191], v[48:51]
	v_mfma_f32_16x16x32_bf16 v[36:39], v[172:175], v[196:199], v[36:39]
	v_mfma_f32_16x16x32_bf16 v[32:35], v[180:183], v[196:199], v[32:35]
	v_mfma_f32_16x16x32_bf16 v[20:23], v[172:175], v[204:207], v[20:23]
	v_mfma_f32_16x16x32_bf16 v[16:19], v[180:183], v[204:207], v[16:19]
	v_mfma_f32_16x16x32_bf16 v[4:7], v[172:175], v[212:215], v[4:7]
	v_mfma_f32_16x16x32_bf16 v[0:3], v[180:183], v[212:215], v[0:3]
	v_mfma_f32_16x16x32_bf16 v[52:55], v[176:179], v[192:195], v[52:55]
	v_mfma_f32_16x16x32_bf16 v[48:51], v[184:187], v[192:195], v[48:51]
	v_mfma_f32_16x16x32_bf16 v[36:39], v[176:179], v[200:203], v[36:39]
	v_mfma_f32_16x16x32_bf16 v[32:35], v[184:187], v[200:203], v[32:35]
	v_mfma_f32_16x16x32_bf16 v[20:23], v[176:179], v[208:211], v[20:23]
	v_mfma_f32_16x16x32_bf16 v[16:19], v[184:187], v[208:211], v[16:19]
	v_mfma_f32_16x16x32_bf16 v[4:7], v[176:179], v[216:219], v[4:7]
	v_mfma_f32_16x16x32_bf16 v[0:3], v[184:187], v[216:219], v[0:3]
	s_barrier
	s_add_i32 s79, 0, 0x18000
	v_add_u32_e32 v136, s79, v149
	s_add_i32 s80, 0, 0x1c000
	ds_read_b128 v[156:159], v136
	ds_read_b128 v[160:163], v136 offset:1024
	ds_read_b128 v[164:167], v136 offset:2048
	ds_read_b128 v[168:171], v136 offset:3072
	v_add_u32_e32 v136, s80, v149
	ds_read_b128 v[172:175], v136
	ds_read_b128 v[176:179], v136 offset:1024
	ds_read_b128 v[180:183], v136 offset:2048
	ds_read_b128 v[184:187], v136 offset:3072
	s_add_u32 s62, s62, 0x100000
	s_addc_u32 s63, s63, 0
	s_mov_b32 m0, s28
	v_lshl_add_u64 v[226:227], s[62:63], 0, v[134:135]
	ds_read_b128 v[188:191], v153 offset:32768
	ds_read_b128 v[192:195], v153 offset:33792
	ds_read_b128 v[196:199], v153 offset:34816
	ds_read_b128 v[200:203], v153 offset:35840
	ds_read_b128 v[204:207], v153 offset:36864
	ds_read_b128 v[208:211], v153 offset:37888
	ds_read_b128 v[212:215], v153 offset:38912
	ds_read_b128 v[216:219], v153 offset:39936
	global_load_lds_dwordx4 v[226:227], off
	v_lshl_add_u64 v[226:227], s[62:63], 0, v[130:131]
	s_mov_b32 m0, s29
	s_nop 0
	global_load_lds_dwordx4 v[226:227], off
	s_waitcnt vmcnt(8)
	s_waitcnt lgkmcnt(0)
	s_barrier
	s_waitcnt lgkmcnt(0)
	v_mfma_f32_16x16x32_bf16 v[124:127], v[156:159], v[188:191], v[124:127]
	v_mfma_f32_16x16x32_bf16 v[120:123], v[164:167], v[188:191], v[120:123]
	v_mfma_f32_16x16x32_bf16 v[108:111], v[156:159], v[196:199], v[108:111]
	v_mfma_f32_16x16x32_bf16 v[104:107], v[164:167], v[196:199], v[104:107]
	v_mfma_f32_16x16x32_bf16 v[92:95], v[156:159], v[204:207], v[92:95]
	v_mfma_f32_16x16x32_bf16 v[88:91], v[164:167], v[204:207], v[88:91]
	v_mfma_f32_16x16x32_bf16 v[76:79], v[156:159], v[212:215], v[76:79]
	v_mfma_f32_16x16x32_bf16 v[72:75], v[164:167], v[212:215], v[72:75]
	v_mfma_f32_16x16x32_bf16 v[124:127], v[160:163], v[192:195], v[124:127]
	v_mfma_f32_16x16x32_bf16 v[120:123], v[168:171], v[192:195], v[120:123]
	v_mfma_f32_16x16x32_bf16 v[108:111], v[160:163], v[200:203], v[108:111]
	v_mfma_f32_16x16x32_bf16 v[104:107], v[168:171], v[200:203], v[104:107]
	v_mfma_f32_16x16x32_bf16 v[92:95], v[160:163], v[208:211], v[92:95]
	v_mfma_f32_16x16x32_bf16 v[88:91], v[168:171], v[208:211], v[88:91]
	v_mfma_f32_16x16x32_bf16 v[76:79], v[160:163], v[216:219], v[76:79]
	v_mfma_f32_16x16x32_bf16 v[72:75], v[168:171], v[216:219], v[72:75]
	v_mfma_f32_16x16x32_bf16 v[116:119], v[172:175], v[188:191], v[116:119]
	v_mfma_f32_16x16x32_bf16 v[112:115], v[180:183], v[188:191], v[112:115]
	v_mfma_f32_16x16x32_bf16 v[100:103], v[172:175], v[196:199], v[100:103]
	v_mfma_f32_16x16x32_bf16 v[96:99], v[180:183], v[196:199], v[96:99]
	v_mfma_f32_16x16x32_bf16 v[84:87], v[172:175], v[204:207], v[84:87]
	v_mfma_f32_16x16x32_bf16 v[80:83], v[180:183], v[204:207], v[80:83]
	v_mfma_f32_16x16x32_bf16 v[68:71], v[172:175], v[212:215], v[68:71]
	v_mfma_f32_16x16x32_bf16 v[64:67], v[180:183], v[212:215], v[64:67]
	v_mfma_f32_16x16x32_bf16 v[116:119], v[176:179], v[192:195], v[116:119]
	v_mfma_f32_16x16x32_bf16 v[112:115], v[184:187], v[192:195], v[112:115]
	v_mfma_f32_16x16x32_bf16 v[100:103], v[176:179], v[200:203], v[100:103]
	v_mfma_f32_16x16x32_bf16 v[96:99], v[184:187], v[200:203], v[96:99]
	v_mfma_f32_16x16x32_bf16 v[84:87], v[176:179], v[208:211], v[84:87]
	v_mfma_f32_16x16x32_bf16 v[80:83], v[184:187], v[208:211], v[80:83]
	v_mfma_f32_16x16x32_bf16 v[68:71], v[176:179], v[216:219], v[68:71]
	v_mfma_f32_16x16x32_bf16 v[64:67], v[184:187], v[216:219], v[64:67]
	s_barrier
; #define PG8_STAGE(bufoff, gbase, voff) do { _Pragma("unroll") for (int _i = 0; _i < 2; ++_i) \
;         __builtin_amdgcn_global_load_lds((const unsigned*)((const char*)(gbase) + (voff)[_i]), (LAS unsigned*)(lds + (bufoff) + ldsw + _i * 8192), 16, 0, 0); } while (0)
; #define PG8_LDA(dst, b, h) do { _Pragma("unroll") for (int m = 0; m < 4; ++m) _Pragma("unroll") for (int k = 0; k < 2; ++k) dst[m][k] = *(const LAS bf16x8*)(lds + PG8_SA(b, h) + aoff + m * 2048 + k * 1024); } while (0)
; #define PG8_MMA(ai, bj, At, Bt) do { __builtin_amdgcn_s_setprio(1); _Pragma("unroll") for (int m = 0; m < 4; ++m) _Pragma("unroll") for (int n = 0; n < 2; ++n) _Pragma("unroll") for (int k = 0; k < 2; ++k) \
;         acc[ai][bj][m][n] = __builtin_amdgcn_mfma_f32_16x16x32_bf16(Bt[n][k], At[m][k], acc[ai][bj][m][n], 0, 0, 0); __builtin_amdgcn_s_setprio(0); } while (0)
; #define PG8_WAIT_V(n) asm volatile("s_waitcnt vmcnt(" #n ")" ::: "memory")
; #define PG8_WAIT_L(n) asm volatile("s_waitcnt lgkmcnt(" #n ")" ::: "memory")
; #define PG8_BAR __builtin_amdgcn_s_barrier()
; #define PG8_SCHED __builtin_amdgcn_sched_barrier(0)
; template <class Epi, class Sched>
; __device__ __forceinline__ void gemm_phase(LAS unsigned char* lds, const int K, const int lda, const int ldb, const Sched& S, const Epi& E) {
;     ...
;             PG8_LDA(At, 1, 1); PG8_STAGE(PG8_SB(1, 0), b3, voffB); PG8_STAGE(PG8_SB(1, 1), b3 + hB, voffB); PG8_STAGE(PG8_SA(1, 0), a3, voffA);
;             PG8_WAIT_V(8); PG8_WAIT_L(0); PG8_BAR; PG8_MMA(1, 0, At, B0); PG8_MMA(1, 1, At, B1); PG8_BAR; PG8_SCHED;
;         }
;         if (wr == 0) PG8_BAR;
	s_add_i32 s62, s79, s25
	v_lshl_add_u64 v[146:147], v[146:147], 0, s[46:47]
	s_mov_b32 m0, s62
	ds_read_b128 v[188:191], v153 offset:49152
	ds_read_b128 v[192:195], v153 offset:50176
	ds_read_b128 v[196:199], v153 offset:51200
	ds_read_b128 v[200:203], v153 offset:52224
	ds_read_b128 v[204:207], v153 offset:53248
	ds_read_b128 v[208:211], v153 offset:54272
	ds_read_b128 v[212:215], v153 offset:55296
	ds_read_b128 v[216:219], v153 offset:56320
	global_load_lds_dwordx4 v[146:147], off
	s_add_i32 m0, s62, 0x2000
	s_add_u32 s60, s60, 0x400080
	v_lshl_add_u64 v[146:147], v[220:221], 0, s[46:47]
	s_addc_u32 s61, s61, 0
	s_add_i32 s62, s80, s25
	global_load_lds_dwordx4 v[146:147], off
	v_lshl_add_u64 v[146:147], s[60:61], 0, v[132:133]
	s_mov_b32 m0, s62
	s_nop 0
	global_load_lds_dwordx4 v[146:147], off
	v_lshl_add_u64 v[146:147], s[60:61], 0, v[128:129]
	s_add_i32 m0, s62, 0x2000
	s_nop 0
	global_load_lds_dwordx4 v[146:147], off
	v_lshl_add_u64 v[146:147], v[222:223], 0, s[46:47]
	s_mov_b32 m0, s35
	s_nop 0
	global_load_lds_dwordx4 v[146:147], off
	v_lshl_add_u64 v[146:147], v[224:225], 0, s[46:47]
	s_mov_b32 m0, s38
	s_nop 0
	global_load_lds_dwordx4 v[146:147], off
	s_waitcnt vmcnt(8)
	s_waitcnt lgkmcnt(0)
	s_barrier
	s_waitcnt lgkmcnt(0)
	v_mfma_f32_16x16x32_bf16 v[60:63], v[156:159], v[188:191], v[60:63]
	v_mfma_f32_16x16x32_bf16 v[56:59], v[164:167], v[188:191], v[56:59]
	v_mfma_f32_16x16x32_bf16 v[44:47], v[156:159], v[196:199], v[44:47]
	v_mfma_f32_16x16x32_bf16 v[40:43], v[164:167], v[196:199], v[40:43]
	v_mfma_f32_16x16x32_bf16 v[28:31], v[156:159], v[204:207], v[28:31]
	v_mfma_f32_16x16x32_bf16 v[24:27], v[164:167], v[204:207], v[24:27]
	v_mfma_f32_16x16x32_bf16 v[12:15], v[156:159], v[212:215], v[12:15]
	v_mfma_f32_16x16x32_bf16 v[8:11], v[164:167], v[212:215], v[8:11]
	v_mfma_f32_16x16x32_bf16 v[60:63], v[160:163], v[192:195], v[60:63]
	v_mfma_f32_16x16x32_bf16 v[56:59], v[168:171], v[192:195], v[56:59]
	v_mfma_f32_16x16x32_bf16 v[44:47], v[160:163], v[200:203], v[44:47]
	v_mfma_f32_16x16x32_bf16 v[40:43], v[168:171], v[200:203], v[40:43]
	v_mfma_f32_16x16x32_bf16 v[28:31], v[160:163], v[208:211], v[28:31]
	v_mfma_f32_16x16x32_bf16 v[24:27], v[168:171], v[208:211], v[24:27]
	v_mfma_f32_16x16x32_bf16 v[12:15], v[160:163], v[216:219], v[12:15]
	v_mfma_f32_16x16x32_bf16 v[8:11], v[168:171], v[216:219], v[8:11]
	v_mfma_f32_16x16x32_bf16 v[52:55], v[172:175], v[188:191], v[52:55]
	v_mfma_f32_16x16x32_bf16 v[48:51], v[180:183], v[188:191], v[48:51]
	v_mfma_f32_16x16x32_bf16 v[36:39], v[172:175], v[196:199], v[36:39]
	v_mfma_f32_16x16x32_bf16 v[32:35], v[180:183], v[196:199], v[32:35]
	v_mfma_f32_16x16x32_bf16 v[20:23], v[172:175], v[204:207], v[20:23]
	v_mfma_f32_16x16x32_bf16 v[16:19], v[180:183], v[204:207], v[16:19]
	v_mfma_f32_16x16x32_bf16 v[4:7], v[172:175], v[212:215], v[4:7]
	v_mfma_f32_16x16x32_bf16 v[0:3], v[180:183], v[212:215], v[0:3]
	v_mfma_f32_16x16x32_bf16 v[52:55], v[176:179], v[192:195], v[52:55]
	v_mfma_f32_16x16x32_bf16 v[48:51], v[184:187], v[192:195], v[48:51]
	v_mfma_f32_16x16x32_bf16 v[36:39], v[176:179], v[200:203], v[36:39]
	v_mfma_f32_16x16x32_bf16 v[32:35], v[184:187], v[200:203], v[32:35]
	v_mfma_f32_16x16x32_bf16 v[20:23], v[176:179], v[208:211], v[20:23]
	v_mfma_f32_16x16x32_bf16 v[16:19], v[184:187], v[208:211], v[16:19]
	v_mfma_f32_16x16x32_bf16 v[4:7], v[176:179], v[216:219], v[4:7]
	v_mfma_f32_16x16x32_bf16 v[0:3], v[184:187], v[216:219], v[0:3]
	s_barrier
	s_add_i32 s78, s78, 2
	s_add_u32 s55, s55, 0x100
	s_addc_u32 s59, s59, 0
	s_add_u32 s8, s8, 0x100
	s_addc_u32 s9, s9, 0
	s_cmp_gt_u32 s78, 29
	s_cbranch_scc0 .LBB0_427
	s_and_b64 vcc, exec, s[48:49]
	s_cbranch_vccz .LBB0_430
	s_barrier

; #define PG8_STAGE(bufoff, gbase, voff) do { _Pragma("unroll") for (int _i = 0; _i < 2; ++_i) \
;         __builtin_amdgcn_global_load_lds((const unsigned*)((const char*)(gbase) + (voff)[_i]), (LAS unsigned*)(lds + (bufoff) + ldsw + _i * 8192), 16, 0, 0); } while (0)
; #define PG8_LDA(dst, b, h) do { _Pragma("unroll") for (int m = 0; m < 4; ++m) _Pragma("unroll") for (int k = 0; k < 2; ++k) dst[m][k] = *(const LAS bf16x8*)(lds + PG8_SA(b, h) + aoff + m * 2048 + k * 1024); } while (0)
; #define PG8_LDB(dst, b, h) do { _Pragma("unroll") for (int n = 0; n < 2; ++n) _Pragma("unroll") for (int k = 0; k < 2; ++k) dst[n][k] = *(const LAS bf16x8*)(lds + PG8_SB(b, h) + boff + n * 2048 + k * 1024); } while (0)
; #define PG8_MMA(ai, bj, At, Bt) do { __builtin_amdgcn_s_setprio(1); _Pragma("unroll") for (int m = 0; m < 4; ++m) _Pragma("unroll") for (int n = 0; n < 2; ++n) _Pragma("unroll") for (int k = 0; k < 2; ++k) \
;         acc[ai][bj][m][n] = __builtin_amdgcn_mfma_f32_16x16x32_bf16(Bt[n][k], At[m][k], acc[ai][bj][m][n], 0, 0, 0); __builtin_amdgcn_s_setprio(0); } while (0)
; #define PG8_WAIT_V(n) asm volatile("s_waitcnt vmcnt(" #n ")" ::: "memory")
; #define PG8_WAIT_L(n) asm volatile("s_waitcnt lgkmcnt(" #n ")" ::: "memory")
; #define PG8_BAR __builtin_amdgcn_s_barrier()
; #define PG8_SCHED __builtin_amdgcn_sched_barrier(0)
; template <class Epi, class Sched>
; __device__ __forceinline__ void gemm_phase(LAS unsigned char* lds, const int K, const int lda, const int ldb, const Sched& S, const Epi& E) {
;     ...
;         for (int t = 0; t < nt; t += 2) {
;             const bool last = (t == nt - 2);
;             const char* a1 = cA + (size_t)(t + 1) * kstep;
;             const char* a2 = last ? nA : cA + (size_t)(t + 2) * kstep; const char* b2 = last ? nB : cB + (size_t)(t + 2) * kstep;
;             const char* a3 = a2 + kstep; const char* b3 = b2 + kstep;
;             PG8_LDB(B0, 0, 0); PG8_LDB(B1, 0, 1); PG8_SCHED; PG8_LDA(At, 0, 0); PG8_STAGE(PG8_SA(1, 1), a1 + hA, voffA);
;             PG8_WAIT_V(8); PG8_WAIT_L(0); PG8_BAR; PG8_MMA(0, 0, At, B0); PG8_MMA(0, 1, At, B1); PG8_BAR; PG8_SCHED;
;             PG8_LDA(At, 0, 1); PG8_STAGE(PG8_SB(0, 0), b2, voffB); PG8_STAGE(PG8_SB(0, 1), b2 + hB, voffB); PG8_STAGE(PG8_SA(0, 0), a2, voffA);
.LBB0_477:
	ds_read_b128 v[156:159], v151
	ds_read_b128 v[160:163], v151 offset:1024
	ds_read_b128 v[164:167], v151 offset:2048
	ds_read_b128 v[168:171], v151 offset:3072
	ds_read_b128 v[172:175], v152
	ds_read_b128 v[176:179], v152 offset:1024
	ds_read_b128 v[180:183], v152 offset:2048
	ds_read_b128 v[184:187], v152 offset:3072
	s_add_u32 s60, s8, 0xffe00080
	s_addc_u32 s61, s9, -1
	s_cmp_eq_u32 s63, 12
	s_cselect_b32 s65, s53, s61
	s_cselect_b32 s64, s52, s60
	s_cselect_b32 s61, s59, s57
	s_cselect_b32 s60, s58, s19
	v_lshl_add_u64 v[146:147], s[8:9], 0, v[140:141]
	s_add_i32 m0, s1, 0xc000
	ds_read_b128 v[188:191], v153
	ds_read_b128 v[192:195], v153 offset:1024
	ds_read_b128 v[196:199], v153 offset:2048
	ds_read_b128 v[200:203], v153 offset:3072
	ds_read_b128 v[204:207], v153 offset:4096
	ds_read_b128 v[208:211], v153 offset:5120
	ds_read_b128 v[212:215], v153 offset:6144
	ds_read_b128 v[216:219], v153 offset:7168
	global_load_lds_dwordx4 v[146:147], off
	v_lshl_add_u64 v[146:147], s[8:9], 0, v[138:139]
	s_add_i32 m0, s1, 0xe000
	s_nop 0
	global_load_lds_dwordx4 v[146:147], off
	s_waitcnt vmcnt(8)
	s_waitcnt lgkmcnt(0)
	s_barrier
	s_waitcnt lgkmcnt(0)
	v_mfma_f32_16x16x32_bf16 v[124:127], v[156:159], v[188:191], v[124:127]
	v_mfma_f32_16x16x32_bf16 v[120:123], v[164:167], v[188:191], v[120:123]
	v_mfma_f32_16x16x32_bf16 v[108:111], v[156:159], v[196:199], v[108:111]
	v_mfma_f32_16x16x32_bf16 v[104:107], v[164:167], v[196:199], v[104:107]
	v_mfma_f32_16x16x32_bf16 v[92:95], v[156:159], v[204:207], v[92:95]
	v_mfma_f32_16x16x32_bf16 v[88:91], v[164:167], v[204:207], v[88:91]
	v_mfma_f32_16x16x32_bf16 v[76:79], v[156:159], v[212:215], v[76:79]
	v_mfma_f32_16x16x32_bf16 v[72:75], v[164:167], v[212:215], v[72:75]
	v_mfma_f32_16x16x32_bf16 v[124:127], v[160:163], v[192:195], v[124:127]
	v_mfma_f32_16x16x32_bf16 v[120:123], v[168:171], v[192:195], v[120:123]
	v_mfma_f32_16x16x32_bf16 v[108:111], v[160:163], v[200:203], v[108:111]
	v_mfma_f32_16x16x32_bf16 v[104:107], v[168:171], v[200:203], v[104:107]
	v_mfma_f32_16x16x32_bf16 v[92:95], v[160:163], v[208:211], v[92:95]
	v_mfma_f32_16x16x32_bf16 v[88:91], v[168:171], v[208:211], v[88:91]
	v_mfma_f32_16x16x32_bf16 v[76:79], v[160:163], v[216:219], v[76:79]
	v_mfma_f32_16x16x32_bf16 v[72:75], v[168:171], v[216:219], v[72:75]
	v_mfma_f32_16x16x32_bf16 v[116:119], v[172:175], v[188:191], v[116:119]
	v_mfma_f32_16x16x32_bf16 v[112:115], v[180:183], v[188:191], v[112:115]
	v_mfma_f32_16x16x32_bf16 v[100:103], v[172:175], v[196:199], v[100:103]
	v_mfma_f32_16x16x32_bf16 v[96:99], v[180:183], v[196:199], v[96:99]
	v_mfma_f32_16x16x32_bf16 v[84:87], v[172:175], v[204:207], v[84:87]
	v_mfma_f32_16x16x32_bf16 v[80:83], v[180:183], v[204:207], v[80:83]
	v_mfma_f32_16x16x32_bf16 v[68:71], v[172:175], v[212:215], v[68:71]
	v_mfma_f32_16x16x32_bf16 v[64:67], v[180:183], v[212:215], v[64:67]
	v_mfma_f32_16x16x32_bf16 v[116:119], v[176:179], v[192:195], v[116:119]
	v_mfma_f32_16x16x32_bf16 v[112:115], v[184:187], v[192:195], v[112:115]
	v_mfma_f32_16x16x32_bf16 v[100:103], v[176:179], v[200:203], v[100:103]
	v_mfma_f32_16x16x32_bf16 v[96:99], v[184:187], v[200:203], v[96:99]
	v_mfma_f32_16x16x32_bf16 v[84:87], v[176:179], v[208:211], v[84:87]
	v_mfma_f32_16x16x32_bf16 v[80:83], v[184:187], v[208:211], v[80:83]
	v_mfma_f32_16x16x32_bf16 v[68:71], v[176:179], v[216:219], v[68:71]
	v_mfma_f32_16x16x32_bf16 v[64:67], v[184:187], v[216:219], v[64:67]
	s_barrier
	s_add_i32 s72, s41, s25
	v_lshl_add_u64 v[146:147], s[60:61], 0, v[132:133]
	s_mov_b32 m0, s72
	ds_read_b128 v[188:191], v153 offset:16384
	ds_read_b128 v[192:195], v153 offset:17408
	ds_read_b128 v[196:199], v153 offset:18432
	ds_read_b128 v[200:203], v153 offset:19456
	ds_read_b128 v[204:207], v153 offset:20480
	ds_read_b128 v[208:211], v153 offset:21504
	ds_read_b128 v[212:215], v153 offset:22528
	ds_read_b128 v[216:219], v153 offset:23552
	global_load_lds_dwordx4 v[146:147], off
	s_add_i32 m0, s72, 0x2000
	s_add_u32 s72, s60, 0x400000
	v_lshl_add_u64 v[220:221], s[60:61], 0, v[128:129]
	s_addc_u32 s73, s61, 0
	s_add_i32 s74, s66, s25
	global_load_lds_dwordx4 v[220:221], off
	v_lshl_add_u64 v[222:223], s[72:73], 0, v[132:133]
	s_mov_b32 m0, s74
	v_lshl_add_u64 v[224:225], s[64:65], 0, v[130:131]
	global_load_lds_dwordx4 v[222:223], off
	v_lshl_add_u64 v[222:223], s[72:73], 0, v[128:129]
	s_add_i32 m0, s74, 0x2000
	s_nop 0
	global_load_lds_dwordx4 v[222:223], off
	v_lshl_add_u64 v[222:223], s[64:65], 0, v[134:135]
	s_mov_b32 m0, s1
	s_nop 0
	global_load_lds_dwordx4 v[222:223], off
	s_mov_b32 m0, s23
	s_nop 0
	global_load_lds_dwordx4 v[224:225], off
	s_waitcnt vmcnt(8)
	s_waitcnt lgkmcnt(0)
	s_barrier
; #define PG8_STAGE(bufoff, gbase, voff) do { _Pragma("unroll") for (int _i = 0; _i < 2; ++_i) \
;         __builtin_amdgcn_global_load_lds((const unsigned*)((const char*)(gbase) + (voff)[_i]), (LAS unsigned*)(lds + (bufoff) + ldsw + _i * 8192), 16, 0, 0); } while (0)
; #define PG8_LDA(dst, b, h) do { _Pragma("unroll") for (int m = 0; m < 4; ++m) _Pragma("unroll") for (int k = 0; k < 2; ++k) dst[m][k] = *(const LAS bf16x8*)(lds + PG8_SA(b, h) + aoff + m * 2048 + k * 1024); } while (0)
; #define PG8_LDB(dst, b, h) do { _Pragma("unroll") for (int n = 0; n < 2; ++n) _Pragma("unroll") for (int k = 0; k < 2; ++k) dst[n][k] = *(const LAS bf16x8*)(lds + PG8_SB(b, h) + boff + n * 2048 + k * 1024); } while (0)
; #define PG8_MMA(ai, bj, At, Bt) do { __builtin_amdgcn_s_setprio(1); _Pragma("unroll") for (int m = 0; m < 4; ++m) _Pragma("unroll") for (int n = 0; n < 2; ++n) _Pragma("unroll") for (int k = 0; k < 2; ++k) \
;         acc[ai][bj][m][n] = __builtin_amdgcn_mfma_f32_16x16x32_bf16(Bt[n][k], At[m][k], acc[ai][bj][m][n], 0, 0, 0); __builtin_amdgcn_s_setprio(0); } while (0)
; #define PG8_WAIT_V(n) asm volatile("s_waitcnt vmcnt(" #n ")" ::: "memory")
; #define PG8_WAIT_L(n) asm volatile("s_waitcnt lgkmcnt(" #n ")" ::: "memory")
; #define PG8_BAR __builtin_amdgcn_s_barrier()
; #define PG8_SCHED __builtin_amdgcn_sched_barrier(0)
; template <class Epi, class Sched>
; __device__ __forceinline__ void gemm_phase(LAS unsigned char* lds, const int K, const int lda, const int ldb, const Sched& S, const Epi& E) {
;     ...
;             PG8_WAIT_V(8); PG8_WAIT_L(0); PG8_BAR; PG8_MMA(1, 0, At, B0); PG8_MMA(1, 1, At, B1); PG8_BAR; PG8_SCHED;
;             PG8_LDB(B0, 1, 0); PG8_LDB(B1, 1, 1); PG8_SCHED; PG8_LDA(At, 1, 0); PG8_STAGE(PG8_SA(0, 1), a2 + hA, voffA);
;             PG8_WAIT_V(8); PG8_WAIT_L(0); PG8_BAR; PG8_MMA(0, 0, At, B0); PG8_MMA(0, 1, At, B1); PG8_BAR; PG8_SCHED;
	s_waitcnt lgkmcnt(0)
	v_mfma_f32_16x16x32_bf16 v[60:63], v[156:159], v[188:191], v[60:63]
	v_mfma_f32_16x16x32_bf16 v[56:59], v[164:167], v[188:191], v[56:59]
	v_mfma_f32_16x16x32_bf16 v[44:47], v[156:159], v[196:199], v[44:47]
	v_mfma_f32_16x16x32_bf16 v[40:43], v[164:167], v[196:199], v[40:43]
	v_mfma_f32_16x16x32_bf16 v[28:31], v[156:159], v[204:207], v[28:31]
	v_mfma_f32_16x16x32_bf16 v[24:27], v[164:167], v[204:207], v[24:27]
	v_mfma_f32_16x16x32_bf16 v[12:15], v[156:159], v[212:215], v[12:15]
	v_mfma_f32_16x16x32_bf16 v[8:11], v[164:167], v[212:215], v[8:11]
	v_mfma_f32_16x16x32_bf16 v[60:63], v[160:163], v[192:195], v[60:63]
	v_mfma_f32_16x16x32_bf16 v[56:59], v[168:171], v[192:195], v[56:59]
	v_mfma_f32_16x16x32_bf16 v[44:47], v[160:163], v[200:203], v[44:47]
	v_mfma_f32_16x16x32_bf16 v[40:43], v[168:171], v[200:203], v[40:43]
	v_mfma_f32_16x16x32_bf16 v[28:31], v[160:163], v[208:211], v[28:31]
	v_mfma_f32_16x16x32_bf16 v[24:27], v[168:171], v[208:211], v[24:27]
	v_mfma_f32_16x16x32_bf16 v[12:15], v[160:163], v[216:219], v[12:15]
	v_mfma_f32_16x16x32_bf16 v[8:11], v[168:171], v[216:219], v[8:11]
	v_mfma_f32_16x16x32_bf16 v[52:55], v[172:175], v[188:191], v[52:55]
	v_mfma_f32_16x16x32_bf16 v[48:51], v[180:183], v[188:191], v[48:51]
	v_mfma_f32_16x16x32_bf16 v[36:39], v[172:175], v[196:199], v[36:39]
	v_mfma_f32_16x16x32_bf16 v[32:35], v[180:183], v[196:199], v[32:35]
	v_mfma_f32_16x16x32_bf16 v[20:23], v[172:175], v[204:207], v[20:23]
	v_mfma_f32_16x16x32_bf16 v[16:19], v[180:183], v[204:207], v[16:19]
	v_mfma_f32_16x16x32_bf16 v[4:7], v[172:175], v[212:215], v[4:7]
	v_mfma_f32_16x16x32_bf16 v[0:3], v[180:183], v[212:215], v[0:3]
	v_mfma_f32_16x16x32_bf16 v[52:55], v[176:179], v[192:195], v[52:55]
	v_mfma_f32_16x16x32_bf16 v[48:51], v[184:187], v[192:195], v[48:51]
	v_mfma_f32_16x16x32_bf16 v[36:39], v[176:179], v[200:203], v[36:39]
	v_mfma_f32_16x16x32_bf16 v[32:35], v[184:187], v[200:203], v[32:35]
	v_mfma_f32_16x16x32_bf16 v[20:23], v[176:179], v[208:211], v[20:23]
	v_mfma_f32_16x16x32_bf16 v[16:19], v[184:187], v[208:211], v[16:19]
	v_mfma_f32_16x16x32_bf16 v[4:7], v[176:179], v[216:219], v[4:7]
	v_mfma_f32_16x16x32_bf16 v[0:3], v[184:187], v[216:219], v[0:3]
	s_barrier
	s_add_i32 s72, 0, 0x18000
	v_add_u32_e32 v136, s72, v149
	s_add_i32 s73, 0, 0x1c000
	ds_read_b128 v[156:159], v136
	ds_read_b128 v[160:163], v136 offset:1024
	ds_read_b128 v[164:167], v136 offset:2048
	ds_read_b128 v[168:171], v136 offset:3072
	v_add_u32_e32 v136, s73, v149
	ds_read_b128 v[172:175], v136
	ds_read_b128 v[176:179], v136 offset:1024
	ds_read_b128 v[180:183], v136 offset:2048
	ds_read_b128 v[184:187], v136 offset:3072
	s_add_u32 s64, s64, 0x200000
	s_addc_u32 s65, s65, 0
	s_mov_b32 m0, s26
	v_lshl_add_u64 v[226:227], s[64:65], 0, v[134:135]
	ds_read_b128 v[188:191], v153 offset:32768
	ds_read_b128 v[192:195], v153 offset:33792
	ds_read_b128 v[196:199], v153 offset:34816
	ds_read_b128 v[200:203], v153 offset:35840
	ds_read_b128 v[204:207], v153 offset:36864
	ds_read_b128 v[208:211], v153 offset:37888
	ds_read_b128 v[212:215], v153 offset:38912
	ds_read_b128 v[216:219], v153 offset:39936
	global_load_lds_dwordx4 v[226:227], off
	v_lshl_add_u64 v[226:227], s[64:65], 0, v[130:131]
	s_mov_b32 m0, s27
	s_nop 0
	global_load_lds_dwordx4 v[226:227], off
	s_waitcnt vmcnt(8)
	s_waitcnt lgkmcnt(0)
	s_barrier
	s_waitcnt lgkmcnt(0)
	v_mfma_f32_16x16x32_bf16 v[124:127], v[156:159], v[188:191], v[124:127]
	v_mfma_f32_16x16x32_bf16 v[120:123], v[164:167], v[188:191], v[120:123]
	v_mfma_f32_16x16x32_bf16 v[108:111], v[156:159], v[196:199], v[108:111]
	v_mfma_f32_16x16x32_bf16 v[104:107], v[164:167], v[196:199], v[104:107]
	v_mfma_f32_16x16x32_bf16 v[92:95], v[156:159], v[204:207], v[92:95]
	v_mfma_f32_16x16x32_bf16 v[88:91], v[164:167], v[204:207], v[88:91]
	v_mfma_f32_16x16x32_bf16 v[76:79], v[156:159], v[212:215], v[76:79]
	v_mfma_f32_16x16x32_bf16 v[72:75], v[164:167], v[212:215], v[72:75]
	v_mfma_f32_16x16x32_bf16 v[124:127], v[160:163], v[192:195], v[124:127]
	v_mfma_f32_16x16x32_bf16 v[120:123], v[168:171], v[192:195], v[120:123]
	v_mfma_f32_16x16x32_bf16 v[108:111], v[160:163], v[200:203], v[108:111]
	v_mfma_f32_16x16x32_bf16 v[104:107], v[168:171], v[200:203], v[104:107]
	v_mfma_f32_16x16x32_bf16 v[92:95], v[160:163], v[208:211], v[92:95]
	v_mfma_f32_16x16x32_bf16 v[88:91], v[168:171], v[208:211], v[88:91]
	v_mfma_f32_16x16x32_bf16 v[76:79], v[160:163], v[216:219], v[76:79]
	v_mfma_f32_16x16x32_bf16 v[72:75], v[168:171], v[216:219], v[72:75]
	v_mfma_f32_16x16x32_bf16 v[116:119], v[172:175], v[188:191], v[116:119]
	v_mfma_f32_16x16x32_bf16 v[112:115], v[180:183], v[188:191], v[112:115]
	v_mfma_f32_16x16x32_bf16 v[100:103], v[172:175], v[196:199], v[100:103]
	v_mfma_f32_16x16x32_bf16 v[96:99], v[180:183], v[196:199], v[96:99]
	v_mfma_f32_16x16x32_bf16 v[84:87], v[172:175], v[204:207], v[84:87]
	v_mfma_f32_16x16x32_bf16 v[80:83], v[180:183], v[204:207], v[80:83]
	v_mfma_f32_16x16x32_bf16 v[68:71], v[172:175], v[212:215], v[68:71]
	v_mfma_f32_16x16x32_bf16 v[64:67], v[180:183], v[212:215], v[64:67]
	v_mfma_f32_16x16x32_bf16 v[116:119], v[176:179], v[192:195], v[116:119]
	v_mfma_f32_16x16x32_bf16 v[112:115], v[184:187], v[192:195], v[112:115]
	v_mfma_f32_16x16x32_bf16 v[100:103], v[176:179], v[200:203], v[100:103]
	v_mfma_f32_16x16x32_bf16 v[96:99], v[184:187], v[200:203], v[96:99]
	v_mfma_f32_16x16x32_bf16 v[84:87], v[176:179], v[208:211], v[84:87]
	v_mfma_f32_16x16x32_bf16 v[80:83], v[184:187], v[208:211], v[80:83]
	v_mfma_f32_16x16x32_bf16 v[68:71], v[176:179], v[216:219], v[68:71]
	v_mfma_f32_16x16x32_bf16 v[64:67], v[184:187], v[216:219], v[64:67]
	s_barrier
; #define PG8_STAGE(bufoff, gbase, voff) do { _Pragma("unroll") for (int _i = 0; _i < 2; ++_i) \
;         __builtin_amdgcn_global_load_lds((const unsigned*)((const char*)(gbase) + (voff)[_i]), (LAS unsigned*)(lds + (bufoff) + ldsw + _i * 8192), 16, 0, 0); } while (0)
; #define PG8_LDA(dst, b, h) do { _Pragma("unroll") for (int m = 0; m < 4; ++m) _Pragma("unroll") for (int k = 0; k < 2; ++k) dst[m][k] = *(const LAS bf16x8*)(lds + PG8_SA(b, h) + aoff + m * 2048 + k * 1024); } while (0)
; #define PG8_MMA(ai, bj, At, Bt) do { __builtin_amdgcn_s_setprio(1); _Pragma("unroll") for (int m = 0; m < 4; ++m) _Pragma("unroll") for (int n = 0; n < 2; ++n) _Pragma("unroll") for (int k = 0; k < 2; ++k) \
;         acc[ai][bj][m][n] = __builtin_amdgcn_mfma_f32_16x16x32_bf16(Bt[n][k], At[m][k], acc[ai][bj][m][n], 0, 0, 0); __builtin_amdgcn_s_setprio(0); } while (0)
; #define PG8_WAIT_V(n) asm volatile("s_waitcnt vmcnt(" #n ")" ::: "memory")
; #define PG8_WAIT_L(n) asm volatile("s_waitcnt lgkmcnt(" #n ")" ::: "memory")
; #define PG8_BAR __builtin_amdgcn_s_barrier()
; #define PG8_SCHED __builtin_amdgcn_sched_barrier(0)
; template <class Epi, class Sched>
; __device__ __forceinline__ void gemm_phase(LAS unsigned char* lds, const int K, const int lda, const int ldb, const Sched& S, const Epi& E) {
;     ...
;             PG8_LDA(At, 1, 1); PG8_STAGE(PG8_SB(1, 0), b3, voffB); PG8_STAGE(PG8_SB(1, 1), b3 + hB, voffB); PG8_STAGE(PG8_SA(1, 0), a3, voffA);
;             PG8_WAIT_V(8); PG8_WAIT_L(0); PG8_BAR; PG8_MMA(1, 0, At, B0); PG8_MMA(1, 1, At, B1); PG8_BAR; PG8_SCHED;
;         }
;         if (wr == 0) PG8_BAR;
	s_add_i32 s64, s72, s25
	v_lshl_add_u64 v[146:147], v[146:147], 0, s[48:49]
	s_mov_b32 m0, s64
	ds_read_b128 v[188:191], v153 offset:49152
	ds_read_b128 v[192:195], v153 offset:50176
	ds_read_b128 v[196:199], v153 offset:51200
	ds_read_b128 v[200:203], v153 offset:52224
	ds_read_b128 v[204:207], v153 offset:53248
	ds_read_b128 v[208:211], v153 offset:54272
	ds_read_b128 v[212:215], v153 offset:55296
	ds_read_b128 v[216:219], v153 offset:56320
	global_load_lds_dwordx4 v[146:147], off
	s_add_i32 m0, s64, 0x2000
	s_add_u32 s60, s60, 0x400080
	v_lshl_add_u64 v[146:147], v[220:221], 0, s[48:49]
	s_addc_u32 s61, s61, 0
	s_add_i32 s64, s73, s25
	global_load_lds_dwordx4 v[146:147], off
	v_lshl_add_u64 v[146:147], s[60:61], 0, v[132:133]
	s_mov_b32 m0, s64
	s_nop 0
	global_load_lds_dwordx4 v[146:147], off
	v_lshl_add_u64 v[146:147], s[60:61], 0, v[128:129]
	s_add_i32 m0, s64, 0x2000
	s_nop 0
	global_load_lds_dwordx4 v[146:147], off
	v_lshl_add_u64 v[146:147], v[222:223], 0, s[48:49]
	s_mov_b32 m0, s34
	s_nop 0
	global_load_lds_dwordx4 v[146:147], off
	v_lshl_add_u64 v[146:147], v[224:225], 0, s[48:49]
	s_mov_b32 m0, s35
	s_nop 0
	global_load_lds_dwordx4 v[146:147], off
	s_waitcnt vmcnt(8)
	s_waitcnt lgkmcnt(0)
	s_barrier
	s_waitcnt lgkmcnt(0)
	v_mfma_f32_16x16x32_bf16 v[60:63], v[156:159], v[188:191], v[60:63]
	v_mfma_f32_16x16x32_bf16 v[56:59], v[164:167], v[188:191], v[56:59]
	v_mfma_f32_16x16x32_bf16 v[44:47], v[156:159], v[196:199], v[44:47]
	v_mfma_f32_16x16x32_bf16 v[40:43], v[164:167], v[196:199], v[40:43]
	v_mfma_f32_16x16x32_bf16 v[28:31], v[156:159], v[204:207], v[28:31]
	v_mfma_f32_16x16x32_bf16 v[24:27], v[164:167], v[204:207], v[24:27]
	v_mfma_f32_16x16x32_bf16 v[12:15], v[156:159], v[212:215], v[12:15]
	v_mfma_f32_16x16x32_bf16 v[8:11], v[164:167], v[212:215], v[8:11]
	v_mfma_f32_16x16x32_bf16 v[60:63], v[160:163], v[192:195], v[60:63]
	v_mfma_f32_16x16x32_bf16 v[56:59], v[168:171], v[192:195], v[56:59]
	v_mfma_f32_16x16x32_bf16 v[44:47], v[160:163], v[200:203], v[44:47]
	v_mfma_f32_16x16x32_bf16 v[40:43], v[168:171], v[200:203], v[40:43]
	v_mfma_f32_16x16x32_bf16 v[28:31], v[160:163], v[208:211], v[28:31]
	v_mfma_f32_16x16x32_bf16 v[24:27], v[168:171], v[208:211], v[24:27]
	v_mfma_f32_16x16x32_bf16 v[12:15], v[160:163], v[216:219], v[12:15]
	v_mfma_f32_16x16x32_bf16 v[8:11], v[168:171], v[216:219], v[8:11]
	v_mfma_f32_16x16x32_bf16 v[52:55], v[172:175], v[188:191], v[52:55]
	v_mfma_f32_16x16x32_bf16 v[48:51], v[180:183], v[188:191], v[48:51]
	v_mfma_f32_16x16x32_bf16 v[36:39], v[172:175], v[196:199], v[36:39]
	v_mfma_f32_16x16x32_bf16 v[32:35], v[180:183], v[196:199], v[32:35]
	v_mfma_f32_16x16x32_bf16 v[20:23], v[172:175], v[204:207], v[20:23]
	v_mfma_f32_16x16x32_bf16 v[16:19], v[180:183], v[204:207], v[16:19]
	v_mfma_f32_16x16x32_bf16 v[4:7], v[172:175], v[212:215], v[4:7]
	v_mfma_f32_16x16x32_bf16 v[0:3], v[180:183], v[212:215], v[0:3]
	v_mfma_f32_16x16x32_bf16 v[52:55], v[176:179], v[192:195], v[52:55]
	v_mfma_f32_16x16x32_bf16 v[48:51], v[184:187], v[192:195], v[48:51]
	v_mfma_f32_16x16x32_bf16 v[36:39], v[176:179], v[200:203], v[36:39]
	v_mfma_f32_16x16x32_bf16 v[32:35], v[184:187], v[200:203], v[32:35]
	v_mfma_f32_16x16x32_bf16 v[20:23], v[176:179], v[208:211], v[20:23]
	v_mfma_f32_16x16x32_bf16 v[16:19], v[184:187], v[208:211], v[16:19]
	v_mfma_f32_16x16x32_bf16 v[4:7], v[176:179], v[216:219], v[4:7]
	v_mfma_f32_16x16x32_bf16 v[0:3], v[184:187], v[216:219], v[0:3]
	s_barrier
	s_add_i32 s63, s63, 2
	s_add_u32 s19, s19, 0x100
	s_addc_u32 s57, s57, 0
	s_add_u32 s8, s8, 0x100
	s_addc_u32 s9, s9, 0
	s_cmp_gt_u32 s63, 13
	s_cbranch_scc0 .LBB0_477
	s_and_b64 vcc, exec, s[50:51]
	s_cbranch_vccz .LBB0_480
	s_barrier

; #define PG8_STAGE(bufoff, gbase, voff) do { _Pragma("unroll") for (int _i = 0; _i < 2; ++_i) \
;         __builtin_amdgcn_global_load_lds((const unsigned*)((const char*)(gbase) + (voff)[_i]), (LAS unsigned*)(lds + (bufoff) + ldsw + _i * 8192), 16, 0, 0); } while (0)
; #define PG8_LDA(dst, b, h) do { _Pragma("unroll") for (int m = 0; m < 4; ++m) _Pragma("unroll") for (int k = 0; k < 2; ++k) dst[m][k] = *(const LAS bf16x8*)(lds + PG8_SA(b, h) + aoff + m * 2048 + k * 1024); } while (0)
; #define PG8_LDB(dst, b, h) do { _Pragma("unroll") for (int n = 0; n < 2; ++n) _Pragma("unroll") for (int k = 0; k < 2; ++k) dst[n][k] = *(const LAS bf16x8*)(lds + PG8_SB(b, h) + boff + n * 2048 + k * 1024); } while (0)
; #define PG8_MMA(ai, bj, At, Bt) do { __builtin_amdgcn_s_setprio(1); _Pragma("unroll") for (int m = 0; m < 4; ++m) _Pragma("unroll") for (int n = 0; n < 2; ++n) _Pragma("unroll") for (int k = 0; k < 2; ++k) \
;         acc[ai][bj][m][n] = __builtin_amdgcn_mfma_f32_16x16x32_bf16(Bt[n][k], At[m][k], acc[ai][bj][m][n], 0, 0, 0); __builtin_amdgcn_s_setprio(0); } while (0)
; #define PG8_WAIT_V(n) asm volatile("s_waitcnt vmcnt(" #n ")" ::: "memory")
; #define PG8_WAIT_L(n) asm volatile("s_waitcnt lgkmcnt(" #n ")" ::: "memory")
; #define PG8_BAR __builtin_amdgcn_s_barrier()
; #define PG8_SCHED __builtin_amdgcn_sched_barrier(0)
; template <class Epi, class Sched>
; __device__ __forceinline__ void gemm_phase(LAS unsigned char* lds, const int K, const int lda, const int ldb, const Sched& S, const Epi& E) {
;     ...
;         for (int t = 0; t < nt; t += 2) {
;             const bool last = (t == nt - 2);
;             const char* a1 = cA + (size_t)(t + 1) * kstep;
;             const char* a2 = last ? nA : cA + (size_t)(t + 2) * kstep; const char* b2 = last ? nB : cB + (size_t)(t + 2) * kstep;
;             const char* a3 = a2 + kstep; const char* b3 = b2 + kstep;
;             PG8_LDB(B0, 0, 0); PG8_LDB(B1, 0, 1); PG8_SCHED; PG8_LDA(At, 0, 0); PG8_STAGE(PG8_SA(1, 1), a1 + hA, voffA);
;             PG8_WAIT_V(8); PG8_WAIT_L(0); PG8_BAR; PG8_MMA(0, 0, At, B0); PG8_MMA(0, 1, At, B1); PG8_BAR; PG8_SCHED;
;             PG8_LDA(At, 0, 1); PG8_STAGE(PG8_SB(0, 0), b2, voffB); PG8_STAGE(PG8_SB(0, 1), b2 + hB, voffB); PG8_STAGE(PG8_SA(0, 0), a2, voffA);
.LBB0_619:
	ds_read_b128 v[128:131], v208
	ds_read_b128 v[132:135], v235
	ds_read_b128 v[136:139], v208 offset:2048
	ds_read_b128 v[140:143], v235 offset:2048
	ds_read_b128 v[144:147], v209
	ds_read_b128 v[148:151], v236
	ds_read_b128 v[152:155], v209 offset:2048
	ds_read_b128 v[156:159], v236 offset:2048
	s_add_u32 s53, s62, 0xfff80080
	s_addc_u32 s55, s63, -1
	s_cmp_eq_u32 s47, 28
	s_cselect_b32 s67, s18, s55
	s_cselect_b32 s66, s19, s53
	s_cselect_b32 s65, s35, s41
	s_cselect_b32 s64, s38, s39
	v_lshl_add_u64 v[218:219], s[62:63], 0, v[186:187]
	s_add_i32 m0, s5, 0xc000
	ds_read_b128 v[160:163], v210
	ds_read_b128 v[164:167], v234
	ds_read_b128 v[168:171], v210 offset:2048
	ds_read_b128 v[172:175], v234 offset:2048
	ds_read_b128 v[192:195], v210 offset:4096
	ds_read_b128 v[196:199], v234 offset:4096
	ds_read_b128 v[200:203], v210 offset:6144
	ds_read_b128 v[214:217], v234 offset:6144
	global_load_lds_dwordx4 v[218:219], off
	v_lshl_add_u64 v[218:219], s[62:63], 0, v[184:185]
	s_add_i32 m0, s5, 0xe000
	s_nop 0
	global_load_lds_dwordx4 v[218:219], off
	s_waitcnt vmcnt(8)
	s_waitcnt lgkmcnt(0)
	s_barrier
	s_waitcnt lgkmcnt(0)
	v_mfma_f32_16x16x32_bf16 v[124:127], v[160:163], v[128:131], v[124:127]
	v_mfma_f32_16x16x32_bf16 v[120:123], v[160:163], v[136:139], v[120:123]
	v_mfma_f32_16x16x32_bf16 v[108:111], v[168:171], v[128:131], v[108:111]
	v_mfma_f32_16x16x32_bf16 v[104:107], v[168:171], v[136:139], v[104:107]
	v_mfma_f32_16x16x32_bf16 v[92:95], v[192:195], v[128:131], v[92:95]
	v_mfma_f32_16x16x32_bf16 v[88:91], v[192:195], v[136:139], v[88:91]
	v_mfma_f32_16x16x32_bf16 v[76:79], v[200:203], v[128:131], v[76:79]
	v_mfma_f32_16x16x32_bf16 v[72:75], v[200:203], v[136:139], v[72:75]
	v_mfma_f32_16x16x32_bf16 v[124:127], v[164:167], v[132:135], v[124:127]
	v_mfma_f32_16x16x32_bf16 v[120:123], v[164:167], v[140:143], v[120:123]
	v_mfma_f32_16x16x32_bf16 v[108:111], v[172:175], v[132:135], v[108:111]
	v_mfma_f32_16x16x32_bf16 v[104:107], v[172:175], v[140:143], v[104:107]
	v_mfma_f32_16x16x32_bf16 v[92:95], v[196:199], v[132:135], v[92:95]
	v_mfma_f32_16x16x32_bf16 v[88:91], v[196:199], v[140:143], v[88:91]
	v_mfma_f32_16x16x32_bf16 v[76:79], v[214:217], v[132:135], v[76:79]
	v_mfma_f32_16x16x32_bf16 v[72:75], v[214:217], v[140:143], v[72:75]
	v_mfma_f32_16x16x32_bf16 v[116:119], v[160:163], v[144:147], v[116:119]
	v_mfma_f32_16x16x32_bf16 v[112:115], v[160:163], v[152:155], v[112:115]
	v_mfma_f32_16x16x32_bf16 v[100:103], v[168:171], v[144:147], v[100:103]
	v_mfma_f32_16x16x32_bf16 v[96:99], v[168:171], v[152:155], v[96:99]
	v_mfma_f32_16x16x32_bf16 v[84:87], v[192:195], v[144:147], v[84:87]
	v_mfma_f32_16x16x32_bf16 v[80:83], v[192:195], v[152:155], v[80:83]
	v_mfma_f32_16x16x32_bf16 v[68:71], v[200:203], v[144:147], v[68:71]
	v_mfma_f32_16x16x32_bf16 v[64:67], v[200:203], v[152:155], v[64:67]
	v_mfma_f32_16x16x32_bf16 v[116:119], v[164:167], v[148:151], v[116:119]
	v_mfma_f32_16x16x32_bf16 v[112:115], v[164:167], v[156:159], v[112:115]
	v_mfma_f32_16x16x32_bf16 v[100:103], v[172:175], v[148:151], v[100:103]
	v_mfma_f32_16x16x32_bf16 v[96:99], v[172:175], v[156:159], v[96:99]
	v_mfma_f32_16x16x32_bf16 v[84:87], v[196:199], v[148:151], v[84:87]
	v_mfma_f32_16x16x32_bf16 v[80:83], v[196:199], v[156:159], v[80:83]
	v_mfma_f32_16x16x32_bf16 v[68:71], v[214:217], v[148:151], v[68:71]
	v_mfma_f32_16x16x32_bf16 v[64:67], v[214:217], v[156:159], v[64:67]
	s_barrier
	s_add_i32 s53, s29, s1
	v_lshl_add_u64 v[218:219], s[64:65], 0, v[178:179]
	s_mov_b32 m0, s53
	ds_read_b128 v[160:163], v210 offset:16384
	ds_read_b128 v[164:167], v234 offset:16384
	ds_read_b128 v[168:171], v210 offset:18432
	ds_read_b128 v[172:175], v234 offset:18432
	ds_read_b128 v[192:195], v210 offset:20480
	ds_read_b128 v[196:199], v234 offset:20480
	ds_read_b128 v[200:203], v210 offset:22528
	ds_read_b128 v[214:217], v234 offset:22528
	global_load_lds_dwordx4 v[218:219], off
	s_add_i32 m0, s53, 0x2000
	s_add_u32 s68, s64, 0x80000
	v_lshl_add_u64 v[220:221], s[64:65], 0, v[182:183]
	s_addc_u32 s69, s65, 0
	s_add_i32 s53, s34, s1
	global_load_lds_dwordx4 v[220:221], off
	v_lshl_add_u64 v[222:223], s[68:69], 0, v[178:179]
	s_mov_b32 m0, s53
	v_lshl_add_u64 v[224:225], s[66:67], 0, v[180:181]
	global_load_lds_dwordx4 v[222:223], off
	v_lshl_add_u64 v[222:223], s[68:69], 0, v[182:183]
	s_add_i32 m0, s53, 0x2000
	s_nop 0
	global_load_lds_dwordx4 v[222:223], off
	v_lshl_add_u64 v[222:223], s[66:67], 0, v[176:177]
	s_mov_b32 m0, s5
	s_nop 0
	global_load_lds_dwordx4 v[222:223], off
	s_mov_b32 m0, s14
	s_nop 0
	global_load_lds_dwordx4 v[224:225], off
	s_waitcnt vmcnt(8)
	s_waitcnt lgkmcnt(0)
	s_barrier
; #define PG8_STAGE(bufoff, gbase, voff) do { _Pragma("unroll") for (int _i = 0; _i < 2; ++_i) \
;         __builtin_amdgcn_global_load_lds((const unsigned*)((const char*)(gbase) + (voff)[_i]), (LAS unsigned*)(lds + (bufoff) + ldsw + _i * 8192), 16, 0, 0); } while (0)
; #define PG8_LDA(dst, b, h) do { _Pragma("unroll") for (int m = 0; m < 4; ++m) _Pragma("unroll") for (int k = 0; k < 2; ++k) dst[m][k] = *(const LAS bf16x8*)(lds + PG8_SA(b, h) + aoff + m * 2048 + k * 1024); } while (0)
; #define PG8_LDB(dst, b, h) do { _Pragma("unroll") for (int n = 0; n < 2; ++n) _Pragma("unroll") for (int k = 0; k < 2; ++k) dst[n][k] = *(const LAS bf16x8*)(lds + PG8_SB(b, h) + boff + n * 2048 + k * 1024); } while (0)
; #define PG8_MMA(ai, bj, At, Bt) do { __builtin_amdgcn_s_setprio(1); _Pragma("unroll") for (int m = 0; m < 4; ++m) _Pragma("unroll") for (int n = 0; n < 2; ++n) _Pragma("unroll") for (int k = 0; k < 2; ++k) \
;         acc[ai][bj][m][n] = __builtin_amdgcn_mfma_f32_16x16x32_bf16(Bt[n][k], At[m][k], acc[ai][bj][m][n], 0, 0, 0); __builtin_amdgcn_s_setprio(0); } while (0)
; #define PG8_WAIT_V(n) asm volatile("s_waitcnt vmcnt(" #n ")" ::: "memory")
; #define PG8_WAIT_L(n) asm volatile("s_waitcnt lgkmcnt(" #n ")" ::: "memory")
; #define PG8_BAR __builtin_amdgcn_s_barrier()
; #define PG8_SCHED __builtin_amdgcn_sched_barrier(0)
; template <class Epi, class Sched>
; __device__ __forceinline__ void gemm_phase(LAS unsigned char* lds, const int K, const int lda, const int ldb, const Sched& S, const Epi& E) {
;     ...
;             PG8_WAIT_V(8); PG8_WAIT_L(0); PG8_BAR; PG8_MMA(1, 0, At, B0); PG8_MMA(1, 1, At, B1); PG8_BAR; PG8_SCHED;
;             PG8_LDB(B0, 1, 0); PG8_LDB(B1, 1, 1); PG8_SCHED; PG8_LDA(At, 1, 0); PG8_STAGE(PG8_SA(0, 1), a2 + hA, voffA);
;             PG8_WAIT_V(8); PG8_WAIT_L(0); PG8_BAR; PG8_MMA(0, 0, At, B0); PG8_MMA(0, 1, At, B1); PG8_BAR; PG8_SCHED;
	s_waitcnt lgkmcnt(0)
	v_mfma_f32_16x16x32_bf16 v[60:63], v[160:163], v[128:131], v[60:63]
	v_mfma_f32_16x16x32_bf16 v[56:59], v[160:163], v[136:139], v[56:59]
	v_mfma_f32_16x16x32_bf16 v[44:47], v[168:171], v[128:131], v[44:47]
	v_mfma_f32_16x16x32_bf16 v[40:43], v[168:171], v[136:139], v[40:43]
	v_mfma_f32_16x16x32_bf16 v[28:31], v[192:195], v[128:131], v[28:31]
	v_mfma_f32_16x16x32_bf16 v[24:27], v[192:195], v[136:139], v[24:27]
	v_mfma_f32_16x16x32_bf16 v[12:15], v[200:203], v[128:131], v[12:15]
	v_mfma_f32_16x16x32_bf16 v[8:11], v[200:203], v[136:139], v[8:11]
	v_mfma_f32_16x16x32_bf16 v[60:63], v[164:167], v[132:135], v[60:63]
	v_mfma_f32_16x16x32_bf16 v[56:59], v[164:167], v[140:143], v[56:59]
	v_mfma_f32_16x16x32_bf16 v[44:47], v[172:175], v[132:135], v[44:47]
	v_mfma_f32_16x16x32_bf16 v[40:43], v[172:175], v[140:143], v[40:43]
	v_mfma_f32_16x16x32_bf16 v[28:31], v[196:199], v[132:135], v[28:31]
	v_mfma_f32_16x16x32_bf16 v[24:27], v[196:199], v[140:143], v[24:27]
	v_mfma_f32_16x16x32_bf16 v[12:15], v[214:217], v[132:135], v[12:15]
	v_mfma_f32_16x16x32_bf16 v[8:11], v[214:217], v[140:143], v[8:11]
	v_mfma_f32_16x16x32_bf16 v[52:55], v[160:163], v[144:147], v[52:55]
	v_mfma_f32_16x16x32_bf16 v[48:51], v[160:163], v[152:155], v[48:51]
	v_mfma_f32_16x16x32_bf16 v[36:39], v[168:171], v[144:147], v[36:39]
	v_mfma_f32_16x16x32_bf16 v[32:35], v[168:171], v[152:155], v[32:35]
	v_mfma_f32_16x16x32_bf16 v[20:23], v[192:195], v[144:147], v[20:23]
	v_mfma_f32_16x16x32_bf16 v[16:19], v[192:195], v[152:155], v[16:19]
	v_mfma_f32_16x16x32_bf16 v[4:7], v[200:203], v[144:147], v[4:7]
	v_mfma_f32_16x16x32_bf16 v[0:3], v[200:203], v[152:155], v[0:3]
	v_mfma_f32_16x16x32_bf16 v[52:55], v[164:167], v[148:151], v[52:55]
	v_mfma_f32_16x16x32_bf16 v[48:51], v[164:167], v[156:159], v[48:51]
	v_mfma_f32_16x16x32_bf16 v[36:39], v[172:175], v[148:151], v[36:39]
	v_mfma_f32_16x16x32_bf16 v[32:35], v[172:175], v[156:159], v[32:35]
	v_mfma_f32_16x16x32_bf16 v[20:23], v[196:199], v[148:151], v[20:23]
	v_mfma_f32_16x16x32_bf16 v[16:19], v[196:199], v[156:159], v[16:19]
	v_mfma_f32_16x16x32_bf16 v[4:7], v[214:217], v[148:151], v[4:7]
	v_mfma_f32_16x16x32_bf16 v[0:3], v[214:217], v[156:159], v[0:3]
	s_barrier
	s_add_i32 s53, 0, 0x18000
	s_add_i32 s55, 0, 0x1c000
	v_add_u32_e32 v140, s53, v205
	v_add_u32_e32 v238, s53, v237
	v_add_u32_e32 v156, 0x19000, v205
	v_add_u32_e32 v239, 0x19000, v237
	ds_read_b128 v[128:131], v140
	ds_read_b128 v[132:135], v238
	ds_read_b128 v[136:139], v140 offset:2048
	ds_read_b128 v[140:143], v238 offset:2048
	ds_read_b128 v[144:147], v156
	ds_read_b128 v[148:151], v239
	ds_read_b128 v[152:155], v156 offset:2048
	ds_read_b128 v[156:159], v239 offset:2048
	s_add_u32 s66, s66, 0x80000
	s_addc_u32 s67, s67, 0
	s_mov_b32 m0, s15
	v_lshl_add_u64 v[226:227], s[66:67], 0, v[176:177]
	ds_read_b128 v[160:163], v210 offset:32768
	ds_read_b128 v[164:167], v234 offset:32768
	ds_read_b128 v[168:171], v210 offset:34816
	ds_read_b128 v[172:175], v234 offset:34816
	ds_read_b128 v[192:195], v210 offset:36864
	ds_read_b128 v[196:199], v234 offset:36864
	ds_read_b128 v[200:203], v210 offset:38912
	ds_read_b128 v[214:217], v234 offset:38912
	global_load_lds_dwordx4 v[226:227], off
	v_lshl_add_u64 v[226:227], s[66:67], 0, v[180:181]
	s_mov_b32 m0, s17
	s_nop 0
	global_load_lds_dwordx4 v[226:227], off
	s_waitcnt vmcnt(8)
	s_waitcnt lgkmcnt(0)
	s_barrier
	s_waitcnt lgkmcnt(0)
	v_mfma_f32_16x16x32_bf16 v[124:127], v[160:163], v[128:131], v[124:127]
	v_mfma_f32_16x16x32_bf16 v[120:123], v[160:163], v[136:139], v[120:123]
	v_mfma_f32_16x16x32_bf16 v[108:111], v[168:171], v[128:131], v[108:111]
	v_mfma_f32_16x16x32_bf16 v[104:107], v[168:171], v[136:139], v[104:107]
	v_mfma_f32_16x16x32_bf16 v[92:95], v[192:195], v[128:131], v[92:95]
	v_mfma_f32_16x16x32_bf16 v[88:91], v[192:195], v[136:139], v[88:91]
	v_mfma_f32_16x16x32_bf16 v[76:79], v[200:203], v[128:131], v[76:79]
	v_mfma_f32_16x16x32_bf16 v[72:75], v[200:203], v[136:139], v[72:75]
	v_mfma_f32_16x16x32_bf16 v[124:127], v[164:167], v[132:135], v[124:127]
	v_mfma_f32_16x16x32_bf16 v[120:123], v[164:167], v[140:143], v[120:123]
	v_mfma_f32_16x16x32_bf16 v[108:111], v[172:175], v[132:135], v[108:111]
	v_mfma_f32_16x16x32_bf16 v[104:107], v[172:175], v[140:143], v[104:107]
	v_mfma_f32_16x16x32_bf16 v[92:95], v[196:199], v[132:135], v[92:95]
	v_mfma_f32_16x16x32_bf16 v[88:91], v[196:199], v[140:143], v[88:91]
	v_mfma_f32_16x16x32_bf16 v[76:79], v[214:217], v[132:135], v[76:79]
	v_mfma_f32_16x16x32_bf16 v[72:75], v[214:217], v[140:143], v[72:75]
	v_mfma_f32_16x16x32_bf16 v[116:119], v[160:163], v[144:147], v[116:119]
	v_mfma_f32_16x16x32_bf16 v[112:115], v[160:163], v[152:155], v[112:115]
	v_mfma_f32_16x16x32_bf16 v[100:103], v[168:171], v[144:147], v[100:103]
	v_mfma_f32_16x16x32_bf16 v[96:99], v[168:171], v[152:155], v[96:99]
	v_mfma_f32_16x16x32_bf16 v[84:87], v[192:195], v[144:147], v[84:87]
	v_mfma_f32_16x16x32_bf16 v[80:83], v[192:195], v[152:155], v[80:83]
	v_mfma_f32_16x16x32_bf16 v[68:71], v[200:203], v[144:147], v[68:71]
	v_mfma_f32_16x16x32_bf16 v[64:67], v[200:203], v[152:155], v[64:67]
	v_mfma_f32_16x16x32_bf16 v[116:119], v[164:167], v[148:151], v[116:119]
	v_mfma_f32_16x16x32_bf16 v[112:115], v[164:167], v[156:159], v[112:115]
	v_mfma_f32_16x16x32_bf16 v[100:103], v[172:175], v[148:151], v[100:103]
	v_mfma_f32_16x16x32_bf16 v[96:99], v[172:175], v[156:159], v[96:99]
	v_mfma_f32_16x16x32_bf16 v[84:87], v[196:199], v[148:151], v[84:87]
	v_mfma_f32_16x16x32_bf16 v[80:83], v[196:199], v[156:159], v[80:83]
	v_mfma_f32_16x16x32_bf16 v[68:71], v[214:217], v[148:151], v[68:71]
	v_mfma_f32_16x16x32_bf16 v[64:67], v[214:217], v[156:159], v[64:67]
	s_barrier
; #define PG8_STAGE(bufoff, gbase, voff) do { _Pragma("unroll") for (int _i = 0; _i < 2; ++_i) \
;         __builtin_amdgcn_global_load_lds((const unsigned*)((const char*)(gbase) + (voff)[_i]), (LAS unsigned*)(lds + (bufoff) + ldsw + _i * 8192), 16, 0, 0); } while (0)
; #define PG8_LDA(dst, b, h) do { _Pragma("unroll") for (int m = 0; m < 4; ++m) _Pragma("unroll") for (int k = 0; k < 2; ++k) dst[m][k] = *(const LAS bf16x8*)(lds + PG8_SA(b, h) + aoff + m * 2048 + k * 1024); } while (0)
; #define PG8_MMA(ai, bj, At, Bt) do { __builtin_amdgcn_s_setprio(1); _Pragma("unroll") for (int m = 0; m < 4; ++m) _Pragma("unroll") for (int n = 0; n < 2; ++n) _Pragma("unroll") for (int k = 0; k < 2; ++k) \
;         acc[ai][bj][m][n] = __builtin_amdgcn_mfma_f32_16x16x32_bf16(Bt[n][k], At[m][k], acc[ai][bj][m][n], 0, 0, 0); __builtin_amdgcn_s_setprio(0); } while (0)
; #define PG8_WAIT_V(n) asm volatile("s_waitcnt vmcnt(" #n ")" ::: "memory")
; #define PG8_WAIT_L(n) asm volatile("s_waitcnt lgkmcnt(" #n ")" ::: "memory")
; #define PG8_BAR __builtin_amdgcn_s_barrier()
; #define PG8_SCHED __builtin_amdgcn_sched_barrier(0)
; template <class Epi, class Sched>
; __device__ __forceinline__ void gemm_phase(LAS unsigned char* lds, const int K, const int lda, const int ldb, const Sched& S, const Epi& E) {
;     ...
;             PG8_LDA(At, 1, 1); PG8_STAGE(PG8_SB(1, 0), b3, voffB); PG8_STAGE(PG8_SB(1, 1), b3 + hB, voffB); PG8_STAGE(PG8_SA(1, 0), a3, voffA);
;             PG8_WAIT_V(8); PG8_WAIT_L(0); PG8_BAR; PG8_MMA(1, 0, At, B0); PG8_MMA(1, 1, At, B1); PG8_BAR; PG8_SCHED;
;         }
;         if (wr == 0) PG8_BAR;
	s_add_i32 s53, s53, s1
	v_lshl_add_u64 v[218:219], v[218:219], 0, s[48:49]
	s_mov_b32 m0, s53
	ds_read_b128 v[160:163], v210 offset:49152
	ds_read_b128 v[164:167], v234 offset:49152
	ds_read_b128 v[168:171], v210 offset:51200
	ds_read_b128 v[172:175], v234 offset:51200
	ds_read_b128 v[192:195], v210 offset:53248
	ds_read_b128 v[196:199], v234 offset:53248
	ds_read_b128 v[200:203], v210 offset:55296
	ds_read_b128 v[214:217], v234 offset:55296
	global_load_lds_dwordx4 v[218:219], off
	s_add_i32 m0, s53, 0x2000
	s_add_u32 s64, s64, 0x80080
	v_lshl_add_u64 v[218:219], v[220:221], 0, s[48:49]
	s_addc_u32 s65, s65, 0
	s_add_i32 s53, s55, s1
	global_load_lds_dwordx4 v[218:219], off
	v_lshl_add_u64 v[218:219], s[64:65], 0, v[178:179]
	s_mov_b32 m0, s53
	s_nop 0
	global_load_lds_dwordx4 v[218:219], off
	v_lshl_add_u64 v[218:219], s[64:65], 0, v[182:183]
	s_add_i32 m0, s53, 0x2000
	s_nop 0
	global_load_lds_dwordx4 v[218:219], off
	v_lshl_add_u64 v[218:219], v[222:223], 0, s[48:49]
	s_mov_b32 m0, s0
	s_nop 0
	global_load_lds_dwordx4 v[218:219], off
	v_lshl_add_u64 v[218:219], v[224:225], 0, s[48:49]
	s_mov_b32 m0, s24
	s_nop 0
	global_load_lds_dwordx4 v[218:219], off
	s_waitcnt vmcnt(8)
	s_waitcnt lgkmcnt(0)
	s_barrier
	s_waitcnt lgkmcnt(0)
	v_mfma_f32_16x16x32_bf16 v[60:63], v[160:163], v[128:131], v[60:63]
	v_mfma_f32_16x16x32_bf16 v[56:59], v[160:163], v[136:139], v[56:59]
	v_mfma_f32_16x16x32_bf16 v[44:47], v[168:171], v[128:131], v[44:47]
	v_mfma_f32_16x16x32_bf16 v[40:43], v[168:171], v[136:139], v[40:43]
	v_mfma_f32_16x16x32_bf16 v[28:31], v[192:195], v[128:131], v[28:31]
	v_mfma_f32_16x16x32_bf16 v[24:27], v[192:195], v[136:139], v[24:27]
	v_mfma_f32_16x16x32_bf16 v[12:15], v[200:203], v[128:131], v[12:15]
	v_mfma_f32_16x16x32_bf16 v[8:11], v[200:203], v[136:139], v[8:11]
	v_mfma_f32_16x16x32_bf16 v[60:63], v[164:167], v[132:135], v[60:63]
	v_mfma_f32_16x16x32_bf16 v[56:59], v[164:167], v[140:143], v[56:59]
	v_mfma_f32_16x16x32_bf16 v[44:47], v[172:175], v[132:135], v[44:47]
	v_mfma_f32_16x16x32_bf16 v[40:43], v[172:175], v[140:143], v[40:43]
	v_mfma_f32_16x16x32_bf16 v[28:31], v[196:199], v[132:135], v[28:31]
	v_mfma_f32_16x16x32_bf16 v[24:27], v[196:199], v[140:143], v[24:27]
	v_mfma_f32_16x16x32_bf16 v[12:15], v[214:217], v[132:135], v[12:15]
	v_mfma_f32_16x16x32_bf16 v[8:11], v[214:217], v[140:143], v[8:11]
	v_mfma_f32_16x16x32_bf16 v[52:55], v[160:163], v[144:147], v[52:55]
	v_mfma_f32_16x16x32_bf16 v[48:51], v[160:163], v[152:155], v[48:51]
	v_mfma_f32_16x16x32_bf16 v[36:39], v[168:171], v[144:147], v[36:39]
	v_mfma_f32_16x16x32_bf16 v[32:35], v[168:171], v[152:155], v[32:35]
	v_mfma_f32_16x16x32_bf16 v[20:23], v[192:195], v[144:147], v[20:23]
	v_mfma_f32_16x16x32_bf16 v[16:19], v[192:195], v[152:155], v[16:19]
	v_mfma_f32_16x16x32_bf16 v[4:7], v[200:203], v[144:147], v[4:7]
	v_mfma_f32_16x16x32_bf16 v[0:3], v[200:203], v[152:155], v[0:3]
	v_mfma_f32_16x16x32_bf16 v[52:55], v[164:167], v[148:151], v[52:55]
	v_mfma_f32_16x16x32_bf16 v[48:51], v[164:167], v[156:159], v[48:51]
	v_mfma_f32_16x16x32_bf16 v[36:39], v[172:175], v[148:151], v[36:39]
	v_mfma_f32_16x16x32_bf16 v[32:35], v[172:175], v[156:159], v[32:35]
	v_mfma_f32_16x16x32_bf16 v[20:23], v[196:199], v[148:151], v[20:23]
	v_mfma_f32_16x16x32_bf16 v[16:19], v[196:199], v[156:159], v[16:19]
	v_mfma_f32_16x16x32_bf16 v[4:7], v[214:217], v[148:151], v[4:7]
	v_mfma_f32_16x16x32_bf16 v[0:3], v[214:217], v[156:159], v[0:3]
	s_barrier
	s_add_i32 s47, s47, 2
	s_add_u32 s39, s39, 0x100
	s_addc_u32 s41, s41, 0
	s_add_u32 s62, s62, 0x100
	s_addc_u32 s63, s63, 0
	s_cmp_gt_u32 s47, 29
	s_cbranch_scc0 .LBB0_619
	s_and_b64 vcc, exec, s[50:51]
	s_cbranch_vccz .LBB0_622
	s_barrier

; #define PG8_STAGE(bufoff, gbase, voff) do { _Pragma("unroll") for (int _i = 0; _i < 2; ++_i) \
;         __builtin_amdgcn_global_load_lds((const unsigned*)((const char*)(gbase) + (voff)[_i]), (LAS unsigned*)(lds + (bufoff) + ldsw + _i * 8192), 16, 0, 0); } while (0)
; #define PG8_LDA(dst, b, h) do { _Pragma("unroll") for (int m = 0; m < 4; ++m) _Pragma("unroll") for (int k = 0; k < 2; ++k) dst[m][k] = *(const LAS bf16x8*)(lds + PG8_SA(b, h) + aoff + m * 2048 + k * 1024); } while (0)
; #define PG8_LDB(dst, b, h) do { _Pragma("unroll") for (int n = 0; n < 2; ++n) _Pragma("unroll") for (int k = 0; k < 2; ++k) dst[n][k] = *(const LAS bf16x8*)(lds + PG8_SB(b, h) + boff + n * 2048 + k * 1024); } while (0)
; #define PG8_MMA(ai, bj, At, Bt) do { __builtin_amdgcn_s_setprio(1); _Pragma("unroll") for (int m = 0; m < 4; ++m) _Pragma("unroll") for (int n = 0; n < 2; ++n) _Pragma("unroll") for (int k = 0; k < 2; ++k) \
;         acc[ai][bj][m][n] = __builtin_amdgcn_mfma_f32_16x16x32_bf16(Bt[n][k], At[m][k], acc[ai][bj][m][n], 0, 0, 0); __builtin_amdgcn_s_setprio(0); } while (0)
; #define PG8_WAIT_V(n) asm volatile("s_waitcnt vmcnt(" #n ")" ::: "memory")
; #define PG8_WAIT_L(n) asm volatile("s_waitcnt lgkmcnt(" #n ")" ::: "memory")
; #define PG8_BAR __builtin_amdgcn_s_barrier()
; #define PG8_SCHED __builtin_amdgcn_sched_barrier(0)
; template <class Epi, class Sched>
; __device__ __forceinline__ void gemm_phase(LAS unsigned char* lds, const int K, const int lda, const int ldb, const Sched& S, const Epi& E) {
;     ...
;         for (int t = 0; t < nt; t += 2) {
;             const bool last = (t == nt - 2);
;             const char* a1 = cA + (size_t)(t + 1) * kstep;
;             const char* a2 = last ? nA : cA + (size_t)(t + 2) * kstep; const char* b2 = last ? nB : cB + (size_t)(t + 2) * kstep;
;             const char* a3 = a2 + kstep; const char* b3 = b2 + kstep;
;             PG8_LDB(B0, 0, 0); PG8_LDB(B1, 0, 1); PG8_SCHED; PG8_LDA(At, 0, 0); PG8_STAGE(PG8_SA(1, 1), a1 + hA, voffA);
;             PG8_WAIT_V(8); PG8_WAIT_L(0); PG8_BAR; PG8_MMA(0, 0, At, B0); PG8_MMA(0, 1, At, B1); PG8_BAR; PG8_SCHED;
;             PG8_LDA(At, 0, 1); PG8_STAGE(PG8_SB(0, 0), b2, voffB); PG8_STAGE(PG8_SB(0, 1), b2 + hB, voffB); PG8_STAGE(PG8_SA(0, 0), a2, voffA);
.LBB0_695:
	s_waitcnt lgkmcnt(0)
	ds_read_b128 v[158:161], v236
	ds_read_b128 v[162:165], v248
	ds_read_b128 v[166:169], v236 offset:2048
	ds_read_b128 v[170:173], v248 offset:2048
	ds_read_b128 v[174:177], v237
	ds_read_b128 v[178:181], v249
	ds_read_b128 v[182:185], v237 offset:2048
	ds_read_b128 v[186:189], v249 offset:2048
	s_add_u32 s38, s64, 0xfff80080
	s_addc_u32 s39, s65, -1
	s_cmp_eq_u32 s29, 28
	s_cselect_b32 s71, s0, s39
	s_cselect_b32 s70, s1, s38
	s_cselect_b32 s69, s13, s28
	s_cselect_b32 s68, s18, s19
	v_lshl_add_u64 v[222:223], s[64:65], 0, v[148:149]
	s_add_i32 m0, s4, 0xc000
	ds_read_b128 v[190:193], v145
	ds_read_b128 v[194:197], v247
	ds_read_b128 v[198:201], v145 offset:2048
	ds_read_b128 v[202:205], v247 offset:2048
	ds_read_b128 v[206:209], v145 offset:4096
	ds_read_b128 v[210:213], v247 offset:4096
	ds_read_b128 v[214:217], v145 offset:6144
	ds_read_b128 v[218:221], v247 offset:6144
	global_load_lds_dwordx4 v[222:223], off
	v_lshl_add_u64 v[222:223], s[64:65], 0, v[146:147]
	s_add_i32 m0, s4, 0xe000
	s_nop 0
	global_load_lds_dwordx4 v[222:223], off
	s_waitcnt vmcnt(8)
	s_waitcnt lgkmcnt(0)
	s_barrier
	s_waitcnt lgkmcnt(0)
	v_mfma_f32_16x16x32_bf16 v[124:127], v[158:161], v[190:193], v[124:127]
	v_mfma_f32_16x16x32_bf16 v[116:119], v[166:169], v[190:193], v[116:119]
	v_mfma_f32_16x16x32_bf16 v[108:111], v[158:161], v[198:201], v[108:111]
	v_mfma_f32_16x16x32_bf16 v[100:103], v[166:169], v[198:201], v[100:103]
	v_mfma_f32_16x16x32_bf16 v[92:95], v[158:161], v[206:209], v[92:95]
	v_mfma_f32_16x16x32_bf16 v[84:87], v[166:169], v[206:209], v[84:87]
	v_mfma_f32_16x16x32_bf16 v[76:79], v[158:161], v[214:217], v[76:79]
	v_mfma_f32_16x16x32_bf16 v[68:71], v[166:169], v[214:217], v[68:71]
	v_mfma_f32_16x16x32_bf16 v[124:127], v[162:165], v[194:197], v[124:127]
	v_mfma_f32_16x16x32_bf16 v[116:119], v[170:173], v[194:197], v[116:119]
	v_mfma_f32_16x16x32_bf16 v[108:111], v[162:165], v[202:205], v[108:111]
	v_mfma_f32_16x16x32_bf16 v[100:103], v[170:173], v[202:205], v[100:103]
	v_mfma_f32_16x16x32_bf16 v[92:95], v[162:165], v[210:213], v[92:95]
	v_mfma_f32_16x16x32_bf16 v[84:87], v[170:173], v[210:213], v[84:87]
	v_mfma_f32_16x16x32_bf16 v[76:79], v[162:165], v[218:221], v[76:79]
	v_mfma_f32_16x16x32_bf16 v[68:71], v[170:173], v[218:221], v[68:71]
	v_mfma_f32_16x16x32_bf16 v[120:123], v[174:177], v[190:193], v[120:123]
	v_mfma_f32_16x16x32_bf16 v[112:115], v[182:185], v[190:193], v[112:115]
	v_mfma_f32_16x16x32_bf16 v[104:107], v[174:177], v[198:201], v[104:107]
	v_mfma_f32_16x16x32_bf16 v[96:99], v[182:185], v[198:201], v[96:99]
	v_mfma_f32_16x16x32_bf16 v[88:91], v[174:177], v[206:209], v[88:91]
	v_mfma_f32_16x16x32_bf16 v[80:83], v[182:185], v[206:209], v[80:83]
	v_mfma_f32_16x16x32_bf16 v[72:75], v[174:177], v[214:217], v[72:75]
	v_mfma_f32_16x16x32_bf16 v[64:67], v[182:185], v[214:217], v[64:67]
	v_mfma_f32_16x16x32_bf16 v[120:123], v[178:181], v[194:197], v[120:123]
	v_mfma_f32_16x16x32_bf16 v[112:115], v[186:189], v[194:197], v[112:115]
	v_mfma_f32_16x16x32_bf16 v[104:107], v[178:181], v[202:205], v[104:107]
	v_mfma_f32_16x16x32_bf16 v[96:99], v[186:189], v[202:205], v[96:99]
	v_mfma_f32_16x16x32_bf16 v[88:91], v[178:181], v[210:213], v[88:91]
	v_mfma_f32_16x16x32_bf16 v[80:83], v[186:189], v[210:213], v[80:83]
	v_mfma_f32_16x16x32_bf16 v[72:75], v[178:181], v[218:221], v[72:75]
	v_mfma_f32_16x16x32_bf16 v[64:67], v[186:189], v[218:221], v[64:67]
	s_barrier
	s_add_i32 s38, s79, s2
	v_lshl_add_u64 v[222:223], s[68:69], 0, v[130:131]
	s_mov_b32 m0, s38
	ds_read_b128 v[190:193], v145 offset:16384
	ds_read_b128 v[194:197], v247 offset:16384
	ds_read_b128 v[198:201], v145 offset:18432
	ds_read_b128 v[202:205], v247 offset:18432
	ds_read_b128 v[206:209], v145 offset:20480
	ds_read_b128 v[210:213], v247 offset:20480
	ds_read_b128 v[214:217], v145 offset:22528
	ds_read_b128 v[218:221], v247 offset:22528
	global_load_lds_dwordx4 v[222:223], off
	s_add_i32 m0, s38, 0x2000
	s_add_u32 s38, s68, 0x80000
	v_lshl_add_u64 v[224:225], s[68:69], 0, v[134:135]
	s_addc_u32 s39, s69, 0
	s_add_i32 s41, s80, s2
	global_load_lds_dwordx4 v[224:225], off
	v_lshl_add_u64 v[226:227], s[38:39], 0, v[130:131]
	s_mov_b32 m0, s41
	v_lshl_add_u64 v[228:229], s[70:71], 0, v[132:133]
	global_load_lds_dwordx4 v[226:227], off
	v_lshl_add_u64 v[226:227], s[38:39], 0, v[134:135]
	s_add_i32 m0, s41, 0x2000
	s_nop 0
	global_load_lds_dwordx4 v[226:227], off
	v_lshl_add_u64 v[226:227], s[70:71], 0, v[128:129]
	s_mov_b32 m0, s4
	s_nop 0
	global_load_lds_dwordx4 v[226:227], off
	s_mov_b32 m0, s5
	s_nop 0
	global_load_lds_dwordx4 v[228:229], off
	s_waitcnt vmcnt(8)
	s_waitcnt lgkmcnt(0)
	s_barrier
; #define PG8_STAGE(bufoff, gbase, voff) do { _Pragma("unroll") for (int _i = 0; _i < 2; ++_i) \
;         __builtin_amdgcn_global_load_lds((const unsigned*)((const char*)(gbase) + (voff)[_i]), (LAS unsigned*)(lds + (bufoff) + ldsw + _i * 8192), 16, 0, 0); } while (0)
; #define PG8_LDA(dst, b, h) do { _Pragma("unroll") for (int m = 0; m < 4; ++m) _Pragma("unroll") for (int k = 0; k < 2; ++k) dst[m][k] = *(const LAS bf16x8*)(lds + PG8_SA(b, h) + aoff + m * 2048 + k * 1024); } while (0)
; #define PG8_LDB(dst, b, h) do { _Pragma("unroll") for (int n = 0; n < 2; ++n) _Pragma("unroll") for (int k = 0; k < 2; ++k) dst[n][k] = *(const LAS bf16x8*)(lds + PG8_SB(b, h) + boff + n * 2048 + k * 1024); } while (0)
; #define PG8_MMA(ai, bj, At, Bt) do { __builtin_amdgcn_s_setprio(1); _Pragma("unroll") for (int m = 0; m < 4; ++m) _Pragma("unroll") for (int n = 0; n < 2; ++n) _Pragma("unroll") for (int k = 0; k < 2; ++k) \
;         acc[ai][bj][m][n] = __builtin_amdgcn_mfma_f32_16x16x32_bf16(Bt[n][k], At[m][k], acc[ai][bj][m][n], 0, 0, 0); __builtin_amdgcn_s_setprio(0); } while (0)
; #define PG8_WAIT_V(n) asm volatile("s_waitcnt vmcnt(" #n ")" ::: "memory")
; #define PG8_WAIT_L(n) asm volatile("s_waitcnt lgkmcnt(" #n ")" ::: "memory")
; #define PG8_BAR __builtin_amdgcn_s_barrier()
; #define PG8_SCHED __builtin_amdgcn_sched_barrier(0)
; template <class Epi, class Sched>
; __device__ __forceinline__ void gemm_phase(LAS unsigned char* lds, const int K, const int lda, const int ldb, const Sched& S, const Epi& E) {
;     ...
;             PG8_WAIT_V(8); PG8_WAIT_L(0); PG8_BAR; PG8_MMA(1, 0, At, B0); PG8_MMA(1, 1, At, B1); PG8_BAR; PG8_SCHED;
;             PG8_LDB(B0, 1, 0); PG8_LDB(B1, 1, 1); PG8_SCHED; PG8_LDA(At, 1, 0); PG8_STAGE(PG8_SA(0, 1), a2 + hA, voffA);
;             PG8_WAIT_V(8); PG8_WAIT_L(0); PG8_BAR; PG8_MMA(0, 0, At, B0); PG8_MMA(0, 1, At, B1); PG8_BAR; PG8_SCHED;
	s_waitcnt lgkmcnt(0)
	v_mfma_f32_16x16x32_bf16 v[60:63], v[158:161], v[190:193], v[60:63]
	v_mfma_f32_16x16x32_bf16 v[52:55], v[166:169], v[190:193], v[52:55]
	v_mfma_f32_16x16x32_bf16 v[44:47], v[158:161], v[198:201], v[44:47]
	v_mfma_f32_16x16x32_bf16 v[36:39], v[166:169], v[198:201], v[36:39]
	v_mfma_f32_16x16x32_bf16 v[28:31], v[158:161], v[206:209], v[28:31]
	v_mfma_f32_16x16x32_bf16 v[20:23], v[166:169], v[206:209], v[20:23]
	v_mfma_f32_16x16x32_bf16 v[12:15], v[158:161], v[214:217], v[12:15]
	v_mfma_f32_16x16x32_bf16 v[4:7], v[166:169], v[214:217], v[4:7]
	v_mfma_f32_16x16x32_bf16 v[60:63], v[162:165], v[194:197], v[60:63]
	v_mfma_f32_16x16x32_bf16 v[52:55], v[170:173], v[194:197], v[52:55]
	v_mfma_f32_16x16x32_bf16 v[44:47], v[162:165], v[202:205], v[44:47]
	v_mfma_f32_16x16x32_bf16 v[36:39], v[170:173], v[202:205], v[36:39]
	v_mfma_f32_16x16x32_bf16 v[28:31], v[162:165], v[210:213], v[28:31]
	v_mfma_f32_16x16x32_bf16 v[20:23], v[170:173], v[210:213], v[20:23]
	v_mfma_f32_16x16x32_bf16 v[12:15], v[162:165], v[218:221], v[12:15]
	v_mfma_f32_16x16x32_bf16 v[4:7], v[170:173], v[218:221], v[4:7]
	v_mfma_f32_16x16x32_bf16 v[56:59], v[174:177], v[190:193], v[56:59]
	v_mfma_f32_16x16x32_bf16 v[48:51], v[182:185], v[190:193], v[48:51]
	v_mfma_f32_16x16x32_bf16 v[40:43], v[174:177], v[198:201], v[40:43]
	v_mfma_f32_16x16x32_bf16 v[32:35], v[182:185], v[198:201], v[32:35]
	v_mfma_f32_16x16x32_bf16 v[24:27], v[174:177], v[206:209], v[24:27]
	v_mfma_f32_16x16x32_bf16 v[16:19], v[182:185], v[206:209], v[16:19]
	v_mfma_f32_16x16x32_bf16 v[8:11], v[174:177], v[214:217], v[8:11]
	v_mfma_f32_16x16x32_bf16 v[0:3], v[182:185], v[214:217], v[0:3]
	v_mfma_f32_16x16x32_bf16 v[56:59], v[178:181], v[194:197], v[56:59]
	v_mfma_f32_16x16x32_bf16 v[48:51], v[186:189], v[194:197], v[48:51]
	v_mfma_f32_16x16x32_bf16 v[40:43], v[178:181], v[202:205], v[40:43]
	v_mfma_f32_16x16x32_bf16 v[32:35], v[186:189], v[202:205], v[32:35]
	v_mfma_f32_16x16x32_bf16 v[24:27], v[178:181], v[210:213], v[24:27]
	v_mfma_f32_16x16x32_bf16 v[16:19], v[186:189], v[210:213], v[16:19]
	v_mfma_f32_16x16x32_bf16 v[8:11], v[178:181], v[218:221], v[8:11]
	v_mfma_f32_16x16x32_bf16 v[0:3], v[186:189], v[218:221], v[0:3]
	s_barrier
	s_add_i32 s41, 0, 0x18000
	v_add_u32_e32 v151, s41, v143
	v_add_u32_e32 v251, s41, v250
	s_add_i32 s57, 0, 0x1c000
	ds_read_b128 v[158:161], v151
	ds_read_b128 v[162:165], v251
	ds_read_b128 v[166:169], v151 offset:2048
	ds_read_b128 v[170:173], v251 offset:2048
	v_add_u32_e32 v151, s57, v143
	v_add_u32_e32 v251, s57, v250
	ds_read_b128 v[174:177], v151
	ds_read_b128 v[178:181], v251
	ds_read_b128 v[182:185], v151 offset:2048
	ds_read_b128 v[186:189], v251 offset:2048
	s_add_u32 s38, s70, 0x80000
	s_addc_u32 s39, s71, 0
	s_mov_b32 m0, s6
	v_lshl_add_u64 v[230:231], s[38:39], 0, v[128:129]
	ds_read_b128 v[190:193], v145 offset:32768
	ds_read_b128 v[194:197], v247 offset:32768
	ds_read_b128 v[198:201], v145 offset:34816
	ds_read_b128 v[202:205], v247 offset:34816
	ds_read_b128 v[206:209], v145 offset:36864
	ds_read_b128 v[210:213], v247 offset:36864
	ds_read_b128 v[214:217], v145 offset:38912
	ds_read_b128 v[218:221], v247 offset:38912
	global_load_lds_dwordx4 v[230:231], off
	v_lshl_add_u64 v[230:231], s[38:39], 0, v[132:133]
	s_mov_b32 m0, s7
	s_nop 0
	global_load_lds_dwordx4 v[230:231], off
	s_waitcnt vmcnt(8)
	s_waitcnt lgkmcnt(0)
	s_barrier
	s_waitcnt lgkmcnt(0)
	v_mfma_f32_16x16x32_bf16 v[124:127], v[158:161], v[190:193], v[124:127]
	v_mfma_f32_16x16x32_bf16 v[116:119], v[166:169], v[190:193], v[116:119]
	v_mfma_f32_16x16x32_bf16 v[108:111], v[158:161], v[198:201], v[108:111]
	v_mfma_f32_16x16x32_bf16 v[100:103], v[166:169], v[198:201], v[100:103]
	v_mfma_f32_16x16x32_bf16 v[92:95], v[158:161], v[206:209], v[92:95]
	v_mfma_f32_16x16x32_bf16 v[84:87], v[166:169], v[206:209], v[84:87]
	v_mfma_f32_16x16x32_bf16 v[76:79], v[158:161], v[214:217], v[76:79]
	v_mfma_f32_16x16x32_bf16 v[68:71], v[166:169], v[214:217], v[68:71]
	v_mfma_f32_16x16x32_bf16 v[124:127], v[162:165], v[194:197], v[124:127]
	v_mfma_f32_16x16x32_bf16 v[116:119], v[170:173], v[194:197], v[116:119]
	v_mfma_f32_16x16x32_bf16 v[108:111], v[162:165], v[202:205], v[108:111]
	v_mfma_f32_16x16x32_bf16 v[100:103], v[170:173], v[202:205], v[100:103]
	v_mfma_f32_16x16x32_bf16 v[92:95], v[162:165], v[210:213], v[92:95]
	v_mfma_f32_16x16x32_bf16 v[84:87], v[170:173], v[210:213], v[84:87]
	v_mfma_f32_16x16x32_bf16 v[76:79], v[162:165], v[218:221], v[76:79]
	v_mfma_f32_16x16x32_bf16 v[68:71], v[170:173], v[218:221], v[68:71]
	v_mfma_f32_16x16x32_bf16 v[120:123], v[174:177], v[190:193], v[120:123]
	v_mfma_f32_16x16x32_bf16 v[112:115], v[182:185], v[190:193], v[112:115]
	v_mfma_f32_16x16x32_bf16 v[104:107], v[174:177], v[198:201], v[104:107]
	v_mfma_f32_16x16x32_bf16 v[96:99], v[182:185], v[198:201], v[96:99]
	v_mfma_f32_16x16x32_bf16 v[88:91], v[174:177], v[206:209], v[88:91]
	v_mfma_f32_16x16x32_bf16 v[80:83], v[182:185], v[206:209], v[80:83]
	v_mfma_f32_16x16x32_bf16 v[72:75], v[174:177], v[214:217], v[72:75]
	v_mfma_f32_16x16x32_bf16 v[64:67], v[182:185], v[214:217], v[64:67]
	v_mfma_f32_16x16x32_bf16 v[120:123], v[178:181], v[194:197], v[120:123]
	v_mfma_f32_16x16x32_bf16 v[112:115], v[186:189], v[194:197], v[112:115]
	v_mfma_f32_16x16x32_bf16 v[104:107], v[178:181], v[202:205], v[104:107]
	v_mfma_f32_16x16x32_bf16 v[96:99], v[186:189], v[202:205], v[96:99]
	v_mfma_f32_16x16x32_bf16 v[88:91], v[178:181], v[210:213], v[88:91]
	v_mfma_f32_16x16x32_bf16 v[80:83], v[186:189], v[210:213], v[80:83]
	v_mfma_f32_16x16x32_bf16 v[72:75], v[178:181], v[218:221], v[72:75]
	v_mfma_f32_16x16x32_bf16 v[64:67], v[186:189], v[218:221], v[64:67]
	s_barrier
; #define PG8_STAGE(bufoff, gbase, voff) do { _Pragma("unroll") for (int _i = 0; _i < 2; ++_i) \
;         __builtin_amdgcn_global_load_lds((const unsigned*)((const char*)(gbase) + (voff)[_i]), (LAS unsigned*)(lds + (bufoff) + ldsw + _i * 8192), 16, 0, 0); } while (0)
; #define PG8_LDA(dst, b, h) do { _Pragma("unroll") for (int m = 0; m < 4; ++m) _Pragma("unroll") for (int k = 0; k < 2; ++k) dst[m][k] = *(const LAS bf16x8*)(lds + PG8_SA(b, h) + aoff + m * 2048 + k * 1024); } while (0)
; #define PG8_MMA(ai, bj, At, Bt) do { __builtin_amdgcn_s_setprio(1); _Pragma("unroll") for (int m = 0; m < 4; ++m) _Pragma("unroll") for (int n = 0; n < 2; ++n) _Pragma("unroll") for (int k = 0; k < 2; ++k) \
;         acc[ai][bj][m][n] = __builtin_amdgcn_mfma_f32_16x16x32_bf16(Bt[n][k], At[m][k], acc[ai][bj][m][n], 0, 0, 0); __builtin_amdgcn_s_setprio(0); } while (0)
; #define PG8_WAIT_V(n) asm volatile("s_waitcnt vmcnt(" #n ")" ::: "memory")
; #define PG8_WAIT_L(n) asm volatile("s_waitcnt lgkmcnt(" #n ")" ::: "memory")
; #define PG8_BAR __builtin_amdgcn_s_barrier()
; #define PG8_SCHED __builtin_amdgcn_sched_barrier(0)
; template <class Epi, class Sched>
; __device__ __forceinline__ void gemm_phase(LAS unsigned char* lds, const int K, const int lda, const int ldb, const Sched& S, const Epi& E) {
;     ...
;             PG8_LDA(At, 1, 1); PG8_STAGE(PG8_SB(1, 0), b3, voffB); PG8_STAGE(PG8_SB(1, 1), b3 + hB, voffB); PG8_STAGE(PG8_SA(1, 0), a3, voffA);
;             PG8_WAIT_V(8); PG8_WAIT_L(0); PG8_BAR; PG8_MMA(1, 0, At, B0); PG8_MMA(1, 1, At, B1); PG8_BAR; PG8_SCHED;
;         }
;         if (wr == 0) PG8_BAR;
	s_add_i32 s38, s41, s2
	v_lshl_add_u64 v[222:223], v[222:223], 0, s[52:53]
	s_mov_b32 m0, s38
	ds_read_b128 v[190:193], v145 offset:49152
	ds_read_b128 v[194:197], v247 offset:49152
	ds_read_b128 v[198:201], v145 offset:51200
	ds_read_b128 v[202:205], v247 offset:51200
	ds_read_b128 v[206:209], v145 offset:53248
	ds_read_b128 v[210:213], v247 offset:53248
	ds_read_b128 v[214:217], v145 offset:55296
	ds_read_b128 v[218:221], v247 offset:55296
	global_load_lds_dwordx4 v[222:223], off
	s_add_i32 m0, s38, 0x2000
	s_add_u32 s38, s68, 0x80080
	v_lshl_add_u64 v[222:223], v[224:225], 0, s[52:53]
	s_addc_u32 s39, s69, 0
	s_add_i32 s41, s57, s2
	global_load_lds_dwordx4 v[222:223], off
	v_lshl_add_u64 v[222:223], s[38:39], 0, v[130:131]
	s_mov_b32 m0, s41
	s_nop 0
	global_load_lds_dwordx4 v[222:223], off
	v_lshl_add_u64 v[222:223], s[38:39], 0, v[134:135]
	s_add_i32 m0, s41, 0x2000
	s_nop 0
	global_load_lds_dwordx4 v[222:223], off
	v_lshl_add_u64 v[222:223], v[226:227], 0, s[52:53]
	s_mov_b32 m0, s15
	s_nop 0
	global_load_lds_dwordx4 v[222:223], off
	v_lshl_add_u64 v[222:223], v[228:229], 0, s[52:53]
	s_mov_b32 m0, s17
	s_nop 0
	global_load_lds_dwordx4 v[222:223], off
	s_waitcnt vmcnt(8)
	s_waitcnt lgkmcnt(0)
	s_barrier
	s_waitcnt lgkmcnt(0)
	v_mfma_f32_16x16x32_bf16 v[60:63], v[158:161], v[190:193], v[60:63]
	v_mfma_f32_16x16x32_bf16 v[52:55], v[166:169], v[190:193], v[52:55]
	v_mfma_f32_16x16x32_bf16 v[44:47], v[158:161], v[198:201], v[44:47]
	v_mfma_f32_16x16x32_bf16 v[36:39], v[166:169], v[198:201], v[36:39]
	v_mfma_f32_16x16x32_bf16 v[28:31], v[158:161], v[206:209], v[28:31]
	v_mfma_f32_16x16x32_bf16 v[20:23], v[166:169], v[206:209], v[20:23]
	v_mfma_f32_16x16x32_bf16 v[12:15], v[158:161], v[214:217], v[12:15]
	v_mfma_f32_16x16x32_bf16 v[4:7], v[166:169], v[214:217], v[4:7]
	v_mfma_f32_16x16x32_bf16 v[60:63], v[162:165], v[194:197], v[60:63]
	v_mfma_f32_16x16x32_bf16 v[52:55], v[170:173], v[194:197], v[52:55]
	v_mfma_f32_16x16x32_bf16 v[44:47], v[162:165], v[202:205], v[44:47]
	v_mfma_f32_16x16x32_bf16 v[36:39], v[170:173], v[202:205], v[36:39]
	v_mfma_f32_16x16x32_bf16 v[28:31], v[162:165], v[210:213], v[28:31]
	v_mfma_f32_16x16x32_bf16 v[20:23], v[170:173], v[210:213], v[20:23]
	v_mfma_f32_16x16x32_bf16 v[12:15], v[162:165], v[218:221], v[12:15]
	v_mfma_f32_16x16x32_bf16 v[4:7], v[170:173], v[218:221], v[4:7]
	v_mfma_f32_16x16x32_bf16 v[56:59], v[174:177], v[190:193], v[56:59]
	v_mfma_f32_16x16x32_bf16 v[48:51], v[182:185], v[190:193], v[48:51]
	v_mfma_f32_16x16x32_bf16 v[40:43], v[174:177], v[198:201], v[40:43]
	v_mfma_f32_16x16x32_bf16 v[32:35], v[182:185], v[198:201], v[32:35]
	v_mfma_f32_16x16x32_bf16 v[24:27], v[174:177], v[206:209], v[24:27]
	v_mfma_f32_16x16x32_bf16 v[16:19], v[182:185], v[206:209], v[16:19]
	v_mfma_f32_16x16x32_bf16 v[8:11], v[174:177], v[214:217], v[8:11]
	v_mfma_f32_16x16x32_bf16 v[0:3], v[182:185], v[214:217], v[0:3]
	v_mfma_f32_16x16x32_bf16 v[56:59], v[178:181], v[194:197], v[56:59]
	v_mfma_f32_16x16x32_bf16 v[48:51], v[186:189], v[194:197], v[48:51]
	v_mfma_f32_16x16x32_bf16 v[40:43], v[178:181], v[202:205], v[40:43]
	v_mfma_f32_16x16x32_bf16 v[32:35], v[186:189], v[202:205], v[32:35]
	v_mfma_f32_16x16x32_bf16 v[24:27], v[178:181], v[210:213], v[24:27]
	v_mfma_f32_16x16x32_bf16 v[16:19], v[186:189], v[210:213], v[16:19]
	v_mfma_f32_16x16x32_bf16 v[8:11], v[178:181], v[218:221], v[8:11]
	v_mfma_f32_16x16x32_bf16 v[0:3], v[186:189], v[218:221], v[0:3]
	s_barrier
	s_add_i32 s29, s29, 2
	s_add_u32 s19, s19, 0x100
	s_addc_u32 s28, s28, 0
	s_add_u32 s64, s64, 0x100
	s_addc_u32 s65, s65, 0
	s_cmp_gt_u32 s29, 29
	s_cbranch_scc0 .LBB0_695
	s_and_b64 vcc, exec, s[54:55]
	s_cbranch_vccz .LBB0_698
	s_barrier

; #define PG8_STAGE(bufoff, gbase, voff) do { _Pragma("unroll") for (int _i = 0; _i < 2; ++_i) \
;         __builtin_amdgcn_global_load_lds((const unsigned*)((const char*)(gbase) + (voff)[_i]), (LAS unsigned*)(lds + (bufoff) + ldsw + _i * 8192), 16, 0, 0); } while (0)
; #define PG8_LDA(dst, b, h) do { _Pragma("unroll") for (int m = 0; m < 4; ++m) _Pragma("unroll") for (int k = 0; k < 2; ++k) dst[m][k] = *(const LAS bf16x8*)(lds + PG8_SA(b, h) + aoff + m * 2048 + k * 1024); } while (0)
; #define PG8_LDB(dst, b, h) do { _Pragma("unroll") for (int n = 0; n < 2; ++n) _Pragma("unroll") for (int k = 0; k < 2; ++k) dst[n][k] = *(const LAS bf16x8*)(lds + PG8_SB(b, h) + boff + n * 2048 + k * 1024); } while (0)
; #define PG8_MMA(ai, bj, At, Bt) do { __builtin_amdgcn_s_setprio(1); _Pragma("unroll") for (int m = 0; m < 4; ++m) _Pragma("unroll") for (int n = 0; n < 2; ++n) _Pragma("unroll") for (int k = 0; k < 2; ++k) \
;         acc[ai][bj][m][n] = __builtin_amdgcn_mfma_f32_16x16x32_bf16(Bt[n][k], At[m][k], acc[ai][bj][m][n], 0, 0, 0); __builtin_amdgcn_s_setprio(0); } while (0)
; #define PG8_WAIT_V(n) asm volatile("s_waitcnt vmcnt(" #n ")" ::: "memory")
; #define PG8_WAIT_L(n) asm volatile("s_waitcnt lgkmcnt(" #n ")" ::: "memory")
; #define PG8_BAR __builtin_amdgcn_s_barrier()
; #define PG8_SCHED __builtin_amdgcn_sched_barrier(0)
; template <class Epi, class Sched>
; __device__ __forceinline__ void gemm_phase(LAS unsigned char* lds, const int K, const int lda, const int ldb, const Sched& S, const Epi& E) {
;     ...
;         for (int t = 0; t < nt; t += 2) {
;             const bool last = (t == nt - 2);
;             const char* a1 = cA + (size_t)(t + 1) * kstep;
;             const char* a2 = last ? nA : cA + (size_t)(t + 2) * kstep; const char* b2 = last ? nB : cB + (size_t)(t + 2) * kstep;
;             const char* a3 = a2 + kstep; const char* b3 = b2 + kstep;
;             PG8_LDB(B0, 0, 0); PG8_LDB(B1, 0, 1); PG8_SCHED; PG8_LDA(At, 0, 0); PG8_STAGE(PG8_SA(1, 1), a1 + hA, voffA);
;             PG8_WAIT_V(8); PG8_WAIT_L(0); PG8_BAR; PG8_MMA(0, 0, At, B0); PG8_MMA(0, 1, At, B1); PG8_BAR; PG8_SCHED;
;             PG8_LDA(At, 0, 1); PG8_STAGE(PG8_SB(0, 0), b2, voffB); PG8_STAGE(PG8_SB(0, 1), b2 + hB, voffB); PG8_STAGE(PG8_SA(0, 0), a2, voffA);
.LBB0_889:
	ds_read_b128 v[104:107], v220
	ds_read_b128 v[112:115], v247
	ds_read_b128 v[124:127], v220 offset:2048
	ds_read_b128 v[140:143], v247 offset:2048
	ds_read_b128 v[144:147], v221
	ds_read_b128 v[148:151], v248
	ds_read_b128 v[152:155], v221 offset:2048
	ds_read_b128 v[156:159], v248 offset:2048
	s_add_u32 s29, s66, 0xfff80080
	s_addc_u32 s30, s67, -1
	s_cmp_eq_u32 s28, 28
	s_cselect_b32 s71, s18, s30
	s_cselect_b32 s70, s19, s29
	s_cselect_b32 s69, s24, s27
	s_cselect_b32 s68, s25, s26
	v_lshl_add_u64 v[208:209], s[66:67], 0, v[194:195]
	s_add_i32 m0, s2, 0xc000
	ds_read_b128 v[160:163], v222
	ds_read_b128 v[164:167], v246
	ds_read_b128 v[168:171], v222 offset:2048
	ds_read_b128 v[172:175], v246 offset:2048
	ds_read_b128 v[176:179], v222 offset:4096
	ds_read_b128 v[180:183], v246 offset:4096
	ds_read_b128 v[200:203], v222 offset:6144
	ds_read_b128 v[204:207], v246 offset:6144
	global_load_lds_dwordx4 v[208:209], off
	v_lshl_add_u64 v[208:209], s[66:67], 0, v[192:193]
	s_add_i32 m0, s2, 0xe000
	s_nop 0
	global_load_lds_dwordx4 v[208:209], off
	s_waitcnt vmcnt(8)
	s_waitcnt lgkmcnt(0)
	s_barrier
	s_waitcnt lgkmcnt(0)
	v_mfma_f32_16x16x32_bf16 v[136:139], v[160:163], v[104:107], v[136:139]
	v_mfma_f32_16x16x32_bf16 v[132:135], v[160:163], v[124:127], v[132:135]
	v_mfma_f32_16x16x32_bf16 v[116:119], v[168:171], v[104:107], v[116:119]
	v_mfma_f32_16x16x32_bf16 v[108:111], v[168:171], v[124:127], v[108:111]
	v_mfma_f32_16x16x32_bf16 v[92:95], v[176:179], v[104:107], v[92:95]
	v_mfma_f32_16x16x32_bf16 v[88:91], v[176:179], v[124:127], v[88:91]
	v_mfma_f32_16x16x32_bf16 v[76:79], v[200:203], v[104:107], v[76:79]
	v_mfma_f32_16x16x32_bf16 v[72:75], v[200:203], v[124:127], v[72:75]
	v_mfma_f32_16x16x32_bf16 v[136:139], v[164:167], v[112:115], v[136:139]
	v_mfma_f32_16x16x32_bf16 v[132:135], v[164:167], v[140:143], v[132:135]
	v_mfma_f32_16x16x32_bf16 v[116:119], v[172:175], v[112:115], v[116:119]
	v_mfma_f32_16x16x32_bf16 v[108:111], v[172:175], v[140:143], v[108:111]
	v_mfma_f32_16x16x32_bf16 v[92:95], v[180:183], v[112:115], v[92:95]
	v_mfma_f32_16x16x32_bf16 v[88:91], v[180:183], v[140:143], v[88:91]
	v_mfma_f32_16x16x32_bf16 v[76:79], v[204:207], v[112:115], v[76:79]
	v_mfma_f32_16x16x32_bf16 v[72:75], v[204:207], v[140:143], v[72:75]
	v_mfma_f32_16x16x32_bf16 v[128:131], v[160:163], v[144:147], v[128:131]
	v_mfma_f32_16x16x32_bf16 v[120:123], v[160:163], v[152:155], v[120:123]
	v_mfma_f32_16x16x32_bf16 v[100:103], v[168:171], v[144:147], v[100:103]
	v_mfma_f32_16x16x32_bf16 v[96:99], v[168:171], v[152:155], v[96:99]
	v_mfma_f32_16x16x32_bf16 v[84:87], v[176:179], v[144:147], v[84:87]
	v_mfma_f32_16x16x32_bf16 v[80:83], v[176:179], v[152:155], v[80:83]
	v_mfma_f32_16x16x32_bf16 v[68:71], v[200:203], v[144:147], v[68:71]
	v_mfma_f32_16x16x32_bf16 v[64:67], v[200:203], v[152:155], v[64:67]
	v_mfma_f32_16x16x32_bf16 v[128:131], v[164:167], v[148:151], v[128:131]
	v_mfma_f32_16x16x32_bf16 v[120:123], v[164:167], v[156:159], v[120:123]
	v_mfma_f32_16x16x32_bf16 v[100:103], v[172:175], v[148:151], v[100:103]
	v_mfma_f32_16x16x32_bf16 v[96:99], v[172:175], v[156:159], v[96:99]
	v_mfma_f32_16x16x32_bf16 v[84:87], v[180:183], v[148:151], v[84:87]
	v_mfma_f32_16x16x32_bf16 v[80:83], v[180:183], v[156:159], v[80:83]
	v_mfma_f32_16x16x32_bf16 v[68:71], v[204:207], v[148:151], v[68:71]
	v_mfma_f32_16x16x32_bf16 v[64:67], v[204:207], v[156:159], v[64:67]
	s_barrier
	s_add_i32 s29, s0, s1
	v_lshl_add_u64 v[208:209], s[68:69], 0, v[186:187]
	s_mov_b32 m0, s29
	ds_read_b128 v[160:163], v222 offset:16384
	ds_read_b128 v[164:167], v246 offset:16384
	ds_read_b128 v[168:171], v222 offset:18432
	ds_read_b128 v[172:175], v246 offset:18432
	ds_read_b128 v[176:179], v222 offset:20480
	ds_read_b128 v[180:183], v246 offset:20480
	ds_read_b128 v[200:203], v222 offset:22528
	ds_read_b128 v[204:207], v246 offset:22528
	global_load_lds_dwordx4 v[208:209], off
	s_add_i32 m0, s29, 0x2000
	s_add_u32 s30, s68, 0x80000
	v_lshl_add_u64 v[210:211], s[68:69], 0, v[190:191]
	s_addc_u32 s31, s69, 0
	s_add_i32 s29, s23, s1
	global_load_lds_dwordx4 v[210:211], off
	v_lshl_add_u64 v[212:213], s[30:31], 0, v[186:187]
	s_mov_b32 m0, s29
	v_lshl_add_u64 v[214:215], s[70:71], 0, v[188:189]
	global_load_lds_dwordx4 v[212:213], off
	v_lshl_add_u64 v[212:213], s[30:31], 0, v[190:191]
	s_add_i32 m0, s29, 0x2000
	s_nop 0
	global_load_lds_dwordx4 v[212:213], off
	v_lshl_add_u64 v[212:213], s[70:71], 0, v[184:185]
	s_mov_b32 m0, s2
	s_nop 0
	global_load_lds_dwordx4 v[212:213], off
	s_mov_b32 m0, s4
	s_nop 0
	global_load_lds_dwordx4 v[214:215], off
	s_waitcnt vmcnt(8)
	s_waitcnt lgkmcnt(0)
	s_barrier
; #define PG8_STAGE(bufoff, gbase, voff) do { _Pragma("unroll") for (int _i = 0; _i < 2; ++_i) \
;         __builtin_amdgcn_global_load_lds((const unsigned*)((const char*)(gbase) + (voff)[_i]), (LAS unsigned*)(lds + (bufoff) + ldsw + _i * 8192), 16, 0, 0); } while (0)
; #define PG8_LDA(dst, b, h) do { _Pragma("unroll") for (int m = 0; m < 4; ++m) _Pragma("unroll") for (int k = 0; k < 2; ++k) dst[m][k] = *(const LAS bf16x8*)(lds + PG8_SA(b, h) + aoff + m * 2048 + k * 1024); } while (0)
; #define PG8_LDB(dst, b, h) do { _Pragma("unroll") for (int n = 0; n < 2; ++n) _Pragma("unroll") for (int k = 0; k < 2; ++k) dst[n][k] = *(const LAS bf16x8*)(lds + PG8_SB(b, h) + boff + n * 2048 + k * 1024); } while (0)
; #define PG8_MMA(ai, bj, At, Bt) do { __builtin_amdgcn_s_setprio(1); _Pragma("unroll") for (int m = 0; m < 4; ++m) _Pragma("unroll") for (int n = 0; n < 2; ++n) _Pragma("unroll") for (int k = 0; k < 2; ++k) \
;         acc[ai][bj][m][n] = __builtin_amdgcn_mfma_f32_16x16x32_bf16(Bt[n][k], At[m][k], acc[ai][bj][m][n], 0, 0, 0); __builtin_amdgcn_s_setprio(0); } while (0)
; #define PG8_WAIT_V(n) asm volatile("s_waitcnt vmcnt(" #n ")" ::: "memory")
; #define PG8_WAIT_L(n) asm volatile("s_waitcnt lgkmcnt(" #n ")" ::: "memory")
; #define PG8_BAR __builtin_amdgcn_s_barrier()
; #define PG8_SCHED __builtin_amdgcn_sched_barrier(0)
; template <class Epi, class Sched>
; __device__ __forceinline__ void gemm_phase(LAS unsigned char* lds, const int K, const int lda, const int ldb, const Sched& S, const Epi& E) {
;     ...
;             PG8_WAIT_V(8); PG8_WAIT_L(0); PG8_BAR; PG8_MMA(1, 0, At, B0); PG8_MMA(1, 1, At, B1); PG8_BAR; PG8_SCHED;
;             PG8_LDB(B0, 1, 0); PG8_LDB(B1, 1, 1); PG8_SCHED; PG8_LDA(At, 1, 0); PG8_STAGE(PG8_SA(0, 1), a2 + hA, voffA);
;             PG8_WAIT_V(8); PG8_WAIT_L(0); PG8_BAR; PG8_MMA(0, 0, At, B0); PG8_MMA(0, 1, At, B1); PG8_BAR; PG8_SCHED;
	s_waitcnt lgkmcnt(0)
	v_mfma_f32_16x16x32_bf16 v[60:63], v[160:163], v[104:107], v[60:63]
	v_mfma_f32_16x16x32_bf16 v[56:59], v[160:163], v[124:127], v[56:59]
	v_mfma_f32_16x16x32_bf16 v[44:47], v[168:171], v[104:107], v[44:47]
	v_mfma_f32_16x16x32_bf16 v[40:43], v[168:171], v[124:127], v[40:43]
	v_mfma_f32_16x16x32_bf16 v[28:31], v[176:179], v[104:107], v[28:31]
	v_mfma_f32_16x16x32_bf16 v[24:27], v[176:179], v[124:127], v[24:27]
	v_mfma_f32_16x16x32_bf16 v[12:15], v[200:203], v[104:107], v[12:15]
	v_mfma_f32_16x16x32_bf16 v[8:11], v[200:203], v[124:127], v[8:11]
	v_mfma_f32_16x16x32_bf16 v[60:63], v[164:167], v[112:115], v[60:63]
	v_mfma_f32_16x16x32_bf16 v[56:59], v[164:167], v[140:143], v[56:59]
	v_mfma_f32_16x16x32_bf16 v[44:47], v[172:175], v[112:115], v[44:47]
	v_mfma_f32_16x16x32_bf16 v[40:43], v[172:175], v[140:143], v[40:43]
	v_mfma_f32_16x16x32_bf16 v[28:31], v[180:183], v[112:115], v[28:31]
	v_mfma_f32_16x16x32_bf16 v[24:27], v[180:183], v[140:143], v[24:27]
	v_mfma_f32_16x16x32_bf16 v[12:15], v[204:207], v[112:115], v[12:15]
	v_mfma_f32_16x16x32_bf16 v[8:11], v[204:207], v[140:143], v[8:11]
	v_mfma_f32_16x16x32_bf16 v[52:55], v[160:163], v[144:147], v[52:55]
	v_mfma_f32_16x16x32_bf16 v[48:51], v[160:163], v[152:155], v[48:51]
	v_mfma_f32_16x16x32_bf16 v[36:39], v[168:171], v[144:147], v[36:39]
	v_mfma_f32_16x16x32_bf16 v[32:35], v[168:171], v[152:155], v[32:35]
	v_mfma_f32_16x16x32_bf16 v[20:23], v[176:179], v[144:147], v[20:23]
	v_mfma_f32_16x16x32_bf16 v[16:19], v[176:179], v[152:155], v[16:19]
	v_mfma_f32_16x16x32_bf16 v[4:7], v[200:203], v[144:147], v[4:7]
	v_mfma_f32_16x16x32_bf16 v[0:3], v[200:203], v[152:155], v[0:3]
	v_mfma_f32_16x16x32_bf16 v[52:55], v[164:167], v[148:151], v[52:55]
	v_mfma_f32_16x16x32_bf16 v[48:51], v[164:167], v[156:159], v[48:51]
	v_mfma_f32_16x16x32_bf16 v[36:39], v[172:175], v[148:151], v[36:39]
	v_mfma_f32_16x16x32_bf16 v[32:35], v[172:175], v[156:159], v[32:35]
	v_mfma_f32_16x16x32_bf16 v[20:23], v[180:183], v[148:151], v[20:23]
	v_mfma_f32_16x16x32_bf16 v[16:19], v[180:183], v[156:159], v[16:19]
	v_mfma_f32_16x16x32_bf16 v[4:7], v[204:207], v[148:151], v[4:7]
	v_mfma_f32_16x16x32_bf16 v[0:3], v[204:207], v[156:159], v[0:3]
	s_barrier
	s_add_i32 s29, 0, 0x18000
	s_add_i32 s34, 0, 0x1c000
	v_add_u32_e32 v140, s29, v217
	v_add_u32_e32 v250, s29, v249
	v_add_u32_e32 v156, 0x19000, v217
	v_add_u32_e32 v251, 0x19000, v249
	ds_read_b128 v[104:107], v140
	ds_read_b128 v[112:115], v250
	ds_read_b128 v[124:127], v140 offset:2048
	ds_read_b128 v[140:143], v250 offset:2048
	ds_read_b128 v[144:147], v156
	ds_read_b128 v[148:151], v251
	ds_read_b128 v[152:155], v156 offset:2048
	ds_read_b128 v[156:159], v251 offset:2048
	s_add_u32 s30, s70, 0x80000
	s_addc_u32 s31, s71, 0
	s_mov_b32 m0, s5
	v_lshl_add_u64 v[226:227], s[30:31], 0, v[184:185]
	ds_read_b128 v[160:163], v222 offset:32768
	ds_read_b128 v[164:167], v246 offset:32768
	ds_read_b128 v[168:171], v222 offset:34816
	ds_read_b128 v[172:175], v246 offset:34816
	ds_read_b128 v[176:179], v222 offset:36864
	ds_read_b128 v[180:183], v246 offset:36864
	ds_read_b128 v[200:203], v222 offset:38912
	ds_read_b128 v[204:207], v246 offset:38912
	global_load_lds_dwordx4 v[226:227], off
	v_lshl_add_u64 v[226:227], s[30:31], 0, v[188:189]
	s_mov_b32 m0, s6
	s_nop 0
	global_load_lds_dwordx4 v[226:227], off
	s_waitcnt vmcnt(8)
	s_waitcnt lgkmcnt(0)
	s_barrier
	s_waitcnt lgkmcnt(0)
	v_mfma_f32_16x16x32_bf16 v[136:139], v[160:163], v[104:107], v[136:139]
	v_mfma_f32_16x16x32_bf16 v[132:135], v[160:163], v[124:127], v[132:135]
	v_mfma_f32_16x16x32_bf16 v[116:119], v[168:171], v[104:107], v[116:119]
	v_mfma_f32_16x16x32_bf16 v[108:111], v[168:171], v[124:127], v[108:111]
	v_mfma_f32_16x16x32_bf16 v[92:95], v[176:179], v[104:107], v[92:95]
	v_mfma_f32_16x16x32_bf16 v[88:91], v[176:179], v[124:127], v[88:91]
	v_mfma_f32_16x16x32_bf16 v[76:79], v[200:203], v[104:107], v[76:79]
	v_mfma_f32_16x16x32_bf16 v[72:75], v[200:203], v[124:127], v[72:75]
	v_mfma_f32_16x16x32_bf16 v[136:139], v[164:167], v[112:115], v[136:139]
	v_mfma_f32_16x16x32_bf16 v[132:135], v[164:167], v[140:143], v[132:135]
	v_mfma_f32_16x16x32_bf16 v[116:119], v[172:175], v[112:115], v[116:119]
	v_mfma_f32_16x16x32_bf16 v[108:111], v[172:175], v[140:143], v[108:111]
	v_mfma_f32_16x16x32_bf16 v[92:95], v[180:183], v[112:115], v[92:95]
	v_mfma_f32_16x16x32_bf16 v[88:91], v[180:183], v[140:143], v[88:91]
	v_mfma_f32_16x16x32_bf16 v[76:79], v[204:207], v[112:115], v[76:79]
	v_mfma_f32_16x16x32_bf16 v[72:75], v[204:207], v[140:143], v[72:75]
	v_mfma_f32_16x16x32_bf16 v[128:131], v[160:163], v[144:147], v[128:131]
	v_mfma_f32_16x16x32_bf16 v[120:123], v[160:163], v[152:155], v[120:123]
	v_mfma_f32_16x16x32_bf16 v[100:103], v[168:171], v[144:147], v[100:103]
	v_mfma_f32_16x16x32_bf16 v[96:99], v[168:171], v[152:155], v[96:99]
	v_mfma_f32_16x16x32_bf16 v[84:87], v[176:179], v[144:147], v[84:87]
	v_mfma_f32_16x16x32_bf16 v[80:83], v[176:179], v[152:155], v[80:83]
	v_mfma_f32_16x16x32_bf16 v[68:71], v[200:203], v[144:147], v[68:71]
	v_mfma_f32_16x16x32_bf16 v[64:67], v[200:203], v[152:155], v[64:67]
	v_mfma_f32_16x16x32_bf16 v[128:131], v[164:167], v[148:151], v[128:131]
	v_mfma_f32_16x16x32_bf16 v[120:123], v[164:167], v[156:159], v[120:123]
	v_mfma_f32_16x16x32_bf16 v[100:103], v[172:175], v[148:151], v[100:103]
	v_mfma_f32_16x16x32_bf16 v[96:99], v[172:175], v[156:159], v[96:99]
	v_mfma_f32_16x16x32_bf16 v[84:87], v[180:183], v[148:151], v[84:87]
	v_mfma_f32_16x16x32_bf16 v[80:83], v[180:183], v[156:159], v[80:83]
	v_mfma_f32_16x16x32_bf16 v[68:71], v[204:207], v[148:151], v[68:71]
	v_mfma_f32_16x16x32_bf16 v[64:67], v[204:207], v[156:159], v[64:67]
	s_barrier
; #define PG8_STAGE(bufoff, gbase, voff) do { _Pragma("unroll") for (int _i = 0; _i < 2; ++_i) \
;         __builtin_amdgcn_global_load_lds((const unsigned*)((const char*)(gbase) + (voff)[_i]), (LAS unsigned*)(lds + (bufoff) + ldsw + _i * 8192), 16, 0, 0); } while (0)
; #define PG8_LDA(dst, b, h) do { _Pragma("unroll") for (int m = 0; m < 4; ++m) _Pragma("unroll") for (int k = 0; k < 2; ++k) dst[m][k] = *(const LAS bf16x8*)(lds + PG8_SA(b, h) + aoff + m * 2048 + k * 1024); } while (0)
; #define PG8_MMA(ai, bj, At, Bt) do { __builtin_amdgcn_s_setprio(1); _Pragma("unroll") for (int m = 0; m < 4; ++m) _Pragma("unroll") for (int n = 0; n < 2; ++n) _Pragma("unroll") for (int k = 0; k < 2; ++k) \
;         acc[ai][bj][m][n] = __builtin_amdgcn_mfma_f32_16x16x32_bf16(Bt[n][k], At[m][k], acc[ai][bj][m][n], 0, 0, 0); __builtin_amdgcn_s_setprio(0); } while (0)
; #define PG8_WAIT_V(n) asm volatile("s_waitcnt vmcnt(" #n ")" ::: "memory")
; #define PG8_WAIT_L(n) asm volatile("s_waitcnt lgkmcnt(" #n ")" ::: "memory")
; #define PG8_BAR __builtin_amdgcn_s_barrier()
; #define PG8_SCHED __builtin_amdgcn_sched_barrier(0)
; template <class Epi, class Sched>
; __device__ __forceinline__ void gemm_phase(LAS unsigned char* lds, const int K, const int lda, const int ldb, const Sched& S, const Epi& E) {
;     ...
;             PG8_LDA(At, 1, 1); PG8_STAGE(PG8_SB(1, 0), b3, voffB); PG8_STAGE(PG8_SB(1, 1), b3 + hB, voffB); PG8_STAGE(PG8_SA(1, 0), a3, voffA);
;             PG8_WAIT_V(8); PG8_WAIT_L(0); PG8_BAR; PG8_MMA(1, 0, At, B0); PG8_MMA(1, 1, At, B1); PG8_BAR; PG8_SCHED;
;         }
;         if (wr == 0) PG8_BAR;
	s_add_i32 s29, s29, s1
	v_lshl_add_u64 v[208:209], v[208:209], 0, s[52:53]
	s_mov_b32 m0, s29
	ds_read_b128 v[160:163], v222 offset:49152
	ds_read_b128 v[164:167], v246 offset:49152
	ds_read_b128 v[168:171], v222 offset:51200
	ds_read_b128 v[172:175], v246 offset:51200
	ds_read_b128 v[176:179], v222 offset:53248
	ds_read_b128 v[180:183], v246 offset:53248
	ds_read_b128 v[200:203], v222 offset:55296
	ds_read_b128 v[204:207], v246 offset:55296
	global_load_lds_dwordx4 v[208:209], off
	s_add_i32 m0, s29, 0x2000
	s_add_u32 s30, s68, 0x80080
	v_lshl_add_u64 v[208:209], v[210:211], 0, s[52:53]
	s_addc_u32 s31, s69, 0
	s_add_i32 s29, s34, s1
	global_load_lds_dwordx4 v[208:209], off
	v_lshl_add_u64 v[208:209], s[30:31], 0, v[186:187]
	s_mov_b32 m0, s29
	s_nop 0
	global_load_lds_dwordx4 v[208:209], off
	v_lshl_add_u64 v[208:209], s[30:31], 0, v[190:191]
	s_add_i32 m0, s29, 0x2000
	s_nop 0
	global_load_lds_dwordx4 v[208:209], off
	v_lshl_add_u64 v[208:209], v[212:213], 0, s[52:53]
	s_mov_b32 m0, s14
	s_nop 0
	global_load_lds_dwordx4 v[208:209], off
	v_lshl_add_u64 v[208:209], v[214:215], 0, s[52:53]
	s_mov_b32 m0, s15
	s_nop 0
	global_load_lds_dwordx4 v[208:209], off
	s_waitcnt vmcnt(8)
	s_waitcnt lgkmcnt(0)
	s_barrier
	s_waitcnt lgkmcnt(0)
	v_mfma_f32_16x16x32_bf16 v[60:63], v[160:163], v[104:107], v[60:63]
	v_mfma_f32_16x16x32_bf16 v[56:59], v[160:163], v[124:127], v[56:59]
	v_mfma_f32_16x16x32_bf16 v[44:47], v[168:171], v[104:107], v[44:47]
	v_mfma_f32_16x16x32_bf16 v[40:43], v[168:171], v[124:127], v[40:43]
	v_mfma_f32_16x16x32_bf16 v[28:31], v[176:179], v[104:107], v[28:31]
	v_mfma_f32_16x16x32_bf16 v[24:27], v[176:179], v[124:127], v[24:27]
	v_mfma_f32_16x16x32_bf16 v[12:15], v[200:203], v[104:107], v[12:15]
	v_mfma_f32_16x16x32_bf16 v[8:11], v[200:203], v[124:127], v[8:11]
	v_mfma_f32_16x16x32_bf16 v[60:63], v[164:167], v[112:115], v[60:63]
	v_mfma_f32_16x16x32_bf16 v[56:59], v[164:167], v[140:143], v[56:59]
	v_mfma_f32_16x16x32_bf16 v[44:47], v[172:175], v[112:115], v[44:47]
	v_mfma_f32_16x16x32_bf16 v[40:43], v[172:175], v[140:143], v[40:43]
	v_mfma_f32_16x16x32_bf16 v[28:31], v[180:183], v[112:115], v[28:31]
	v_mfma_f32_16x16x32_bf16 v[24:27], v[180:183], v[140:143], v[24:27]
	v_mfma_f32_16x16x32_bf16 v[12:15], v[204:207], v[112:115], v[12:15]
	v_mfma_f32_16x16x32_bf16 v[8:11], v[204:207], v[140:143], v[8:11]
	v_mfma_f32_16x16x32_bf16 v[52:55], v[160:163], v[144:147], v[52:55]
	v_mfma_f32_16x16x32_bf16 v[48:51], v[160:163], v[152:155], v[48:51]
	v_mfma_f32_16x16x32_bf16 v[36:39], v[168:171], v[144:147], v[36:39]
	v_mfma_f32_16x16x32_bf16 v[32:35], v[168:171], v[152:155], v[32:35]
	v_mfma_f32_16x16x32_bf16 v[20:23], v[176:179], v[144:147], v[20:23]
	v_mfma_f32_16x16x32_bf16 v[16:19], v[176:179], v[152:155], v[16:19]
	v_mfma_f32_16x16x32_bf16 v[4:7], v[200:203], v[144:147], v[4:7]
	v_mfma_f32_16x16x32_bf16 v[0:3], v[200:203], v[152:155], v[0:3]
	v_mfma_f32_16x16x32_bf16 v[52:55], v[164:167], v[148:151], v[52:55]
	v_mfma_f32_16x16x32_bf16 v[48:51], v[164:167], v[156:159], v[48:51]
	v_mfma_f32_16x16x32_bf16 v[36:39], v[172:175], v[148:151], v[36:39]
	v_mfma_f32_16x16x32_bf16 v[32:35], v[172:175], v[156:159], v[32:35]
	v_mfma_f32_16x16x32_bf16 v[20:23], v[180:183], v[148:151], v[20:23]
	v_mfma_f32_16x16x32_bf16 v[16:19], v[180:183], v[156:159], v[16:19]
	v_mfma_f32_16x16x32_bf16 v[4:7], v[204:207], v[148:151], v[4:7]
	v_mfma_f32_16x16x32_bf16 v[0:3], v[204:207], v[156:159], v[0:3]
	s_barrier
	s_add_i32 s28, s28, 2
	s_add_u32 s26, s26, 0x100
	s_addc_u32 s27, s27, 0
	s_add_u32 s66, s66, 0x100
	s_addc_u32 s67, s67, 0
	s_cmp_gt_u32 s28, 29
	s_cbranch_scc0 .LBB0_889
	s_and_b64 vcc, exec, s[54:55]
	s_cbranch_vccz .LBB0_892
	s_barrier

; #define PG8_STAGE(bufoff, gbase, voff) do { _Pragma("unroll") for (int _i = 0; _i < 2; ++_i) \
;         __builtin_amdgcn_global_load_lds((const unsigned*)((const char*)(gbase) + (voff)[_i]), (LAS unsigned*)(lds + (bufoff) + ldsw + _i * 8192), 16, 0, 0); } while (0)
; #define PG8_LDA(dst, b, h) do { _Pragma("unroll") for (int m = 0; m < 4; ++m) _Pragma("unroll") for (int k = 0; k < 2; ++k) dst[m][k] = *(const LAS bf16x8*)(lds + PG8_SA(b, h) + aoff + m * 2048 + k * 1024); } while (0)
; #define PG8_LDB(dst, b, h) do { _Pragma("unroll") for (int n = 0; n < 2; ++n) _Pragma("unroll") for (int k = 0; k < 2; ++k) dst[n][k] = *(const LAS bf16x8*)(lds + PG8_SB(b, h) + boff + n * 2048 + k * 1024); } while (0)
; #define PG8_MMA(ai, bj, At, Bt) do { __builtin_amdgcn_s_setprio(1); _Pragma("unroll") for (int m = 0; m < 4; ++m) _Pragma("unroll") for (int n = 0; n < 2; ++n) _Pragma("unroll") for (int k = 0; k < 2; ++k) \
;         acc[ai][bj][m][n] = __builtin_amdgcn_mfma_f32_16x16x32_bf16(Bt[n][k], At[m][k], acc[ai][bj][m][n], 0, 0, 0); __builtin_amdgcn_s_setprio(0); } while (0)
; #define PG8_WAIT_V(n) asm volatile("s_waitcnt vmcnt(" #n ")" ::: "memory")
; #define PG8_WAIT_L(n) asm volatile("s_waitcnt lgkmcnt(" #n ")" ::: "memory")
; #define PG8_BAR __builtin_amdgcn_s_barrier()
; #define PG8_SCHED __builtin_amdgcn_sched_barrier(0)
; template <class Epi, class Sched>
; __device__ __forceinline__ void gemm_phase(LAS unsigned char* lds, const int K, const int lda, const int ldb, const Sched& S, const Epi& E) {
;     ...
;         for (int t = 0; t < nt; t += 2) {
;             const bool last = (t == nt - 2);
;             const char* a1 = cA + (size_t)(t + 1) * kstep;
;             const char* a2 = last ? nA : cA + (size_t)(t + 2) * kstep; const char* b2 = last ? nB : cB + (size_t)(t + 2) * kstep;
;             const char* a3 = a2 + kstep; const char* b3 = b2 + kstep;
;             PG8_LDB(B0, 0, 0); PG8_LDB(B1, 0, 1); PG8_SCHED; PG8_LDA(At, 0, 0); PG8_STAGE(PG8_SA(1, 1), a1 + hA, voffA);
;             PG8_WAIT_V(8); PG8_WAIT_L(0); PG8_BAR; PG8_MMA(0, 0, At, B0); PG8_MMA(0, 1, At, B1); PG8_BAR; PG8_SCHED;
;             PG8_LDA(At, 0, 1); PG8_STAGE(PG8_SB(0, 0), b2, voffB); PG8_STAGE(PG8_SB(0, 1), b2 + hB, voffB); PG8_STAGE(PG8_SA(0, 0), a2, voffA);
.LBB0_963:
	ds_read_b128 v[174:177], v188
	ds_read_b128 v[178:181], v147
	ds_read_b128 v[190:193], v188 offset:2048
	ds_read_b128 v[194:197], v147 offset:2048
	ds_read_b128 v[198:201], v189
	ds_read_b128 v[202:205], v149
	ds_read_b128 v[206:209], v189 offset:2048
	ds_read_b128 v[210:213], v149 offset:2048
	s_add_u32 s61, s66, 0xfff80080
	s_addc_u32 s68, s67, -1
	s_cmp_eq_u32 s59, 28
	s_cselect_b32 s71, s11, s68
	s_cselect_b32 s70, s18, s61
	s_cselect_b32 s69, s39, s57
	s_cselect_b32 s68, s41, s55
	v_lshl_add_u64 v[182:183], s[66:67], 0, v[140:141]
	s_add_i32 m0, s1, 0xc000
	ds_read_b128 v[214:217], v163
	ds_read_b128 v[218:221], v145
	ds_read_b128 v[222:225], v163 offset:2048
	ds_read_b128 v[226:229], v145 offset:2048
	ds_read_b128 v[230:233], v163 offset:4096
	ds_read_b128 v[236:239], v145 offset:4096
	ds_read_b128 v[240:243], v163 offset:6144
	ds_read_b128 v[244:247], v145 offset:6144
	global_load_lds_dwordx4 v[182:183], off
	v_lshl_add_u64 v[182:183], s[66:67], 0, v[138:139]
	s_add_i32 m0, s1, 0xe000
	s_nop 0
	global_load_lds_dwordx4 v[182:183], off
	s_waitcnt vmcnt(8)
	s_waitcnt lgkmcnt(0)
	s_barrier
	s_waitcnt lgkmcnt(0)
	v_mfma_f32_16x16x32_bf16 v[124:127], v[214:217], v[174:177], v[124:127]
	v_mfma_f32_16x16x32_bf16 v[120:123], v[214:217], v[190:193], v[120:123]
	v_mfma_f32_16x16x32_bf16 v[108:111], v[222:225], v[174:177], v[108:111]
	v_mfma_f32_16x16x32_bf16 v[104:107], v[222:225], v[190:193], v[104:107]
	v_mfma_f32_16x16x32_bf16 v[92:95], v[230:233], v[174:177], v[92:95]
	v_mfma_f32_16x16x32_bf16 v[88:91], v[230:233], v[190:193], v[88:91]
	v_mfma_f32_16x16x32_bf16 v[76:79], v[240:243], v[174:177], v[76:79]
	v_mfma_f32_16x16x32_bf16 v[72:75], v[240:243], v[190:193], v[72:75]
	v_mfma_f32_16x16x32_bf16 v[124:127], v[218:221], v[178:181], v[124:127]
	v_mfma_f32_16x16x32_bf16 v[120:123], v[218:221], v[194:197], v[120:123]
	v_mfma_f32_16x16x32_bf16 v[108:111], v[226:229], v[178:181], v[108:111]
	v_mfma_f32_16x16x32_bf16 v[104:107], v[226:229], v[194:197], v[104:107]
	v_mfma_f32_16x16x32_bf16 v[92:95], v[236:239], v[178:181], v[92:95]
	v_mfma_f32_16x16x32_bf16 v[88:91], v[236:239], v[194:197], v[88:91]
	v_mfma_f32_16x16x32_bf16 v[76:79], v[244:247], v[178:181], v[76:79]
	v_mfma_f32_16x16x32_bf16 v[72:75], v[244:247], v[194:197], v[72:75]
	v_mfma_f32_16x16x32_bf16 v[116:119], v[214:217], v[198:201], v[116:119]
	v_mfma_f32_16x16x32_bf16 v[112:115], v[214:217], v[206:209], v[112:115]
	v_mfma_f32_16x16x32_bf16 v[100:103], v[222:225], v[198:201], v[100:103]
	v_mfma_f32_16x16x32_bf16 v[96:99], v[222:225], v[206:209], v[96:99]
	v_mfma_f32_16x16x32_bf16 v[84:87], v[230:233], v[198:201], v[84:87]
	v_mfma_f32_16x16x32_bf16 v[80:83], v[230:233], v[206:209], v[80:83]
	v_mfma_f32_16x16x32_bf16 v[68:71], v[240:243], v[198:201], v[68:71]
	v_mfma_f32_16x16x32_bf16 v[64:67], v[240:243], v[206:209], v[64:67]
	v_mfma_f32_16x16x32_bf16 v[116:119], v[218:221], v[202:205], v[116:119]
	v_mfma_f32_16x16x32_bf16 v[112:115], v[218:221], v[210:213], v[112:115]
	v_mfma_f32_16x16x32_bf16 v[100:103], v[226:229], v[202:205], v[100:103]
	v_mfma_f32_16x16x32_bf16 v[96:99], v[226:229], v[210:213], v[96:99]
	v_mfma_f32_16x16x32_bf16 v[84:87], v[236:239], v[202:205], v[84:87]
	v_mfma_f32_16x16x32_bf16 v[80:83], v[236:239], v[210:213], v[80:83]
	v_mfma_f32_16x16x32_bf16 v[68:71], v[244:247], v[202:205], v[68:71]
	v_mfma_f32_16x16x32_bf16 v[64:67], v[244:247], v[210:213], v[64:67]
	s_barrier
	s_add_i32 s61, s30, s2
	v_lshl_add_u64 v[182:183], s[68:69], 0, v[132:133]
	s_mov_b32 m0, s61
	ds_read_b128 v[214:217], v163 offset:16384
	ds_read_b128 v[218:221], v145 offset:16384
	ds_read_b128 v[222:225], v163 offset:18432
	ds_read_b128 v[226:229], v145 offset:18432
	ds_read_b128 v[230:233], v163 offset:20480
	ds_read_b128 v[236:239], v145 offset:20480
	ds_read_b128 v[240:243], v163 offset:22528
	ds_read_b128 v[244:247], v145 offset:22528
	global_load_lds_dwordx4 v[182:183], off
	s_add_i32 m0, s61, 0x2000
	s_add_u32 s72, s68, 0x80000
	v_lshl_add_u64 v[234:235], s[68:69], 0, v[128:129]
	s_addc_u32 s73, s69, 0
	s_add_i32 s61, s31, s2
	global_load_lds_dwordx4 v[234:235], off
	v_lshl_add_u64 v[248:249], s[72:73], 0, v[132:133]
	s_mov_b32 m0, s61
	v_lshl_add_u64 v[250:251], s[70:71], 0, v[130:131]
	global_load_lds_dwordx4 v[248:249], off
	v_lshl_add_u64 v[248:249], s[72:73], 0, v[128:129]
	s_add_i32 m0, s61, 0x2000
	s_nop 0
	global_load_lds_dwordx4 v[248:249], off
	v_lshl_add_u64 v[248:249], s[70:71], 0, v[134:135]
	s_mov_b32 m0, s1
	s_nop 0
	global_load_lds_dwordx4 v[248:249], off
	s_mov_b32 m0, s6
	s_nop 0
	global_load_lds_dwordx4 v[250:251], off
	s_waitcnt vmcnt(8)
	s_waitcnt lgkmcnt(0)
	s_barrier
; #define PG8_STAGE(bufoff, gbase, voff) do { _Pragma("unroll") for (int _i = 0; _i < 2; ++_i) \
;         __builtin_amdgcn_global_load_lds((const unsigned*)((const char*)(gbase) + (voff)[_i]), (LAS unsigned*)(lds + (bufoff) + ldsw + _i * 8192), 16, 0, 0); } while (0)
; #define PG8_LDA(dst, b, h) do { _Pragma("unroll") for (int m = 0; m < 4; ++m) _Pragma("unroll") for (int k = 0; k < 2; ++k) dst[m][k] = *(const LAS bf16x8*)(lds + PG8_SA(b, h) + aoff + m * 2048 + k * 1024); } while (0)
; #define PG8_LDB(dst, b, h) do { _Pragma("unroll") for (int n = 0; n < 2; ++n) _Pragma("unroll") for (int k = 0; k < 2; ++k) dst[n][k] = *(const LAS bf16x8*)(lds + PG8_SB(b, h) + boff + n * 2048 + k * 1024); } while (0)
; #define PG8_MMA(ai, bj, At, Bt) do { __builtin_amdgcn_s_setprio(1); _Pragma("unroll") for (int m = 0; m < 4; ++m) _Pragma("unroll") for (int n = 0; n < 2; ++n) _Pragma("unroll") for (int k = 0; k < 2; ++k) \
;         acc[ai][bj][m][n] = __builtin_amdgcn_mfma_f32_16x16x32_bf16(Bt[n][k], At[m][k], acc[ai][bj][m][n], 0, 0, 0); __builtin_amdgcn_s_setprio(0); } while (0)
; #define PG8_WAIT_V(n) asm volatile("s_waitcnt vmcnt(" #n ")" ::: "memory")
; #define PG8_WAIT_L(n) asm volatile("s_waitcnt lgkmcnt(" #n ")" ::: "memory")
; #define PG8_BAR __builtin_amdgcn_s_barrier()
; #define PG8_SCHED __builtin_amdgcn_sched_barrier(0)
; template <class Epi, class Sched>
; __device__ __forceinline__ void gemm_phase(LAS unsigned char* lds, const int K, const int lda, const int ldb, const Sched& S, const Epi& E) {
;     ...
;             PG8_WAIT_V(8); PG8_WAIT_L(0); PG8_BAR; PG8_MMA(1, 0, At, B0); PG8_MMA(1, 1, At, B1); PG8_BAR; PG8_SCHED;
;             PG8_LDB(B0, 1, 0); PG8_LDB(B1, 1, 1); PG8_SCHED; PG8_LDA(At, 1, 0); PG8_STAGE(PG8_SA(0, 1), a2 + hA, voffA);
;             PG8_WAIT_V(8); PG8_WAIT_L(0); PG8_BAR; PG8_MMA(0, 0, At, B0); PG8_MMA(0, 1, At, B1); PG8_BAR; PG8_SCHED;
	s_waitcnt lgkmcnt(0)
	v_mfma_f32_16x16x32_bf16 v[60:63], v[214:217], v[174:177], v[60:63]
	v_mfma_f32_16x16x32_bf16 v[56:59], v[214:217], v[190:193], v[56:59]
	v_mfma_f32_16x16x32_bf16 v[44:47], v[222:225], v[174:177], v[44:47]
	v_mfma_f32_16x16x32_bf16 v[40:43], v[222:225], v[190:193], v[40:43]
	v_mfma_f32_16x16x32_bf16 v[28:31], v[230:233], v[174:177], v[28:31]
	v_mfma_f32_16x16x32_bf16 v[24:27], v[230:233], v[190:193], v[24:27]
	v_mfma_f32_16x16x32_bf16 v[12:15], v[240:243], v[174:177], v[12:15]
	v_mfma_f32_16x16x32_bf16 v[8:11], v[240:243], v[190:193], v[8:11]
	v_mfma_f32_16x16x32_bf16 v[60:63], v[218:221], v[178:181], v[60:63]
	v_mfma_f32_16x16x32_bf16 v[56:59], v[218:221], v[194:197], v[56:59]
	v_mfma_f32_16x16x32_bf16 v[44:47], v[226:229], v[178:181], v[44:47]
	v_mfma_f32_16x16x32_bf16 v[40:43], v[226:229], v[194:197], v[40:43]
	v_mfma_f32_16x16x32_bf16 v[28:31], v[236:239], v[178:181], v[28:31]
	v_mfma_f32_16x16x32_bf16 v[24:27], v[236:239], v[194:197], v[24:27]
	v_mfma_f32_16x16x32_bf16 v[12:15], v[244:247], v[178:181], v[12:15]
	v_mfma_f32_16x16x32_bf16 v[8:11], v[244:247], v[194:197], v[8:11]
	v_mfma_f32_16x16x32_bf16 v[52:55], v[214:217], v[198:201], v[52:55]
	v_mfma_f32_16x16x32_bf16 v[48:51], v[214:217], v[206:209], v[48:51]
	v_mfma_f32_16x16x32_bf16 v[36:39], v[222:225], v[198:201], v[36:39]
	v_mfma_f32_16x16x32_bf16 v[32:35], v[222:225], v[206:209], v[32:35]
	v_mfma_f32_16x16x32_bf16 v[20:23], v[230:233], v[198:201], v[20:23]
	v_mfma_f32_16x16x32_bf16 v[16:19], v[230:233], v[206:209], v[16:19]
	v_mfma_f32_16x16x32_bf16 v[4:7], v[240:243], v[198:201], v[4:7]
	v_mfma_f32_16x16x32_bf16 v[0:3], v[240:243], v[206:209], v[0:3]
	v_mfma_f32_16x16x32_bf16 v[52:55], v[218:221], v[202:205], v[52:55]
	v_mfma_f32_16x16x32_bf16 v[48:51], v[218:221], v[210:213], v[48:51]
	v_mfma_f32_16x16x32_bf16 v[36:39], v[226:229], v[202:205], v[36:39]
	v_mfma_f32_16x16x32_bf16 v[32:35], v[226:229], v[210:213], v[32:35]
	v_mfma_f32_16x16x32_bf16 v[20:23], v[236:239], v[202:205], v[20:23]
	v_mfma_f32_16x16x32_bf16 v[16:19], v[236:239], v[210:213], v[16:19]
	v_mfma_f32_16x16x32_bf16 v[4:7], v[244:247], v[202:205], v[4:7]
	v_mfma_f32_16x16x32_bf16 v[0:3], v[244:247], v[210:213], v[0:3]
	s_barrier
	s_add_i32 s61, 0, 0x18000
	v_add_u32_e32 v143, s61, v161
	v_add_u32_e32 v158, s61, v151
	s_add_i32 s72, 0, 0x1c000
	ds_read_b128 v[174:177], v143
	ds_read_b128 v[178:181], v158
	ds_read_b128 v[190:193], v143 offset:2048
	ds_read_b128 v[194:197], v158 offset:2048
	v_add_u32_e32 v143, 0x19000, v161
	v_add_u32_e32 v158, 0x19000, v151
	ds_read_b128 v[198:201], v143
	ds_read_b128 v[202:205], v158
	ds_read_b128 v[206:209], v143 offset:2048
	ds_read_b128 v[210:213], v158 offset:2048
	s_add_u32 s70, s70, 0x80000
	s_addc_u32 s71, s71, 0
	s_mov_b32 m0, s7
	v_lshl_add_u64 v[252:253], s[70:71], 0, v[134:135]
	ds_read_b128 v[214:217], v163 offset:32768
	ds_read_b128 v[218:221], v145 offset:32768
	ds_read_b128 v[222:225], v163 offset:34816
	ds_read_b128 v[226:229], v145 offset:34816
	ds_read_b128 v[230:233], v163 offset:36864
	ds_read_b128 v[236:239], v145 offset:36864
	ds_read_b128 v[240:243], v163 offset:38912
	ds_read_b128 v[244:247], v145 offset:38912
	global_load_lds_dwordx4 v[252:253], off
	v_lshl_add_u64 v[252:253], s[70:71], 0, v[130:131]
	s_mov_b32 m0, s14
	s_nop 0
	global_load_lds_dwordx4 v[252:253], off
	s_waitcnt vmcnt(8)
	s_waitcnt lgkmcnt(0)
	s_barrier
	s_waitcnt lgkmcnt(0)
	v_mfma_f32_16x16x32_bf16 v[124:127], v[214:217], v[174:177], v[124:127]
	v_mfma_f32_16x16x32_bf16 v[120:123], v[214:217], v[190:193], v[120:123]
	v_mfma_f32_16x16x32_bf16 v[108:111], v[222:225], v[174:177], v[108:111]
	v_mfma_f32_16x16x32_bf16 v[104:107], v[222:225], v[190:193], v[104:107]
	v_mfma_f32_16x16x32_bf16 v[92:95], v[230:233], v[174:177], v[92:95]
	v_mfma_f32_16x16x32_bf16 v[88:91], v[230:233], v[190:193], v[88:91]
	v_mfma_f32_16x16x32_bf16 v[76:79], v[240:243], v[174:177], v[76:79]
	v_mfma_f32_16x16x32_bf16 v[72:75], v[240:243], v[190:193], v[72:75]
	v_mfma_f32_16x16x32_bf16 v[124:127], v[218:221], v[178:181], v[124:127]
	v_mfma_f32_16x16x32_bf16 v[120:123], v[218:221], v[194:197], v[120:123]
	v_mfma_f32_16x16x32_bf16 v[108:111], v[226:229], v[178:181], v[108:111]
	v_mfma_f32_16x16x32_bf16 v[104:107], v[226:229], v[194:197], v[104:107]
	v_mfma_f32_16x16x32_bf16 v[92:95], v[236:239], v[178:181], v[92:95]
	v_mfma_f32_16x16x32_bf16 v[88:91], v[236:239], v[194:197], v[88:91]
	v_mfma_f32_16x16x32_bf16 v[76:79], v[244:247], v[178:181], v[76:79]
	v_mfma_f32_16x16x32_bf16 v[72:75], v[244:247], v[194:197], v[72:75]
	v_mfma_f32_16x16x32_bf16 v[116:119], v[214:217], v[198:201], v[116:119]
	v_mfma_f32_16x16x32_bf16 v[112:115], v[214:217], v[206:209], v[112:115]
	v_mfma_f32_16x16x32_bf16 v[100:103], v[222:225], v[198:201], v[100:103]
	v_mfma_f32_16x16x32_bf16 v[96:99], v[222:225], v[206:209], v[96:99]
	v_mfma_f32_16x16x32_bf16 v[84:87], v[230:233], v[198:201], v[84:87]
	v_mfma_f32_16x16x32_bf16 v[80:83], v[230:233], v[206:209], v[80:83]
	v_mfma_f32_16x16x32_bf16 v[68:71], v[240:243], v[198:201], v[68:71]
	v_mfma_f32_16x16x32_bf16 v[64:67], v[240:243], v[206:209], v[64:67]
	v_mfma_f32_16x16x32_bf16 v[116:119], v[218:221], v[202:205], v[116:119]
	v_mfma_f32_16x16x32_bf16 v[112:115], v[218:221], v[210:213], v[112:115]
	v_mfma_f32_16x16x32_bf16 v[100:103], v[226:229], v[202:205], v[100:103]
	v_mfma_f32_16x16x32_bf16 v[96:99], v[226:229], v[210:213], v[96:99]
	v_mfma_f32_16x16x32_bf16 v[84:87], v[236:239], v[202:205], v[84:87]
	v_mfma_f32_16x16x32_bf16 v[80:83], v[236:239], v[210:213], v[80:83]
	v_mfma_f32_16x16x32_bf16 v[68:71], v[244:247], v[202:205], v[68:71]
	v_mfma_f32_16x16x32_bf16 v[64:67], v[244:247], v[210:213], v[64:67]
	s_barrier
; #define PG8_STAGE(bufoff, gbase, voff) do { _Pragma("unroll") for (int _i = 0; _i < 2; ++_i) \
;         __builtin_amdgcn_global_load_lds((const unsigned*)((const char*)(gbase) + (voff)[_i]), (LAS unsigned*)(lds + (bufoff) + ldsw + _i * 8192), 16, 0, 0); } while (0)
; #define PG8_LDA(dst, b, h) do { _Pragma("unroll") for (int m = 0; m < 4; ++m) _Pragma("unroll") for (int k = 0; k < 2; ++k) dst[m][k] = *(const LAS bf16x8*)(lds + PG8_SA(b, h) + aoff + m * 2048 + k * 1024); } while (0)
; #define PG8_MMA(ai, bj, At, Bt) do { __builtin_amdgcn_s_setprio(1); _Pragma("unroll") for (int m = 0; m < 4; ++m) _Pragma("unroll") for (int n = 0; n < 2; ++n) _Pragma("unroll") for (int k = 0; k < 2; ++k) \
;         acc[ai][bj][m][n] = __builtin_amdgcn_mfma_f32_16x16x32_bf16(Bt[n][k], At[m][k], acc[ai][bj][m][n], 0, 0, 0); __builtin_amdgcn_s_setprio(0); } while (0)
; #define PG8_WAIT_V(n) asm volatile("s_waitcnt vmcnt(" #n ")" ::: "memory")
; #define PG8_WAIT_L(n) asm volatile("s_waitcnt lgkmcnt(" #n ")" ::: "memory")
; #define PG8_BAR __builtin_amdgcn_s_barrier()
; #define PG8_SCHED __builtin_amdgcn_sched_barrier(0)
; template <class Epi, class Sched>
; __device__ __forceinline__ void gemm_phase(LAS unsigned char* lds, const int K, const int lda, const int ldb, const Sched& S, const Epi& E) {
;     ...
;             PG8_LDA(At, 1, 1); PG8_STAGE(PG8_SB(1, 0), b3, voffB); PG8_STAGE(PG8_SB(1, 1), b3 + hB, voffB); PG8_STAGE(PG8_SA(1, 0), a3, voffA);
;             PG8_WAIT_V(8); PG8_WAIT_L(0); PG8_BAR; PG8_MMA(1, 0, At, B0); PG8_MMA(1, 1, At, B1); PG8_BAR; PG8_SCHED;
;         }
;         if (wr == 0) PG8_BAR;
	s_add_i32 s61, s61, s2
	v_lshl_add_u64 v[182:183], v[182:183], 0, s[50:51]
	s_mov_b32 m0, s61
	ds_read_b128 v[214:217], v163 offset:49152
	ds_read_b128 v[218:221], v145 offset:49152
	ds_read_b128 v[222:225], v163 offset:51200
	ds_read_b128 v[226:229], v145 offset:51200
	ds_read_b128 v[230:233], v163 offset:53248
	ds_read_b128 v[236:239], v145 offset:53248
	ds_read_b128 v[240:243], v163 offset:55296
	ds_read_b128 v[244:247], v145 offset:55296
	global_load_lds_dwordx4 v[182:183], off
	s_add_i32 m0, s61, 0x2000
	s_add_u32 s68, s68, 0x80080
	v_lshl_add_u64 v[182:183], v[234:235], 0, s[50:51]
	s_addc_u32 s69, s69, 0
	s_add_i32 s61, s72, s2
	global_load_lds_dwordx4 v[182:183], off
	v_lshl_add_u64 v[182:183], s[68:69], 0, v[132:133]
	s_mov_b32 m0, s61
	s_nop 0
	global_load_lds_dwordx4 v[182:183], off
	v_lshl_add_u64 v[182:183], s[68:69], 0, v[128:129]
	s_add_i32 m0, s61, 0x2000
	s_nop 0
	global_load_lds_dwordx4 v[182:183], off
	v_lshl_add_u64 v[182:183], v[248:249], 0, s[50:51]
	s_mov_b32 m0, s17
	s_nop 0
	global_load_lds_dwordx4 v[182:183], off
	v_lshl_add_u64 v[182:183], v[250:251], 0, s[50:51]
	s_mov_b32 m0, s21
	s_nop 0
	global_load_lds_dwordx4 v[182:183], off
	s_waitcnt vmcnt(8)
	s_waitcnt lgkmcnt(0)
	s_barrier
	s_waitcnt lgkmcnt(0)
	v_mfma_f32_16x16x32_bf16 v[60:63], v[214:217], v[174:177], v[60:63]
	v_mfma_f32_16x16x32_bf16 v[56:59], v[214:217], v[190:193], v[56:59]
	v_mfma_f32_16x16x32_bf16 v[44:47], v[222:225], v[174:177], v[44:47]
	v_mfma_f32_16x16x32_bf16 v[40:43], v[222:225], v[190:193], v[40:43]
	v_mfma_f32_16x16x32_bf16 v[28:31], v[230:233], v[174:177], v[28:31]
	v_mfma_f32_16x16x32_bf16 v[24:27], v[230:233], v[190:193], v[24:27]
	v_mfma_f32_16x16x32_bf16 v[12:15], v[240:243], v[174:177], v[12:15]
	v_mfma_f32_16x16x32_bf16 v[8:11], v[240:243], v[190:193], v[8:11]
	v_mfma_f32_16x16x32_bf16 v[60:63], v[218:221], v[178:181], v[60:63]
	v_mfma_f32_16x16x32_bf16 v[56:59], v[218:221], v[194:197], v[56:59]
	v_mfma_f32_16x16x32_bf16 v[44:47], v[226:229], v[178:181], v[44:47]
	v_mfma_f32_16x16x32_bf16 v[40:43], v[226:229], v[194:197], v[40:43]
	v_mfma_f32_16x16x32_bf16 v[28:31], v[236:239], v[178:181], v[28:31]
	v_mfma_f32_16x16x32_bf16 v[24:27], v[236:239], v[194:197], v[24:27]
	v_mfma_f32_16x16x32_bf16 v[12:15], v[244:247], v[178:181], v[12:15]
	v_mfma_f32_16x16x32_bf16 v[8:11], v[244:247], v[194:197], v[8:11]
	v_mfma_f32_16x16x32_bf16 v[52:55], v[214:217], v[198:201], v[52:55]
	v_mfma_f32_16x16x32_bf16 v[48:51], v[214:217], v[206:209], v[48:51]
	v_mfma_f32_16x16x32_bf16 v[36:39], v[222:225], v[198:201], v[36:39]
	v_mfma_f32_16x16x32_bf16 v[32:35], v[222:225], v[206:209], v[32:35]
	v_mfma_f32_16x16x32_bf16 v[20:23], v[230:233], v[198:201], v[20:23]
	v_mfma_f32_16x16x32_bf16 v[16:19], v[230:233], v[206:209], v[16:19]
	v_mfma_f32_16x16x32_bf16 v[4:7], v[240:243], v[198:201], v[4:7]
	v_mfma_f32_16x16x32_bf16 v[0:3], v[240:243], v[206:209], v[0:3]
	v_mfma_f32_16x16x32_bf16 v[52:55], v[218:221], v[202:205], v[52:55]
	v_mfma_f32_16x16x32_bf16 v[48:51], v[218:221], v[210:213], v[48:51]
	v_mfma_f32_16x16x32_bf16 v[36:39], v[226:229], v[202:205], v[36:39]
	v_mfma_f32_16x16x32_bf16 v[32:35], v[226:229], v[210:213], v[32:35]
	v_mfma_f32_16x16x32_bf16 v[20:23], v[236:239], v[202:205], v[20:23]
	v_mfma_f32_16x16x32_bf16 v[16:19], v[236:239], v[210:213], v[16:19]
	v_mfma_f32_16x16x32_bf16 v[4:7], v[244:247], v[202:205], v[4:7]
	v_mfma_f32_16x16x32_bf16 v[0:3], v[244:247], v[210:213], v[0:3]
	s_barrier
	s_add_i32 s59, s59, 2
	s_add_u32 s55, s55, 0x100
	s_addc_u32 s57, s57, 0
	s_add_u32 s66, s66, 0x100
	s_addc_u32 s67, s67, 0
	s_cmp_gt_u32 s59, 29
	s_cbranch_scc0 .LBB0_963
	s_and_b64 vcc, exec, s[52:53]
	s_cbranch_vccz .LBB0_966
	s_barrier

; #define PG8_STAGE(bufoff, gbase, voff) do { _Pragma("unroll") for (int _i = 0; _i < 2; ++_i) \
;         __builtin_amdgcn_global_load_lds((const unsigned*)((const char*)(gbase) + (voff)[_i]), (LAS unsigned*)(lds + (bufoff) + ldsw + _i * 8192), 16, 0, 0); } while (0)
; #define PG8_LDA(dst, b, h) do { _Pragma("unroll") for (int m = 0; m < 4; ++m) _Pragma("unroll") for (int k = 0; k < 2; ++k) dst[m][k] = *(const LAS bf16x8*)(lds + PG8_SA(b, h) + aoff + m * 2048 + k * 1024); } while (0)
; #define PG8_LDB(dst, b, h) do { _Pragma("unroll") for (int n = 0; n < 2; ++n) _Pragma("unroll") for (int k = 0; k < 2; ++k) dst[n][k] = *(const LAS bf16x8*)(lds + PG8_SB(b, h) + boff + n * 2048 + k * 1024); } while (0)
; #define PG8_MMA(ai, bj, At, Bt) do { __builtin_amdgcn_s_setprio(1); _Pragma("unroll") for (int m = 0; m < 4; ++m) _Pragma("unroll") for (int n = 0; n < 2; ++n) _Pragma("unroll") for (int k = 0; k < 2; ++k) \
;         acc[ai][bj][m][n] = __builtin_amdgcn_mfma_f32_16x16x32_bf16(Bt[n][k], At[m][k], acc[ai][bj][m][n], 0, 0, 0); __builtin_amdgcn_s_setprio(0); } while (0)
; #define PG8_WAIT_V(n) asm volatile("s_waitcnt vmcnt(" #n ")" ::: "memory")
; #define PG8_WAIT_L(n) asm volatile("s_waitcnt lgkmcnt(" #n ")" ::: "memory")
; #define PG8_BAR __builtin_amdgcn_s_barrier()
; #define PG8_SCHED __builtin_amdgcn_sched_barrier(0)
; template <class Epi, class Sched>
; __device__ __forceinline__ void gemm_phase(LAS unsigned char* lds, const int K, const int lda, const int ldb, const Sched& S, const Epi& E) {
;     ...
;             PG8_LDB(B0, 0, 0); PG8_LDB(B1, 0, 1); PG8_SCHED; PG8_LDA(At, 0, 0); PG8_STAGE(PG8_SA(1, 1), a1 + hA, voffA);
;             PG8_WAIT_V(8); PG8_WAIT_L(0); PG8_BAR; PG8_MMA(0, 0, At, B0); PG8_MMA(0, 1, At, B1); PG8_BAR; PG8_SCHED;
;             PG8_LDA(At, 0, 1); PG8_STAGE(PG8_SB(0, 0), b2, voffB); PG8_STAGE(PG8_SB(0, 1), b2 + hB, voffB); PG8_STAGE(PG8_SA(0, 0), a2, voffA);
;             PG8_WAIT_V(8); PG8_WAIT_L(0); PG8_BAR; PG8_MMA(1, 0, At, B0); PG8_MMA(1, 1, At, B1); PG8_BAR; PG8_SCHED;
.LBB0_1180:
	ds_read_b128 v[156:159], v151
	ds_read_b128 v[160:163], v151 offset:1024
	ds_read_b128 v[164:167], v151 offset:2048
	ds_read_b128 v[168:171], v151 offset:3072
	ds_read_b128 v[172:175], v152
	ds_read_b128 v[176:179], v152 offset:1024
	ds_read_b128 v[180:183], v152 offset:2048
	ds_read_b128 v[184:187], v152 offset:3072
	s_add_u32 s60, s12, 0xfff00080
	s_addc_u32 s61, s13, -1
	s_cmp_eq_u32 s74, 28
	s_cselect_b32 s63, s53, s61
	s_cselect_b32 s62, s52, s60
	s_cselect_b32 s61, s59, s57
	s_cselect_b32 s60, s58, s21
	v_lshl_add_u64 v[146:147], s[12:13], 0, v[140:141]
	s_add_i32 m0, s15, 0xc000
	ds_read_b128 v[188:191], v153
	ds_read_b128 v[192:195], v153 offset:1024
	ds_read_b128 v[196:199], v153 offset:2048
	ds_read_b128 v[200:203], v153 offset:3072
	ds_read_b128 v[204:207], v153 offset:4096
	ds_read_b128 v[208:211], v153 offset:5120
	ds_read_b128 v[212:215], v153 offset:6144
	ds_read_b128 v[216:219], v153 offset:7168
	global_load_lds_dwordx4 v[146:147], off
	v_lshl_add_u64 v[146:147], s[12:13], 0, v[138:139]
	s_add_i32 m0, s15, 0xe000
	s_nop 0
	global_load_lds_dwordx4 v[146:147], off
	s_waitcnt vmcnt(8)
	s_waitcnt lgkmcnt(0)
	s_barrier
	s_waitcnt lgkmcnt(0)
	v_mfma_f32_16x16x32_bf16 v[124:127], v[156:159], v[188:191], v[124:127]
	v_mfma_f32_16x16x32_bf16 v[120:123], v[164:167], v[188:191], v[120:123]
	v_mfma_f32_16x16x32_bf16 v[108:111], v[156:159], v[196:199], v[108:111]
	v_mfma_f32_16x16x32_bf16 v[104:107], v[164:167], v[196:199], v[104:107]
	v_mfma_f32_16x16x32_bf16 v[92:95], v[156:159], v[204:207], v[92:95]
	v_mfma_f32_16x16x32_bf16 v[88:91], v[164:167], v[204:207], v[88:91]
	v_mfma_f32_16x16x32_bf16 v[76:79], v[156:159], v[212:215], v[76:79]
	v_mfma_f32_16x16x32_bf16 v[72:75], v[164:167], v[212:215], v[72:75]
	v_mfma_f32_16x16x32_bf16 v[124:127], v[160:163], v[192:195], v[124:127]
	v_mfma_f32_16x16x32_bf16 v[120:123], v[168:171], v[192:195], v[120:123]
	v_mfma_f32_16x16x32_bf16 v[108:111], v[160:163], v[200:203], v[108:111]
	v_mfma_f32_16x16x32_bf16 v[104:107], v[168:171], v[200:203], v[104:107]
	v_mfma_f32_16x16x32_bf16 v[92:95], v[160:163], v[208:211], v[92:95]
	v_mfma_f32_16x16x32_bf16 v[88:91], v[168:171], v[208:211], v[88:91]
	v_mfma_f32_16x16x32_bf16 v[76:79], v[160:163], v[216:219], v[76:79]
	v_mfma_f32_16x16x32_bf16 v[72:75], v[168:171], v[216:219], v[72:75]
	v_mfma_f32_16x16x32_bf16 v[116:119], v[172:175], v[188:191], v[116:119]
	v_mfma_f32_16x16x32_bf16 v[112:115], v[180:183], v[188:191], v[112:115]
	v_mfma_f32_16x16x32_bf16 v[100:103], v[172:175], v[196:199], v[100:103]
	v_mfma_f32_16x16x32_bf16 v[96:99], v[180:183], v[196:199], v[96:99]
	v_mfma_f32_16x16x32_bf16 v[84:87], v[172:175], v[204:207], v[84:87]
	v_mfma_f32_16x16x32_bf16 v[80:83], v[180:183], v[204:207], v[80:83]
	v_mfma_f32_16x16x32_bf16 v[68:71], v[172:175], v[212:215], v[68:71]
	v_mfma_f32_16x16x32_bf16 v[64:67], v[180:183], v[212:215], v[64:67]
	v_mfma_f32_16x16x32_bf16 v[116:119], v[176:179], v[192:195], v[116:119]
	v_mfma_f32_16x16x32_bf16 v[112:115], v[184:187], v[192:195], v[112:115]
	v_mfma_f32_16x16x32_bf16 v[100:103], v[176:179], v[200:203], v[100:103]
	v_mfma_f32_16x16x32_bf16 v[96:99], v[184:187], v[200:203], v[96:99]
	v_mfma_f32_16x16x32_bf16 v[84:87], v[176:179], v[208:211], v[84:87]
	v_mfma_f32_16x16x32_bf16 v[80:83], v[184:187], v[208:211], v[80:83]
	v_mfma_f32_16x16x32_bf16 v[68:71], v[176:179], v[216:219], v[68:71]
	v_mfma_f32_16x16x32_bf16 v[64:67], v[184:187], v[216:219], v[64:67]
	s_barrier
	s_add_i32 s75, s0, s14
	v_lshl_add_u64 v[146:147], s[60:61], 0, v[132:133]
	s_mov_b32 m0, s75
	ds_read_b128 v[188:191], v153 offset:16384
	ds_read_b128 v[192:195], v153 offset:17408
	ds_read_b128 v[196:199], v153 offset:18432
	ds_read_b128 v[200:203], v153 offset:19456
	ds_read_b128 v[204:207], v153 offset:20480
	ds_read_b128 v[208:211], v153 offset:21504
	ds_read_b128 v[212:215], v153 offset:22528
	ds_read_b128 v[216:219], v153 offset:23552
	global_load_lds_dwordx4 v[146:147], off
	s_add_i32 m0, s75, 0x2000
	s_add_u32 s76, s60, 0x400000
	v_lshl_add_u64 v[220:221], s[60:61], 0, v[128:129]
	s_addc_u32 s77, s61, 0
	s_add_i32 s75, s38, s14
	global_load_lds_dwordx4 v[220:221], off
	v_lshl_add_u64 v[222:223], s[76:77], 0, v[132:133]
	s_mov_b32 m0, s75
	v_lshl_add_u64 v[224:225], s[62:63], 0, v[130:131]
	global_load_lds_dwordx4 v[222:223], off
	v_lshl_add_u64 v[222:223], s[76:77], 0, v[128:129]
	s_add_i32 m0, s75, 0x2000
	s_nop 0
	global_load_lds_dwordx4 v[222:223], off
	v_lshl_add_u64 v[222:223], s[62:63], 0, v[134:135]
	s_mov_b32 m0, s15
	s_nop 0
	global_load_lds_dwordx4 v[222:223], off
	s_mov_b32 m0, s18
	s_nop 0
	global_load_lds_dwordx4 v[224:225], off
	s_waitcnt vmcnt(8)
	s_waitcnt lgkmcnt(0)
	s_barrier
; #define PG8_STAGE(bufoff, gbase, voff) do { _Pragma("unroll") for (int _i = 0; _i < 2; ++_i) \
;         __builtin_amdgcn_global_load_lds((const unsigned*)((const char*)(gbase) + (voff)[_i]), (LAS unsigned*)(lds + (bufoff) + ldsw + _i * 8192), 16, 0, 0); } while (0)
; #define PG8_LDA(dst, b, h) do { _Pragma("unroll") for (int m = 0; m < 4; ++m) _Pragma("unroll") for (int k = 0; k < 2; ++k) dst[m][k] = *(const LAS bf16x8*)(lds + PG8_SA(b, h) + aoff + m * 2048 + k * 1024); } while (0)
; #define PG8_LDB(dst, b, h) do { _Pragma("unroll") for (int n = 0; n < 2; ++n) _Pragma("unroll") for (int k = 0; k < 2; ++k) dst[n][k] = *(const LAS bf16x8*)(lds + PG8_SB(b, h) + boff + n * 2048 + k * 1024); } while (0)
; #define PG8_MMA(ai, bj, At, Bt) do { __builtin_amdgcn_s_setprio(1); _Pragma("unroll") for (int m = 0; m < 4; ++m) _Pragma("unroll") for (int n = 0; n < 2; ++n) _Pragma("unroll") for (int k = 0; k < 2; ++k) \
;         acc[ai][bj][m][n] = __builtin_amdgcn_mfma_f32_16x16x32_bf16(Bt[n][k], At[m][k], acc[ai][bj][m][n], 0, 0, 0); __builtin_amdgcn_s_setprio(0); } while (0)
; #define PG8_WAIT_V(n) asm volatile("s_waitcnt vmcnt(" #n ")" ::: "memory")
; #define PG8_WAIT_L(n) asm volatile("s_waitcnt lgkmcnt(" #n ")" ::: "memory")
; #define PG8_BAR __builtin_amdgcn_s_barrier()
; #define PG8_SCHED __builtin_amdgcn_sched_barrier(0)
; template <class Epi, class Sched>
; __device__ __forceinline__ void gemm_phase(LAS unsigned char* lds, const int K, const int lda, const int ldb, const Sched& S, const Epi& E) {
;     ...
;             PG8_WAIT_V(8); PG8_WAIT_L(0); PG8_BAR; PG8_MMA(1, 0, At, B0); PG8_MMA(1, 1, At, B1); PG8_BAR; PG8_SCHED;
;             PG8_LDB(B0, 1, 0); PG8_LDB(B1, 1, 1); PG8_SCHED; PG8_LDA(At, 1, 0); PG8_STAGE(PG8_SA(0, 1), a2 + hA, voffA);
;             PG8_WAIT_V(8); PG8_WAIT_L(0); PG8_BAR; PG8_MMA(0, 0, At, B0); PG8_MMA(0, 1, At, B1); PG8_BAR; PG8_SCHED;
	s_waitcnt lgkmcnt(0)
	v_mfma_f32_16x16x32_bf16 v[60:63], v[156:159], v[188:191], v[60:63]
	v_mfma_f32_16x16x32_bf16 v[56:59], v[164:167], v[188:191], v[56:59]
	v_mfma_f32_16x16x32_bf16 v[44:47], v[156:159], v[196:199], v[44:47]
	v_mfma_f32_16x16x32_bf16 v[40:43], v[164:167], v[196:199], v[40:43]
	v_mfma_f32_16x16x32_bf16 v[28:31], v[156:159], v[204:207], v[28:31]
	v_mfma_f32_16x16x32_bf16 v[24:27], v[164:167], v[204:207], v[24:27]
	v_mfma_f32_16x16x32_bf16 v[12:15], v[156:159], v[212:215], v[12:15]
	v_mfma_f32_16x16x32_bf16 v[8:11], v[164:167], v[212:215], v[8:11]
	v_mfma_f32_16x16x32_bf16 v[60:63], v[160:163], v[192:195], v[60:63]
	v_mfma_f32_16x16x32_bf16 v[56:59], v[168:171], v[192:195], v[56:59]
	v_mfma_f32_16x16x32_bf16 v[44:47], v[160:163], v[200:203], v[44:47]
	v_mfma_f32_16x16x32_bf16 v[40:43], v[168:171], v[200:203], v[40:43]
	v_mfma_f32_16x16x32_bf16 v[28:31], v[160:163], v[208:211], v[28:31]
	v_mfma_f32_16x16x32_bf16 v[24:27], v[168:171], v[208:211], v[24:27]
	v_mfma_f32_16x16x32_bf16 v[12:15], v[160:163], v[216:219], v[12:15]
	v_mfma_f32_16x16x32_bf16 v[8:11], v[168:171], v[216:219], v[8:11]
	v_mfma_f32_16x16x32_bf16 v[52:55], v[172:175], v[188:191], v[52:55]
	v_mfma_f32_16x16x32_bf16 v[48:51], v[180:183], v[188:191], v[48:51]
	v_mfma_f32_16x16x32_bf16 v[36:39], v[172:175], v[196:199], v[36:39]
	v_mfma_f32_16x16x32_bf16 v[32:35], v[180:183], v[196:199], v[32:35]
	v_mfma_f32_16x16x32_bf16 v[20:23], v[172:175], v[204:207], v[20:23]
	v_mfma_f32_16x16x32_bf16 v[16:19], v[180:183], v[204:207], v[16:19]
	v_mfma_f32_16x16x32_bf16 v[4:7], v[172:175], v[212:215], v[4:7]
	v_mfma_f32_16x16x32_bf16 v[0:3], v[180:183], v[212:215], v[0:3]
	v_mfma_f32_16x16x32_bf16 v[52:55], v[176:179], v[192:195], v[52:55]
	v_mfma_f32_16x16x32_bf16 v[48:51], v[184:187], v[192:195], v[48:51]
	v_mfma_f32_16x16x32_bf16 v[36:39], v[176:179], v[200:203], v[36:39]
	v_mfma_f32_16x16x32_bf16 v[32:35], v[184:187], v[200:203], v[32:35]
	v_mfma_f32_16x16x32_bf16 v[20:23], v[176:179], v[208:211], v[20:23]
	v_mfma_f32_16x16x32_bf16 v[16:19], v[184:187], v[208:211], v[16:19]
	v_mfma_f32_16x16x32_bf16 v[4:7], v[176:179], v[216:219], v[4:7]
	v_mfma_f32_16x16x32_bf16 v[0:3], v[184:187], v[216:219], v[0:3]
	s_barrier
	s_add_i32 s75, 0, 0x18000
	v_add_u32_e32 v136, s75, v149
	s_add_i32 s76, 0, 0x1c000
	ds_read_b128 v[156:159], v136
	ds_read_b128 v[160:163], v136 offset:1024
	ds_read_b128 v[164:167], v136 offset:2048
	ds_read_b128 v[168:171], v136 offset:3072
	v_add_u32_e32 v136, s76, v149
	ds_read_b128 v[172:175], v136
	ds_read_b128 v[176:179], v136 offset:1024
	ds_read_b128 v[180:183], v136 offset:2048
	ds_read_b128 v[184:187], v136 offset:3072
	s_add_u32 s62, s62, 0x100000
	s_addc_u32 s63, s63, 0
	s_mov_b32 m0, s23
	v_lshl_add_u64 v[226:227], s[62:63], 0, v[134:135]
	ds_read_b128 v[188:191], v153 offset:32768
	ds_read_b128 v[192:195], v153 offset:33792
	ds_read_b128 v[196:199], v153 offset:34816
	ds_read_b128 v[200:203], v153 offset:35840
	ds_read_b128 v[204:207], v153 offset:36864
	ds_read_b128 v[208:211], v153 offset:37888
	ds_read_b128 v[212:215], v153 offset:38912
	ds_read_b128 v[216:219], v153 offset:39936
	global_load_lds_dwordx4 v[226:227], off
	v_lshl_add_u64 v[226:227], s[62:63], 0, v[130:131]
	s_mov_b32 m0, s26
	s_nop 0
	global_load_lds_dwordx4 v[226:227], off
	s_waitcnt vmcnt(8)
	s_waitcnt lgkmcnt(0)
	s_barrier
	s_waitcnt lgkmcnt(0)
	v_mfma_f32_16x16x32_bf16 v[124:127], v[156:159], v[188:191], v[124:127]
	v_mfma_f32_16x16x32_bf16 v[120:123], v[164:167], v[188:191], v[120:123]
	v_mfma_f32_16x16x32_bf16 v[108:111], v[156:159], v[196:199], v[108:111]
	v_mfma_f32_16x16x32_bf16 v[104:107], v[164:167], v[196:199], v[104:107]
	v_mfma_f32_16x16x32_bf16 v[92:95], v[156:159], v[204:207], v[92:95]
	v_mfma_f32_16x16x32_bf16 v[88:91], v[164:167], v[204:207], v[88:91]
	v_mfma_f32_16x16x32_bf16 v[76:79], v[156:159], v[212:215], v[76:79]
	v_mfma_f32_16x16x32_bf16 v[72:75], v[164:167], v[212:215], v[72:75]
	v_mfma_f32_16x16x32_bf16 v[124:127], v[160:163], v[192:195], v[124:127]
	v_mfma_f32_16x16x32_bf16 v[120:123], v[168:171], v[192:195], v[120:123]
	v_mfma_f32_16x16x32_bf16 v[108:111], v[160:163], v[200:203], v[108:111]
	v_mfma_f32_16x16x32_bf16 v[104:107], v[168:171], v[200:203], v[104:107]
	v_mfma_f32_16x16x32_bf16 v[92:95], v[160:163], v[208:211], v[92:95]
	v_mfma_f32_16x16x32_bf16 v[88:91], v[168:171], v[208:211], v[88:91]
	v_mfma_f32_16x16x32_bf16 v[76:79], v[160:163], v[216:219], v[76:79]
	v_mfma_f32_16x16x32_bf16 v[72:75], v[168:171], v[216:219], v[72:75]
	v_mfma_f32_16x16x32_bf16 v[116:119], v[172:175], v[188:191], v[116:119]
	v_mfma_f32_16x16x32_bf16 v[112:115], v[180:183], v[188:191], v[112:115]
	v_mfma_f32_16x16x32_bf16 v[100:103], v[172:175], v[196:199], v[100:103]
	v_mfma_f32_16x16x32_bf16 v[96:99], v[180:183], v[196:199], v[96:99]
	v_mfma_f32_16x16x32_bf16 v[84:87], v[172:175], v[204:207], v[84:87]
	v_mfma_f32_16x16x32_bf16 v[80:83], v[180:183], v[204:207], v[80:83]
	v_mfma_f32_16x16x32_bf16 v[68:71], v[172:175], v[212:215], v[68:71]
	v_mfma_f32_16x16x32_bf16 v[64:67], v[180:183], v[212:215], v[64:67]
	v_mfma_f32_16x16x32_bf16 v[116:119], v[176:179], v[192:195], v[116:119]
	v_mfma_f32_16x16x32_bf16 v[112:115], v[184:187], v[192:195], v[112:115]
	v_mfma_f32_16x16x32_bf16 v[100:103], v[176:179], v[200:203], v[100:103]
	v_mfma_f32_16x16x32_bf16 v[96:99], v[184:187], v[200:203], v[96:99]
	v_mfma_f32_16x16x32_bf16 v[84:87], v[176:179], v[208:211], v[84:87]
	v_mfma_f32_16x16x32_bf16 v[80:83], v[184:187], v[208:211], v[80:83]
	v_mfma_f32_16x16x32_bf16 v[68:71], v[176:179], v[216:219], v[68:71]
	v_mfma_f32_16x16x32_bf16 v[64:67], v[184:187], v[216:219], v[64:67]
	s_barrier
; #define PG8_STAGE(bufoff, gbase, voff) do { _Pragma("unroll") for (int _i = 0; _i < 2; ++_i) \
;         __builtin_amdgcn_global_load_lds((const unsigned*)((const char*)(gbase) + (voff)[_i]), (LAS unsigned*)(lds + (bufoff) + ldsw + _i * 8192), 16, 0, 0); } while (0)
; #define PG8_LDA(dst, b, h) do { _Pragma("unroll") for (int m = 0; m < 4; ++m) _Pragma("unroll") for (int k = 0; k < 2; ++k) dst[m][k] = *(const LAS bf16x8*)(lds + PG8_SA(b, h) + aoff + m * 2048 + k * 1024); } while (0)
; #define PG8_MMA(ai, bj, At, Bt) do { __builtin_amdgcn_s_setprio(1); _Pragma("unroll") for (int m = 0; m < 4; ++m) _Pragma("unroll") for (int n = 0; n < 2; ++n) _Pragma("unroll") for (int k = 0; k < 2; ++k) \
;         acc[ai][bj][m][n] = __builtin_amdgcn_mfma_f32_16x16x32_bf16(Bt[n][k], At[m][k], acc[ai][bj][m][n], 0, 0, 0); __builtin_amdgcn_s_setprio(0); } while (0)
; #define PG8_WAIT_V(n) asm volatile("s_waitcnt vmcnt(" #n ")" ::: "memory")
; #define PG8_WAIT_L(n) asm volatile("s_waitcnt lgkmcnt(" #n ")" ::: "memory")
; #define PG8_BAR __builtin_amdgcn_s_barrier()
; #define PG8_SCHED __builtin_amdgcn_sched_barrier(0)
; template <class Epi, class Sched>
; __device__ __forceinline__ void gemm_phase(LAS unsigned char* lds, const int K, const int lda, const int ldb, const Sched& S, const Epi& E) {
;     ...
;             PG8_LDA(At, 1, 1); PG8_STAGE(PG8_SB(1, 0), b3, voffB); PG8_STAGE(PG8_SB(1, 1), b3 + hB, voffB); PG8_STAGE(PG8_SA(1, 0), a3, voffA);
;             PG8_WAIT_V(8); PG8_WAIT_L(0); PG8_BAR; PG8_MMA(1, 0, At, B0); PG8_MMA(1, 1, At, B1); PG8_BAR; PG8_SCHED;
;         }
;         if (wr == 0) PG8_BAR;
	s_add_i32 s62, s75, s14
	v_lshl_add_u64 v[146:147], v[146:147], 0, s[48:49]
	s_mov_b32 m0, s62
	ds_read_b128 v[188:191], v153 offset:49152
	ds_read_b128 v[192:195], v153 offset:50176
	ds_read_b128 v[196:199], v153 offset:51200
	ds_read_b128 v[200:203], v153 offset:52224
	ds_read_b128 v[204:207], v153 offset:53248
	ds_read_b128 v[208:211], v153 offset:54272
	ds_read_b128 v[212:215], v153 offset:55296
	ds_read_b128 v[216:219], v153 offset:56320
	global_load_lds_dwordx4 v[146:147], off
	s_add_i32 m0, s62, 0x2000
	s_add_u32 s60, s60, 0x400080
	v_lshl_add_u64 v[146:147], v[220:221], 0, s[48:49]
	s_addc_u32 s61, s61, 0
	s_add_i32 s62, s76, s14
	global_load_lds_dwordx4 v[146:147], off
	v_lshl_add_u64 v[146:147], s[60:61], 0, v[132:133]
	s_mov_b32 m0, s62
	s_nop 0
	global_load_lds_dwordx4 v[146:147], off
	v_lshl_add_u64 v[146:147], s[60:61], 0, v[128:129]
	s_add_i32 m0, s62, 0x2000
	s_nop 0
	global_load_lds_dwordx4 v[146:147], off
	v_lshl_add_u64 v[146:147], v[222:223], 0, s[48:49]
	s_mov_b32 m0, s30
	s_nop 0
	global_load_lds_dwordx4 v[146:147], off
	v_lshl_add_u64 v[146:147], v[224:225], 0, s[48:49]
	s_mov_b32 m0, s31
	s_nop 0
	global_load_lds_dwordx4 v[146:147], off
	s_waitcnt vmcnt(8)
	s_waitcnt lgkmcnt(0)
	s_barrier
	s_waitcnt lgkmcnt(0)
	v_mfma_f32_16x16x32_bf16 v[60:63], v[156:159], v[188:191], v[60:63]
	v_mfma_f32_16x16x32_bf16 v[56:59], v[164:167], v[188:191], v[56:59]
	v_mfma_f32_16x16x32_bf16 v[44:47], v[156:159], v[196:199], v[44:47]
	v_mfma_f32_16x16x32_bf16 v[40:43], v[164:167], v[196:199], v[40:43]
	v_mfma_f32_16x16x32_bf16 v[28:31], v[156:159], v[204:207], v[28:31]
	v_mfma_f32_16x16x32_bf16 v[24:27], v[164:167], v[204:207], v[24:27]
	v_mfma_f32_16x16x32_bf16 v[12:15], v[156:159], v[212:215], v[12:15]
	v_mfma_f32_16x16x32_bf16 v[8:11], v[164:167], v[212:215], v[8:11]
	v_mfma_f32_16x16x32_bf16 v[60:63], v[160:163], v[192:195], v[60:63]
	v_mfma_f32_16x16x32_bf16 v[56:59], v[168:171], v[192:195], v[56:59]
	v_mfma_f32_16x16x32_bf16 v[44:47], v[160:163], v[200:203], v[44:47]
	v_mfma_f32_16x16x32_bf16 v[40:43], v[168:171], v[200:203], v[40:43]
	v_mfma_f32_16x16x32_bf16 v[28:31], v[160:163], v[208:211], v[28:31]
	v_mfma_f32_16x16x32_bf16 v[24:27], v[168:171], v[208:211], v[24:27]
	v_mfma_f32_16x16x32_bf16 v[12:15], v[160:163], v[216:219], v[12:15]
	v_mfma_f32_16x16x32_bf16 v[8:11], v[168:171], v[216:219], v[8:11]
	v_mfma_f32_16x16x32_bf16 v[52:55], v[172:175], v[188:191], v[52:55]
	v_mfma_f32_16x16x32_bf16 v[48:51], v[180:183], v[188:191], v[48:51]
	v_mfma_f32_16x16x32_bf16 v[36:39], v[172:175], v[196:199], v[36:39]
	v_mfma_f32_16x16x32_bf16 v[32:35], v[180:183], v[196:199], v[32:35]
	v_mfma_f32_16x16x32_bf16 v[20:23], v[172:175], v[204:207], v[20:23]
	v_mfma_f32_16x16x32_bf16 v[16:19], v[180:183], v[204:207], v[16:19]
	v_mfma_f32_16x16x32_bf16 v[4:7], v[172:175], v[212:215], v[4:7]
	v_mfma_f32_16x16x32_bf16 v[0:3], v[180:183], v[212:215], v[0:3]
	v_mfma_f32_16x16x32_bf16 v[52:55], v[176:179], v[192:195], v[52:55]
	v_mfma_f32_16x16x32_bf16 v[48:51], v[184:187], v[192:195], v[48:51]
	v_mfma_f32_16x16x32_bf16 v[36:39], v[176:179], v[200:203], v[36:39]
	v_mfma_f32_16x16x32_bf16 v[32:35], v[184:187], v[200:203], v[32:35]
	v_mfma_f32_16x16x32_bf16 v[20:23], v[176:179], v[208:211], v[20:23]
	v_mfma_f32_16x16x32_bf16 v[16:19], v[184:187], v[208:211], v[16:19]
	v_mfma_f32_16x16x32_bf16 v[4:7], v[176:179], v[216:219], v[4:7]
	v_mfma_f32_16x16x32_bf16 v[0:3], v[184:187], v[216:219], v[0:3]
	s_barrier
	s_add_i32 s74, s74, 2
	s_add_u32 s21, s21, 0x100
	s_addc_u32 s57, s57, 0
	s_add_u32 s12, s12, 0x100
	s_addc_u32 s13, s13, 0
	s_cmp_gt_u32 s74, 29
	s_cbranch_scc0 .LBB0_1180
	s_and_b64 vcc, exec, s[50:51]
	s_cbranch_vccz .LBB0_1183
	s_barrier

; #define PG8_STAGE(bufoff, gbase, voff) do { _Pragma("unroll") for (int _i = 0; _i < 2; ++_i) \
;         __builtin_amdgcn_global_load_lds((const unsigned*)((const char*)(gbase) + (voff)[_i]), (LAS unsigned*)(lds + (bufoff) + ldsw + _i * 8192), 16, 0, 0); } while (0)
; #define PG8_LDA(dst, b, h) do { _Pragma("unroll") for (int m = 0; m < 4; ++m) _Pragma("unroll") for (int k = 0; k < 2; ++k) dst[m][k] = *(const LAS bf16x8*)(lds + PG8_SA(b, h) + aoff + m * 2048 + k * 1024); } while (0)
; #define PG8_LDB(dst, b, h) do { _Pragma("unroll") for (int n = 0; n < 2; ++n) _Pragma("unroll") for (int k = 0; k < 2; ++k) dst[n][k] = *(const LAS bf16x8*)(lds + PG8_SB(b, h) + boff + n * 2048 + k * 1024); } while (0)
; #define PG8_MMA(ai, bj, At, Bt) do { __builtin_amdgcn_s_setprio(1); _Pragma("unroll") for (int m = 0; m < 4; ++m) _Pragma("unroll") for (int n = 0; n < 2; ++n) _Pragma("unroll") for (int k = 0; k < 2; ++k) \
;         acc[ai][bj][m][n] = __builtin_amdgcn_mfma_f32_16x16x32_bf16(Bt[n][k], At[m][k], acc[ai][bj][m][n], 0, 0, 0); __builtin_amdgcn_s_setprio(0); } while (0)
; #define PG8_WAIT_V(n) asm volatile("s_waitcnt vmcnt(" #n ")" ::: "memory")
; #define PG8_WAIT_L(n) asm volatile("s_waitcnt lgkmcnt(" #n ")" ::: "memory")
; #define PG8_BAR __builtin_amdgcn_s_barrier()
; #define PG8_SCHED __builtin_amdgcn_sched_barrier(0)
; template <class Epi, class Sched>
; __device__ __forceinline__ void gemm_phase(LAS unsigned char* lds, const int K, const int lda, const int ldb, const Sched& S, const Epi& E) {
;     ...
;             PG8_LDB(B0, 0, 0); PG8_LDB(B1, 0, 1); PG8_SCHED; PG8_LDA(At, 0, 0); PG8_STAGE(PG8_SA(1, 1), a1 + hA, voffA);
;             PG8_WAIT_V(8); PG8_WAIT_L(0); PG8_BAR; PG8_MMA(0, 0, At, B0); PG8_MMA(0, 1, At, B1); PG8_BAR; PG8_SCHED;
;             PG8_LDA(At, 0, 1); PG8_STAGE(PG8_SB(0, 0), b2, voffB); PG8_STAGE(PG8_SB(0, 1), b2 + hB, voffB); PG8_STAGE(PG8_SA(0, 0), a2, voffA);
;             PG8_WAIT_V(8); PG8_WAIT_L(0); PG8_BAR; PG8_MMA(1, 0, At, B0); PG8_MMA(1, 1, At, B1); PG8_BAR; PG8_SCHED;
.LBB0_1230:
	ds_read_b128 v[156:159], v151
	ds_read_b128 v[160:163], v151 offset:1024
	ds_read_b128 v[164:167], v151 offset:2048
	ds_read_b128 v[168:171], v151 offset:3072
	ds_read_b128 v[172:175], v152
	ds_read_b128 v[176:179], v152 offset:1024
	ds_read_b128 v[180:183], v152 offset:2048
	ds_read_b128 v[184:187], v152 offset:3072
	s_add_u32 s54, s12, 0xffe00080
	s_addc_u32 s55, s13, -1
	s_cmp_eq_u32 s78, 12
	s_cselect_b32 s57, s27, s55
	s_cselect_b32 s56, s26, s54
	s_cselect_b32 s55, s53, s51
	s_cselect_b32 s54, s52, s23
	v_lshl_add_u64 v[146:147], s[12:13], 0, v[140:141]
	s_add_i32 m0, s15, 0xc000
	ds_read_b128 v[188:191], v153
	ds_read_b128 v[192:195], v153 offset:1024
	ds_read_b128 v[196:199], v153 offset:2048
	ds_read_b128 v[200:203], v153 offset:3072
	ds_read_b128 v[204:207], v153 offset:4096
	ds_read_b128 v[208:211], v153 offset:5120
	ds_read_b128 v[212:215], v153 offset:6144
	ds_read_b128 v[216:219], v153 offset:7168
	global_load_lds_dwordx4 v[146:147], off
	v_lshl_add_u64 v[146:147], s[12:13], 0, v[138:139]
	s_add_i32 m0, s15, 0xe000
	s_nop 0
	global_load_lds_dwordx4 v[146:147], off
	s_waitcnt vmcnt(8)
	s_waitcnt lgkmcnt(0)
	s_barrier
	s_waitcnt lgkmcnt(0)
	v_mfma_f32_16x16x32_bf16 v[124:127], v[156:159], v[188:191], v[124:127]
	v_mfma_f32_16x16x32_bf16 v[120:123], v[164:167], v[188:191], v[120:123]
	v_mfma_f32_16x16x32_bf16 v[108:111], v[156:159], v[196:199], v[108:111]
	v_mfma_f32_16x16x32_bf16 v[104:107], v[164:167], v[196:199], v[104:107]
	v_mfma_f32_16x16x32_bf16 v[92:95], v[156:159], v[204:207], v[92:95]
	v_mfma_f32_16x16x32_bf16 v[88:91], v[164:167], v[204:207], v[88:91]
	v_mfma_f32_16x16x32_bf16 v[76:79], v[156:159], v[212:215], v[76:79]
	v_mfma_f32_16x16x32_bf16 v[72:75], v[164:167], v[212:215], v[72:75]
	v_mfma_f32_16x16x32_bf16 v[124:127], v[160:163], v[192:195], v[124:127]
	v_mfma_f32_16x16x32_bf16 v[120:123], v[168:171], v[192:195], v[120:123]
	v_mfma_f32_16x16x32_bf16 v[108:111], v[160:163], v[200:203], v[108:111]
	v_mfma_f32_16x16x32_bf16 v[104:107], v[168:171], v[200:203], v[104:107]
	v_mfma_f32_16x16x32_bf16 v[92:95], v[160:163], v[208:211], v[92:95]
	v_mfma_f32_16x16x32_bf16 v[88:91], v[168:171], v[208:211], v[88:91]
	v_mfma_f32_16x16x32_bf16 v[76:79], v[160:163], v[216:219], v[76:79]
	v_mfma_f32_16x16x32_bf16 v[72:75], v[168:171], v[216:219], v[72:75]
	v_mfma_f32_16x16x32_bf16 v[116:119], v[172:175], v[188:191], v[116:119]
	v_mfma_f32_16x16x32_bf16 v[112:115], v[180:183], v[188:191], v[112:115]
	v_mfma_f32_16x16x32_bf16 v[100:103], v[172:175], v[196:199], v[100:103]
	v_mfma_f32_16x16x32_bf16 v[96:99], v[180:183], v[196:199], v[96:99]
	v_mfma_f32_16x16x32_bf16 v[84:87], v[172:175], v[204:207], v[84:87]
	v_mfma_f32_16x16x32_bf16 v[80:83], v[180:183], v[204:207], v[80:83]
	v_mfma_f32_16x16x32_bf16 v[68:71], v[172:175], v[212:215], v[68:71]
	v_mfma_f32_16x16x32_bf16 v[64:67], v[180:183], v[212:215], v[64:67]
	v_mfma_f32_16x16x32_bf16 v[116:119], v[176:179], v[192:195], v[116:119]
	v_mfma_f32_16x16x32_bf16 v[112:115], v[184:187], v[192:195], v[112:115]
	v_mfma_f32_16x16x32_bf16 v[100:103], v[176:179], v[200:203], v[100:103]
	v_mfma_f32_16x16x32_bf16 v[96:99], v[184:187], v[200:203], v[96:99]
	v_mfma_f32_16x16x32_bf16 v[84:87], v[176:179], v[208:211], v[84:87]
	v_mfma_f32_16x16x32_bf16 v[80:83], v[184:187], v[208:211], v[80:83]
	v_mfma_f32_16x16x32_bf16 v[68:71], v[176:179], v[216:219], v[68:71]
	v_mfma_f32_16x16x32_bf16 v[64:67], v[184:187], v[216:219], v[64:67]
	s_barrier
	s_add_i32 s79, s59, s14
	v_lshl_add_u64 v[146:147], s[54:55], 0, v[132:133]
	s_mov_b32 m0, s79
	ds_read_b128 v[188:191], v153 offset:16384
	ds_read_b128 v[192:195], v153 offset:17408
	ds_read_b128 v[196:199], v153 offset:18432
	ds_read_b128 v[200:203], v153 offset:19456
	ds_read_b128 v[204:207], v153 offset:20480
	ds_read_b128 v[208:211], v153 offset:21504
	ds_read_b128 v[212:215], v153 offset:22528
	ds_read_b128 v[216:219], v153 offset:23552
	global_load_lds_dwordx4 v[146:147], off
	s_add_i32 m0, s79, 0x2000
	s_add_u32 s80, s54, 0x400000
	v_lshl_add_u64 v[220:221], s[54:55], 0, v[128:129]
	s_addc_u32 s81, s55, 0
	s_add_i32 s79, s60, s14
	global_load_lds_dwordx4 v[220:221], off
	v_lshl_add_u64 v[222:223], s[80:81], 0, v[132:133]
	s_mov_b32 m0, s79
	v_lshl_add_u64 v[224:225], s[56:57], 0, v[130:131]
	global_load_lds_dwordx4 v[222:223], off
	v_lshl_add_u64 v[222:223], s[80:81], 0, v[128:129]
	s_add_i32 m0, s79, 0x2000
	s_nop 0
	global_load_lds_dwordx4 v[222:223], off
	v_lshl_add_u64 v[222:223], s[56:57], 0, v[134:135]
	s_mov_b32 m0, s15
	s_nop 0
	global_load_lds_dwordx4 v[222:223], off
	s_mov_b32 m0, s0
	s_nop 0
	global_load_lds_dwordx4 v[224:225], off
	s_waitcnt vmcnt(8)
	s_waitcnt lgkmcnt(0)
	s_barrier
; #define PG8_STAGE(bufoff, gbase, voff) do { _Pragma("unroll") for (int _i = 0; _i < 2; ++_i) \
;         __builtin_amdgcn_global_load_lds((const unsigned*)((const char*)(gbase) + (voff)[_i]), (LAS unsigned*)(lds + (bufoff) + ldsw + _i * 8192), 16, 0, 0); } while (0)
; #define PG8_LDA(dst, b, h) do { _Pragma("unroll") for (int m = 0; m < 4; ++m) _Pragma("unroll") for (int k = 0; k < 2; ++k) dst[m][k] = *(const LAS bf16x8*)(lds + PG8_SA(b, h) + aoff + m * 2048 + k * 1024); } while (0)
; #define PG8_LDB(dst, b, h) do { _Pragma("unroll") for (int n = 0; n < 2; ++n) _Pragma("unroll") for (int k = 0; k < 2; ++k) dst[n][k] = *(const LAS bf16x8*)(lds + PG8_SB(b, h) + boff + n * 2048 + k * 1024); } while (0)
; #define PG8_MMA(ai, bj, At, Bt) do { __builtin_amdgcn_s_setprio(1); _Pragma("unroll") for (int m = 0; m < 4; ++m) _Pragma("unroll") for (int n = 0; n < 2; ++n) _Pragma("unroll") for (int k = 0; k < 2; ++k) \
;         acc[ai][bj][m][n] = __builtin_amdgcn_mfma_f32_16x16x32_bf16(Bt[n][k], At[m][k], acc[ai][bj][m][n], 0, 0, 0); __builtin_amdgcn_s_setprio(0); } while (0)
; #define PG8_WAIT_V(n) asm volatile("s_waitcnt vmcnt(" #n ")" ::: "memory")
; #define PG8_WAIT_L(n) asm volatile("s_waitcnt lgkmcnt(" #n ")" ::: "memory")
; #define PG8_BAR __builtin_amdgcn_s_barrier()
; #define PG8_SCHED __builtin_amdgcn_sched_barrier(0)
; template <class Epi, class Sched>
; __device__ __forceinline__ void gemm_phase(LAS unsigned char* lds, const int K, const int lda, const int ldb, const Sched& S, const Epi& E) {
;     ...
;             PG8_WAIT_V(8); PG8_WAIT_L(0); PG8_BAR; PG8_MMA(1, 0, At, B0); PG8_MMA(1, 1, At, B1); PG8_BAR; PG8_SCHED;
;             PG8_LDB(B0, 1, 0); PG8_LDB(B1, 1, 1); PG8_SCHED; PG8_LDA(At, 1, 0); PG8_STAGE(PG8_SA(0, 1), a2 + hA, voffA);
;             PG8_WAIT_V(8); PG8_WAIT_L(0); PG8_BAR; PG8_MMA(0, 0, At, B0); PG8_MMA(0, 1, At, B1); PG8_BAR; PG8_SCHED;
	s_waitcnt lgkmcnt(0)
	v_mfma_f32_16x16x32_bf16 v[60:63], v[156:159], v[188:191], v[60:63]
	v_mfma_f32_16x16x32_bf16 v[56:59], v[164:167], v[188:191], v[56:59]
	v_mfma_f32_16x16x32_bf16 v[44:47], v[156:159], v[196:199], v[44:47]
	v_mfma_f32_16x16x32_bf16 v[40:43], v[164:167], v[196:199], v[40:43]
	v_mfma_f32_16x16x32_bf16 v[28:31], v[156:159], v[204:207], v[28:31]
	v_mfma_f32_16x16x32_bf16 v[24:27], v[164:167], v[204:207], v[24:27]
	v_mfma_f32_16x16x32_bf16 v[12:15], v[156:159], v[212:215], v[12:15]
	v_mfma_f32_16x16x32_bf16 v[8:11], v[164:167], v[212:215], v[8:11]
	v_mfma_f32_16x16x32_bf16 v[60:63], v[160:163], v[192:195], v[60:63]
	v_mfma_f32_16x16x32_bf16 v[56:59], v[168:171], v[192:195], v[56:59]
	v_mfma_f32_16x16x32_bf16 v[44:47], v[160:163], v[200:203], v[44:47]
	v_mfma_f32_16x16x32_bf16 v[40:43], v[168:171], v[200:203], v[40:43]
	v_mfma_f32_16x16x32_bf16 v[28:31], v[160:163], v[208:211], v[28:31]
	v_mfma_f32_16x16x32_bf16 v[24:27], v[168:171], v[208:211], v[24:27]
	v_mfma_f32_16x16x32_bf16 v[12:15], v[160:163], v[216:219], v[12:15]
	v_mfma_f32_16x16x32_bf16 v[8:11], v[168:171], v[216:219], v[8:11]
	v_mfma_f32_16x16x32_bf16 v[52:55], v[172:175], v[188:191], v[52:55]
	v_mfma_f32_16x16x32_bf16 v[48:51], v[180:183], v[188:191], v[48:51]
	v_mfma_f32_16x16x32_bf16 v[36:39], v[172:175], v[196:199], v[36:39]
	v_mfma_f32_16x16x32_bf16 v[32:35], v[180:183], v[196:199], v[32:35]
	v_mfma_f32_16x16x32_bf16 v[20:23], v[172:175], v[204:207], v[20:23]
	v_mfma_f32_16x16x32_bf16 v[16:19], v[180:183], v[204:207], v[16:19]
	v_mfma_f32_16x16x32_bf16 v[4:7], v[172:175], v[212:215], v[4:7]
	v_mfma_f32_16x16x32_bf16 v[0:3], v[180:183], v[212:215], v[0:3]
	v_mfma_f32_16x16x32_bf16 v[52:55], v[176:179], v[192:195], v[52:55]
	v_mfma_f32_16x16x32_bf16 v[48:51], v[184:187], v[192:195], v[48:51]
	v_mfma_f32_16x16x32_bf16 v[36:39], v[176:179], v[200:203], v[36:39]
	v_mfma_f32_16x16x32_bf16 v[32:35], v[184:187], v[200:203], v[32:35]
	v_mfma_f32_16x16x32_bf16 v[20:23], v[176:179], v[208:211], v[20:23]
	v_mfma_f32_16x16x32_bf16 v[16:19], v[184:187], v[208:211], v[16:19]
	v_mfma_f32_16x16x32_bf16 v[4:7], v[176:179], v[216:219], v[4:7]
	v_mfma_f32_16x16x32_bf16 v[0:3], v[184:187], v[216:219], v[0:3]
	s_barrier
	s_add_i32 s79, 0, 0x18000
	v_add_u32_e32 v136, s79, v149
	s_add_i32 s80, 0, 0x1c000
	ds_read_b128 v[156:159], v136
	ds_read_b128 v[160:163], v136 offset:1024
	ds_read_b128 v[164:167], v136 offset:2048
	ds_read_b128 v[168:171], v136 offset:3072
	v_add_u32_e32 v136, s80, v149
	ds_read_b128 v[172:175], v136
	ds_read_b128 v[176:179], v136 offset:1024
	ds_read_b128 v[180:183], v136 offset:2048
	ds_read_b128 v[184:187], v136 offset:3072
	s_add_u32 s56, s56, 0x200000
	s_addc_u32 s57, s57, 0
	s_mov_b32 m0, s30
	v_lshl_add_u64 v[226:227], s[56:57], 0, v[134:135]
	ds_read_b128 v[188:191], v153 offset:32768
	ds_read_b128 v[192:195], v153 offset:33792
	ds_read_b128 v[196:199], v153 offset:34816
	ds_read_b128 v[200:203], v153 offset:35840
	ds_read_b128 v[204:207], v153 offset:36864
	ds_read_b128 v[208:211], v153 offset:37888
	ds_read_b128 v[212:215], v153 offset:38912
	ds_read_b128 v[216:219], v153 offset:39936
	global_load_lds_dwordx4 v[226:227], off
	v_lshl_add_u64 v[226:227], s[56:57], 0, v[130:131]
	s_mov_b32 m0, s31
	s_nop 0
	global_load_lds_dwordx4 v[226:227], off
	s_waitcnt vmcnt(8)
	s_waitcnt lgkmcnt(0)
	s_barrier
	s_waitcnt lgkmcnt(0)
	v_mfma_f32_16x16x32_bf16 v[124:127], v[156:159], v[188:191], v[124:127]
	v_mfma_f32_16x16x32_bf16 v[120:123], v[164:167], v[188:191], v[120:123]
	v_mfma_f32_16x16x32_bf16 v[108:111], v[156:159], v[196:199], v[108:111]
	v_mfma_f32_16x16x32_bf16 v[104:107], v[164:167], v[196:199], v[104:107]
	v_mfma_f32_16x16x32_bf16 v[92:95], v[156:159], v[204:207], v[92:95]
	v_mfma_f32_16x16x32_bf16 v[88:91], v[164:167], v[204:207], v[88:91]
	v_mfma_f32_16x16x32_bf16 v[76:79], v[156:159], v[212:215], v[76:79]
	v_mfma_f32_16x16x32_bf16 v[72:75], v[164:167], v[212:215], v[72:75]
	v_mfma_f32_16x16x32_bf16 v[124:127], v[160:163], v[192:195], v[124:127]
	v_mfma_f32_16x16x32_bf16 v[120:123], v[168:171], v[192:195], v[120:123]
	v_mfma_f32_16x16x32_bf16 v[108:111], v[160:163], v[200:203], v[108:111]
	v_mfma_f32_16x16x32_bf16 v[104:107], v[168:171], v[200:203], v[104:107]
	v_mfma_f32_16x16x32_bf16 v[92:95], v[160:163], v[208:211], v[92:95]
	v_mfma_f32_16x16x32_bf16 v[88:91], v[168:171], v[208:211], v[88:91]
	v_mfma_f32_16x16x32_bf16 v[76:79], v[160:163], v[216:219], v[76:79]
	v_mfma_f32_16x16x32_bf16 v[72:75], v[168:171], v[216:219], v[72:75]
	v_mfma_f32_16x16x32_bf16 v[116:119], v[172:175], v[188:191], v[116:119]
	v_mfma_f32_16x16x32_bf16 v[112:115], v[180:183], v[188:191], v[112:115]
	v_mfma_f32_16x16x32_bf16 v[100:103], v[172:175], v[196:199], v[100:103]
	v_mfma_f32_16x16x32_bf16 v[96:99], v[180:183], v[196:199], v[96:99]
	v_mfma_f32_16x16x32_bf16 v[84:87], v[172:175], v[204:207], v[84:87]
	v_mfma_f32_16x16x32_bf16 v[80:83], v[180:183], v[204:207], v[80:83]
	v_mfma_f32_16x16x32_bf16 v[68:71], v[172:175], v[212:215], v[68:71]
	v_mfma_f32_16x16x32_bf16 v[64:67], v[180:183], v[212:215], v[64:67]
	v_mfma_f32_16x16x32_bf16 v[116:119], v[176:179], v[192:195], v[116:119]
	v_mfma_f32_16x16x32_bf16 v[112:115], v[184:187], v[192:195], v[112:115]
	v_mfma_f32_16x16x32_bf16 v[100:103], v[176:179], v[200:203], v[100:103]
	v_mfma_f32_16x16x32_bf16 v[96:99], v[184:187], v[200:203], v[96:99]
	v_mfma_f32_16x16x32_bf16 v[84:87], v[176:179], v[208:211], v[84:87]
	v_mfma_f32_16x16x32_bf16 v[80:83], v[184:187], v[208:211], v[80:83]
	v_mfma_f32_16x16x32_bf16 v[68:71], v[176:179], v[216:219], v[68:71]
	v_mfma_f32_16x16x32_bf16 v[64:67], v[184:187], v[216:219], v[64:67]
	s_barrier
; #define PG8_STAGE(bufoff, gbase, voff) do { _Pragma("unroll") for (int _i = 0; _i < 2; ++_i) \
;         __builtin_amdgcn_global_load_lds((const unsigned*)((const char*)(gbase) + (voff)[_i]), (LAS unsigned*)(lds + (bufoff) + ldsw + _i * 8192), 16, 0, 0); } while (0)
; #define PG8_LDA(dst, b, h) do { _Pragma("unroll") for (int m = 0; m < 4; ++m) _Pragma("unroll") for (int k = 0; k < 2; ++k) dst[m][k] = *(const LAS bf16x8*)(lds + PG8_SA(b, h) + aoff + m * 2048 + k * 1024); } while (0)
; #define PG8_MMA(ai, bj, At, Bt) do { __builtin_amdgcn_s_setprio(1); _Pragma("unroll") for (int m = 0; m < 4; ++m) _Pragma("unroll") for (int n = 0; n < 2; ++n) _Pragma("unroll") for (int k = 0; k < 2; ++k) \
;         acc[ai][bj][m][n] = __builtin_amdgcn_mfma_f32_16x16x32_bf16(Bt[n][k], At[m][k], acc[ai][bj][m][n], 0, 0, 0); __builtin_amdgcn_s_setprio(0); } while (0)
; #define PG8_WAIT_V(n) asm volatile("s_waitcnt vmcnt(" #n ")" ::: "memory")
; #define PG8_WAIT_L(n) asm volatile("s_waitcnt lgkmcnt(" #n ")" ::: "memory")
; #define PG8_BAR __builtin_amdgcn_s_barrier()
; #define PG8_SCHED __builtin_amdgcn_sched_barrier(0)
; template <class Epi, class Sched>
; __device__ __forceinline__ void gemm_phase(LAS unsigned char* lds, const int K, const int lda, const int ldb, const Sched& S, const Epi& E) {
;     ...
;             PG8_LDA(At, 1, 1); PG8_STAGE(PG8_SB(1, 0), b3, voffB); PG8_STAGE(PG8_SB(1, 1), b3 + hB, voffB); PG8_STAGE(PG8_SA(1, 0), a3, voffA);
;             PG8_WAIT_V(8); PG8_WAIT_L(0); PG8_BAR; PG8_MMA(1, 0, At, B0); PG8_MMA(1, 1, At, B1); PG8_BAR; PG8_SCHED;
;         }
;         if (wr == 0) PG8_BAR;
	s_add_i32 s56, s79, s14
	v_lshl_add_u64 v[146:147], v[146:147], 0, s[20:21]
	s_mov_b32 m0, s56
	ds_read_b128 v[188:191], v153 offset:49152
	ds_read_b128 v[192:195], v153 offset:50176
	ds_read_b128 v[196:199], v153 offset:51200
	ds_read_b128 v[200:203], v153 offset:52224
	ds_read_b128 v[204:207], v153 offset:53248
	ds_read_b128 v[208:211], v153 offset:54272
	ds_read_b128 v[212:215], v153 offset:55296
	ds_read_b128 v[216:219], v153 offset:56320
	global_load_lds_dwordx4 v[146:147], off
	s_add_i32 m0, s56, 0x2000
	s_add_u32 s54, s54, 0x400080
	v_lshl_add_u64 v[146:147], v[220:221], 0, s[20:21]
	s_addc_u32 s55, s55, 0
	s_add_i32 s56, s80, s14
	global_load_lds_dwordx4 v[146:147], off
	v_lshl_add_u64 v[146:147], s[54:55], 0, v[132:133]
	s_mov_b32 m0, s56
	s_nop 0
	global_load_lds_dwordx4 v[146:147], off
	v_lshl_add_u64 v[146:147], s[54:55], 0, v[128:129]
	s_add_i32 m0, s56, 0x2000
	s_nop 0
	global_load_lds_dwordx4 v[146:147], off
	v_lshl_add_u64 v[146:147], v[222:223], 0, s[20:21]
	s_mov_b32 m0, s38
	s_nop 0
	global_load_lds_dwordx4 v[146:147], off
	v_lshl_add_u64 v[146:147], v[224:225], 0, s[20:21]
	s_mov_b32 m0, s39
	s_nop 0
	global_load_lds_dwordx4 v[146:147], off
	s_waitcnt vmcnt(8)
	s_waitcnt lgkmcnt(0)
	s_barrier
	s_waitcnt lgkmcnt(0)
	v_mfma_f32_16x16x32_bf16 v[60:63], v[156:159], v[188:191], v[60:63]
	v_mfma_f32_16x16x32_bf16 v[56:59], v[164:167], v[188:191], v[56:59]
	v_mfma_f32_16x16x32_bf16 v[44:47], v[156:159], v[196:199], v[44:47]
	v_mfma_f32_16x16x32_bf16 v[40:43], v[164:167], v[196:199], v[40:43]
	v_mfma_f32_16x16x32_bf16 v[28:31], v[156:159], v[204:207], v[28:31]
	v_mfma_f32_16x16x32_bf16 v[24:27], v[164:167], v[204:207], v[24:27]
	v_mfma_f32_16x16x32_bf16 v[12:15], v[156:159], v[212:215], v[12:15]
	v_mfma_f32_16x16x32_bf16 v[8:11], v[164:167], v[212:215], v[8:11]
	v_mfma_f32_16x16x32_bf16 v[60:63], v[160:163], v[192:195], v[60:63]
	v_mfma_f32_16x16x32_bf16 v[56:59], v[168:171], v[192:195], v[56:59]
	v_mfma_f32_16x16x32_bf16 v[44:47], v[160:163], v[200:203], v[44:47]
	v_mfma_f32_16x16x32_bf16 v[40:43], v[168:171], v[200:203], v[40:43]
	v_mfma_f32_16x16x32_bf16 v[28:31], v[160:163], v[208:211], v[28:31]
	v_mfma_f32_16x16x32_bf16 v[24:27], v[168:171], v[208:211], v[24:27]
	v_mfma_f32_16x16x32_bf16 v[12:15], v[160:163], v[216:219], v[12:15]
	v_mfma_f32_16x16x32_bf16 v[8:11], v[168:171], v[216:219], v[8:11]
	v_mfma_f32_16x16x32_bf16 v[52:55], v[172:175], v[188:191], v[52:55]
	v_mfma_f32_16x16x32_bf16 v[48:51], v[180:183], v[188:191], v[48:51]
	v_mfma_f32_16x16x32_bf16 v[36:39], v[172:175], v[196:199], v[36:39]
	v_mfma_f32_16x16x32_bf16 v[32:35], v[180:183], v[196:199], v[32:35]
	v_mfma_f32_16x16x32_bf16 v[20:23], v[172:175], v[204:207], v[20:23]
	v_mfma_f32_16x16x32_bf16 v[16:19], v[180:183], v[204:207], v[16:19]
	v_mfma_f32_16x16x32_bf16 v[4:7], v[172:175], v[212:215], v[4:7]
	v_mfma_f32_16x16x32_bf16 v[0:3], v[180:183], v[212:215], v[0:3]
	v_mfma_f32_16x16x32_bf16 v[52:55], v[176:179], v[192:195], v[52:55]
	v_mfma_f32_16x16x32_bf16 v[48:51], v[184:187], v[192:195], v[48:51]
	v_mfma_f32_16x16x32_bf16 v[36:39], v[176:179], v[200:203], v[36:39]
	v_mfma_f32_16x16x32_bf16 v[32:35], v[184:187], v[200:203], v[32:35]
	v_mfma_f32_16x16x32_bf16 v[20:23], v[176:179], v[208:211], v[20:23]
	v_mfma_f32_16x16x32_bf16 v[16:19], v[184:187], v[208:211], v[16:19]
	v_mfma_f32_16x16x32_bf16 v[4:7], v[176:179], v[216:219], v[4:7]
	v_mfma_f32_16x16x32_bf16 v[0:3], v[184:187], v[216:219], v[0:3]
	s_barrier
	s_add_i32 s78, s78, 2
	s_add_u32 s23, s23, 0x100
	s_addc_u32 s51, s51, 0
	s_add_u32 s12, s12, 0x100
	s_addc_u32 s13, s13, 0
	s_cmp_gt_u32 s78, 13
	s_cbranch_scc0 .LBB0_1230
	s_and_b64 vcc, exec, s[24:25]
	s_cbranch_vccz .LBB0_1233
	s_barrier

; #define PG8_STAGE(bufoff, gbase, voff) do { _Pragma("unroll") for (int _i = 0; _i < 2; ++_i) \
;         __builtin_amdgcn_global_load_lds((const unsigned*)((const char*)(gbase) + (voff)[_i]), (LAS unsigned*)(lds + (bufoff) + ldsw + _i * 8192), 16, 0, 0); } while (0)
; #define PG8_LDA(dst, b, h) do { _Pragma("unroll") for (int m = 0; m < 4; ++m) _Pragma("unroll") for (int k = 0; k < 2; ++k) dst[m][k] = *(const LAS bf16x8*)(lds + PG8_SA(b, h) + aoff + m * 2048 + k * 1024); } while (0)
; #define PG8_LDB(dst, b, h) do { _Pragma("unroll") for (int n = 0; n < 2; ++n) _Pragma("unroll") for (int k = 0; k < 2; ++k) dst[n][k] = *(const LAS bf16x8*)(lds + PG8_SB(b, h) + boff + n * 2048 + k * 1024); } while (0)
; #define PG8_MMA(ai, bj, At, Bt) do { __builtin_amdgcn_s_setprio(1); _Pragma("unroll") for (int m = 0; m < 4; ++m) _Pragma("unroll") for (int n = 0; n < 2; ++n) _Pragma("unroll") for (int k = 0; k < 2; ++k) \
;         acc[ai][bj][m][n] = __builtin_amdgcn_mfma_f32_16x16x32_bf16(Bt[n][k], At[m][k], acc[ai][bj][m][n], 0, 0, 0); __builtin_amdgcn_s_setprio(0); } while (0)
; #define PG8_WAIT_V(n) asm volatile("s_waitcnt vmcnt(" #n ")" ::: "memory")
; #define PG8_WAIT_L(n) asm volatile("s_waitcnt lgkmcnt(" #n ")" ::: "memory")
; #define PG8_BAR __builtin_amdgcn_s_barrier()
; #define PG8_SCHED __builtin_amdgcn_sched_barrier(0)
; template <class Epi, class Sched>
; __device__ __forceinline__ void gemm_phase(LAS unsigned char* lds, const int K, const int lda, const int ldb, const Sched& S, const Epi& E) {
;     ...
;             PG8_LDB(B0, 0, 0); PG8_LDB(B1, 0, 1); PG8_SCHED; PG8_LDA(At, 0, 0); PG8_STAGE(PG8_SA(1, 1), a1 + hA, voffA);
;             PG8_WAIT_V(8); PG8_WAIT_L(0); PG8_BAR; PG8_MMA(0, 0, At, B0); PG8_MMA(0, 1, At, B1); PG8_BAR; PG8_SCHED;
;             PG8_LDA(At, 0, 1); PG8_STAGE(PG8_SB(0, 0), b2, voffB); PG8_STAGE(PG8_SB(0, 1), b2 + hB, voffB); PG8_STAGE(PG8_SA(0, 0), a2, voffA);
;             PG8_WAIT_V(8); PG8_WAIT_L(0); PG8_BAR; PG8_MMA(1, 0, At, B0); PG8_MMA(1, 1, At, B1); PG8_BAR; PG8_SCHED;
.LBB0_1372:
	ds_read_b128 v[104:107], v220
	ds_read_b128 v[112:115], v247
	ds_read_b128 v[124:127], v220 offset:2048
	ds_read_b128 v[140:143], v247 offset:2048
	ds_read_b128 v[144:147], v221
	ds_read_b128 v[148:151], v248
	ds_read_b128 v[152:155], v221 offset:2048
	ds_read_b128 v[156:159], v248 offset:2048
	s_add_u32 s51, s52, 0xfff80080
	s_addc_u32 s54, s53, -1
	s_cmp_eq_u32 s41, 28
	s_cselect_b32 s57, s17, s54
	s_cselect_b32 s56, s27, s51
	s_cselect_b32 s55, s25, s39
	s_cselect_b32 s54, s35, s38
	v_lshl_add_u64 v[208:209], s[52:53], 0, v[194:195]
	s_add_i32 m0, s2, 0xc000
	ds_read_b128 v[160:163], v222
	ds_read_b128 v[164:167], v246
	ds_read_b128 v[168:171], v222 offset:2048
	ds_read_b128 v[172:175], v246 offset:2048
	ds_read_b128 v[176:179], v222 offset:4096
	ds_read_b128 v[180:183], v246 offset:4096
	ds_read_b128 v[200:203], v222 offset:6144
	ds_read_b128 v[204:207], v246 offset:6144
	global_load_lds_dwordx4 v[208:209], off
	v_lshl_add_u64 v[208:209], s[52:53], 0, v[192:193]
	s_add_i32 m0, s2, 0xe000
	s_nop 0
	global_load_lds_dwordx4 v[208:209], off
	s_waitcnt vmcnt(8)
	s_waitcnt lgkmcnt(0)
	s_barrier
	s_waitcnt lgkmcnt(0)
	v_mfma_f32_16x16x32_bf16 v[136:139], v[160:163], v[104:107], v[136:139]
	v_mfma_f32_16x16x32_bf16 v[132:135], v[160:163], v[124:127], v[132:135]
	v_mfma_f32_16x16x32_bf16 v[116:119], v[168:171], v[104:107], v[116:119]
	v_mfma_f32_16x16x32_bf16 v[108:111], v[168:171], v[124:127], v[108:111]
	v_mfma_f32_16x16x32_bf16 v[92:95], v[176:179], v[104:107], v[92:95]
	v_mfma_f32_16x16x32_bf16 v[88:91], v[176:179], v[124:127], v[88:91]
	v_mfma_f32_16x16x32_bf16 v[76:79], v[200:203], v[104:107], v[76:79]
	v_mfma_f32_16x16x32_bf16 v[72:75], v[200:203], v[124:127], v[72:75]
	v_mfma_f32_16x16x32_bf16 v[136:139], v[164:167], v[112:115], v[136:139]
	v_mfma_f32_16x16x32_bf16 v[132:135], v[164:167], v[140:143], v[132:135]
	v_mfma_f32_16x16x32_bf16 v[116:119], v[172:175], v[112:115], v[116:119]
	v_mfma_f32_16x16x32_bf16 v[108:111], v[172:175], v[140:143], v[108:111]
	v_mfma_f32_16x16x32_bf16 v[92:95], v[180:183], v[112:115], v[92:95]
	v_mfma_f32_16x16x32_bf16 v[88:91], v[180:183], v[140:143], v[88:91]
	v_mfma_f32_16x16x32_bf16 v[76:79], v[204:207], v[112:115], v[76:79]
	v_mfma_f32_16x16x32_bf16 v[72:75], v[204:207], v[140:143], v[72:75]
	v_mfma_f32_16x16x32_bf16 v[128:131], v[160:163], v[144:147], v[128:131]
	v_mfma_f32_16x16x32_bf16 v[120:123], v[160:163], v[152:155], v[120:123]
	v_mfma_f32_16x16x32_bf16 v[100:103], v[168:171], v[144:147], v[100:103]
	v_mfma_f32_16x16x32_bf16 v[96:99], v[168:171], v[152:155], v[96:99]
	v_mfma_f32_16x16x32_bf16 v[84:87], v[176:179], v[144:147], v[84:87]
	v_mfma_f32_16x16x32_bf16 v[80:83], v[176:179], v[152:155], v[80:83]
	v_mfma_f32_16x16x32_bf16 v[68:71], v[200:203], v[144:147], v[68:71]
	v_mfma_f32_16x16x32_bf16 v[64:67], v[200:203], v[152:155], v[64:67]
	v_mfma_f32_16x16x32_bf16 v[128:131], v[164:167], v[148:151], v[128:131]
	v_mfma_f32_16x16x32_bf16 v[120:123], v[164:167], v[156:159], v[120:123]
	v_mfma_f32_16x16x32_bf16 v[100:103], v[172:175], v[148:151], v[100:103]
	v_mfma_f32_16x16x32_bf16 v[96:99], v[172:175], v[156:159], v[96:99]
	v_mfma_f32_16x16x32_bf16 v[84:87], v[180:183], v[148:151], v[84:87]
	v_mfma_f32_16x16x32_bf16 v[80:83], v[180:183], v[156:159], v[80:83]
	v_mfma_f32_16x16x32_bf16 v[68:71], v[204:207], v[148:151], v[68:71]
	v_mfma_f32_16x16x32_bf16 v[64:67], v[204:207], v[156:159], v[64:67]
	s_barrier
	s_add_i32 s51, s0, s1
	v_lshl_add_u64 v[208:209], s[54:55], 0, v[186:187]
	s_mov_b32 m0, s51
	ds_read_b128 v[160:163], v222 offset:16384
	ds_read_b128 v[164:167], v246 offset:16384
	ds_read_b128 v[168:171], v222 offset:18432
	ds_read_b128 v[172:175], v246 offset:18432
	ds_read_b128 v[176:179], v222 offset:20480
	ds_read_b128 v[180:183], v246 offset:20480
	ds_read_b128 v[200:203], v222 offset:22528
	ds_read_b128 v[204:207], v246 offset:22528
	global_load_lds_dwordx4 v[208:209], off
	s_add_i32 m0, s51, 0x2000
	s_add_u32 s58, s54, 0x80000
	v_lshl_add_u64 v[210:211], s[54:55], 0, v[190:191]
	s_addc_u32 s59, s55, 0
	s_add_i32 s51, s34, s1
	global_load_lds_dwordx4 v[210:211], off
	v_lshl_add_u64 v[212:213], s[58:59], 0, v[186:187]
	s_mov_b32 m0, s51
	v_lshl_add_u64 v[214:215], s[56:57], 0, v[188:189]
	global_load_lds_dwordx4 v[212:213], off
	v_lshl_add_u64 v[212:213], s[58:59], 0, v[190:191]
	s_add_i32 m0, s51, 0x2000
	s_nop 0
	global_load_lds_dwordx4 v[212:213], off
	v_lshl_add_u64 v[212:213], s[56:57], 0, v[184:185]
	s_mov_b32 m0, s2
	s_nop 0
	global_load_lds_dwordx4 v[212:213], off
	s_mov_b32 m0, s4
	s_nop 0
	global_load_lds_dwordx4 v[214:215], off
	s_waitcnt vmcnt(8)
	s_waitcnt lgkmcnt(0)
	s_barrier
; #define PG8_STAGE(bufoff, gbase, voff) do { _Pragma("unroll") for (int _i = 0; _i < 2; ++_i) \
;         __builtin_amdgcn_global_load_lds((const unsigned*)((const char*)(gbase) + (voff)[_i]), (LAS unsigned*)(lds + (bufoff) + ldsw + _i * 8192), 16, 0, 0); } while (0)
; #define PG8_LDA(dst, b, h) do { _Pragma("unroll") for (int m = 0; m < 4; ++m) _Pragma("unroll") for (int k = 0; k < 2; ++k) dst[m][k] = *(const LAS bf16x8*)(lds + PG8_SA(b, h) + aoff + m * 2048 + k * 1024); } while (0)
; #define PG8_LDB(dst, b, h) do { _Pragma("unroll") for (int n = 0; n < 2; ++n) _Pragma("unroll") for (int k = 0; k < 2; ++k) dst[n][k] = *(const LAS bf16x8*)(lds + PG8_SB(b, h) + boff + n * 2048 + k * 1024); } while (0)
; #define PG8_MMA(ai, bj, At, Bt) do { __builtin_amdgcn_s_setprio(1); _Pragma("unroll") for (int m = 0; m < 4; ++m) _Pragma("unroll") for (int n = 0; n < 2; ++n) _Pragma("unroll") for (int k = 0; k < 2; ++k) \
;         acc[ai][bj][m][n] = __builtin_amdgcn_mfma_f32_16x16x32_bf16(Bt[n][k], At[m][k], acc[ai][bj][m][n], 0, 0, 0); __builtin_amdgcn_s_setprio(0); } while (0)
; #define PG8_WAIT_V(n) asm volatile("s_waitcnt vmcnt(" #n ")" ::: "memory")
; #define PG8_WAIT_L(n) asm volatile("s_waitcnt lgkmcnt(" #n ")" ::: "memory")
; #define PG8_BAR __builtin_amdgcn_s_barrier()
; #define PG8_SCHED __builtin_amdgcn_sched_barrier(0)
; template <class Epi, class Sched>
; __device__ __forceinline__ void gemm_phase(LAS unsigned char* lds, const int K, const int lda, const int ldb, const Sched& S, const Epi& E) {
;     ...
;             PG8_WAIT_V(8); PG8_WAIT_L(0); PG8_BAR; PG8_MMA(1, 0, At, B0); PG8_MMA(1, 1, At, B1); PG8_BAR; PG8_SCHED;
;             PG8_LDB(B0, 1, 0); PG8_LDB(B1, 1, 1); PG8_SCHED; PG8_LDA(At, 1, 0); PG8_STAGE(PG8_SA(0, 1), a2 + hA, voffA);
;             PG8_WAIT_V(8); PG8_WAIT_L(0); PG8_BAR; PG8_MMA(0, 0, At, B0); PG8_MMA(0, 1, At, B1); PG8_BAR; PG8_SCHED;
	s_waitcnt lgkmcnt(0)
	v_mfma_f32_16x16x32_bf16 v[60:63], v[160:163], v[104:107], v[60:63]
	v_mfma_f32_16x16x32_bf16 v[56:59], v[160:163], v[124:127], v[56:59]
	v_mfma_f32_16x16x32_bf16 v[44:47], v[168:171], v[104:107], v[44:47]
	v_mfma_f32_16x16x32_bf16 v[40:43], v[168:171], v[124:127], v[40:43]
	v_mfma_f32_16x16x32_bf16 v[28:31], v[176:179], v[104:107], v[28:31]
	v_mfma_f32_16x16x32_bf16 v[24:27], v[176:179], v[124:127], v[24:27]
	v_mfma_f32_16x16x32_bf16 v[12:15], v[200:203], v[104:107], v[12:15]
	v_mfma_f32_16x16x32_bf16 v[8:11], v[200:203], v[124:127], v[8:11]
	v_mfma_f32_16x16x32_bf16 v[60:63], v[164:167], v[112:115], v[60:63]
	v_mfma_f32_16x16x32_bf16 v[56:59], v[164:167], v[140:143], v[56:59]
	v_mfma_f32_16x16x32_bf16 v[44:47], v[172:175], v[112:115], v[44:47]
	v_mfma_f32_16x16x32_bf16 v[40:43], v[172:175], v[140:143], v[40:43]
	v_mfma_f32_16x16x32_bf16 v[28:31], v[180:183], v[112:115], v[28:31]
	v_mfma_f32_16x16x32_bf16 v[24:27], v[180:183], v[140:143], v[24:27]
	v_mfma_f32_16x16x32_bf16 v[12:15], v[204:207], v[112:115], v[12:15]
	v_mfma_f32_16x16x32_bf16 v[8:11], v[204:207], v[140:143], v[8:11]
	v_mfma_f32_16x16x32_bf16 v[52:55], v[160:163], v[144:147], v[52:55]
	v_mfma_f32_16x16x32_bf16 v[48:51], v[160:163], v[152:155], v[48:51]
	v_mfma_f32_16x16x32_bf16 v[36:39], v[168:171], v[144:147], v[36:39]
	v_mfma_f32_16x16x32_bf16 v[32:35], v[168:171], v[152:155], v[32:35]
	v_mfma_f32_16x16x32_bf16 v[20:23], v[176:179], v[144:147], v[20:23]
	v_mfma_f32_16x16x32_bf16 v[16:19], v[176:179], v[152:155], v[16:19]
	v_mfma_f32_16x16x32_bf16 v[4:7], v[200:203], v[144:147], v[4:7]
	v_mfma_f32_16x16x32_bf16 v[0:3], v[200:203], v[152:155], v[0:3]
	v_mfma_f32_16x16x32_bf16 v[52:55], v[164:167], v[148:151], v[52:55]
	v_mfma_f32_16x16x32_bf16 v[48:51], v[164:167], v[156:159], v[48:51]
	v_mfma_f32_16x16x32_bf16 v[36:39], v[172:175], v[148:151], v[36:39]
	v_mfma_f32_16x16x32_bf16 v[32:35], v[172:175], v[156:159], v[32:35]
	v_mfma_f32_16x16x32_bf16 v[20:23], v[180:183], v[148:151], v[20:23]
	v_mfma_f32_16x16x32_bf16 v[16:19], v[180:183], v[156:159], v[16:19]
	v_mfma_f32_16x16x32_bf16 v[4:7], v[204:207], v[148:151], v[4:7]
	v_mfma_f32_16x16x32_bf16 v[0:3], v[204:207], v[156:159], v[0:3]
	s_barrier
	s_add_i32 s51, 0, 0x18000
	s_add_i32 s58, 0, 0x1c000
	v_add_u32_e32 v140, s51, v217
	v_add_u32_e32 v250, s51, v249
	v_add_u32_e32 v156, 0x19000, v217
	v_add_u32_e32 v251, 0x19000, v249
	ds_read_b128 v[104:107], v140
	ds_read_b128 v[112:115], v250
	ds_read_b128 v[124:127], v140 offset:2048
	ds_read_b128 v[140:143], v250 offset:2048
	ds_read_b128 v[144:147], v156
	ds_read_b128 v[148:151], v251
	ds_read_b128 v[152:155], v156 offset:2048
	ds_read_b128 v[156:159], v251 offset:2048
	s_add_u32 s56, s56, 0x80000
	s_addc_u32 s57, s57, 0
	s_mov_b32 m0, s5
	v_lshl_add_u64 v[226:227], s[56:57], 0, v[184:185]
	ds_read_b128 v[160:163], v222 offset:32768
	ds_read_b128 v[164:167], v246 offset:32768
	ds_read_b128 v[168:171], v222 offset:34816
	ds_read_b128 v[172:175], v246 offset:34816
	ds_read_b128 v[176:179], v222 offset:36864
	ds_read_b128 v[180:183], v246 offset:36864
	ds_read_b128 v[200:203], v222 offset:38912
	ds_read_b128 v[204:207], v246 offset:38912
	global_load_lds_dwordx4 v[226:227], off
	v_lshl_add_u64 v[226:227], s[56:57], 0, v[188:189]
	s_mov_b32 m0, s6
	s_nop 0
	global_load_lds_dwordx4 v[226:227], off
	s_waitcnt vmcnt(8)
	s_waitcnt lgkmcnt(0)
	s_barrier
	s_waitcnt lgkmcnt(0)
	v_mfma_f32_16x16x32_bf16 v[136:139], v[160:163], v[104:107], v[136:139]
	v_mfma_f32_16x16x32_bf16 v[132:135], v[160:163], v[124:127], v[132:135]
	v_mfma_f32_16x16x32_bf16 v[116:119], v[168:171], v[104:107], v[116:119]
	v_mfma_f32_16x16x32_bf16 v[108:111], v[168:171], v[124:127], v[108:111]
	v_mfma_f32_16x16x32_bf16 v[92:95], v[176:179], v[104:107], v[92:95]
	v_mfma_f32_16x16x32_bf16 v[88:91], v[176:179], v[124:127], v[88:91]
	v_mfma_f32_16x16x32_bf16 v[76:79], v[200:203], v[104:107], v[76:79]
	v_mfma_f32_16x16x32_bf16 v[72:75], v[200:203], v[124:127], v[72:75]
	v_mfma_f32_16x16x32_bf16 v[136:139], v[164:167], v[112:115], v[136:139]
	v_mfma_f32_16x16x32_bf16 v[132:135], v[164:167], v[140:143], v[132:135]
	v_mfma_f32_16x16x32_bf16 v[116:119], v[172:175], v[112:115], v[116:119]
	v_mfma_f32_16x16x32_bf16 v[108:111], v[172:175], v[140:143], v[108:111]
	v_mfma_f32_16x16x32_bf16 v[92:95], v[180:183], v[112:115], v[92:95]
	v_mfma_f32_16x16x32_bf16 v[88:91], v[180:183], v[140:143], v[88:91]
	v_mfma_f32_16x16x32_bf16 v[76:79], v[204:207], v[112:115], v[76:79]
	v_mfma_f32_16x16x32_bf16 v[72:75], v[204:207], v[140:143], v[72:75]
	v_mfma_f32_16x16x32_bf16 v[128:131], v[160:163], v[144:147], v[128:131]
	v_mfma_f32_16x16x32_bf16 v[120:123], v[160:163], v[152:155], v[120:123]
	v_mfma_f32_16x16x32_bf16 v[100:103], v[168:171], v[144:147], v[100:103]
	v_mfma_f32_16x16x32_bf16 v[96:99], v[168:171], v[152:155], v[96:99]
	v_mfma_f32_16x16x32_bf16 v[84:87], v[176:179], v[144:147], v[84:87]
	v_mfma_f32_16x16x32_bf16 v[80:83], v[176:179], v[152:155], v[80:83]
	v_mfma_f32_16x16x32_bf16 v[68:71], v[200:203], v[144:147], v[68:71]
	v_mfma_f32_16x16x32_bf16 v[64:67], v[200:203], v[152:155], v[64:67]
	v_mfma_f32_16x16x32_bf16 v[128:131], v[164:167], v[148:151], v[128:131]
	v_mfma_f32_16x16x32_bf16 v[120:123], v[164:167], v[156:159], v[120:123]
	v_mfma_f32_16x16x32_bf16 v[100:103], v[172:175], v[148:151], v[100:103]
	v_mfma_f32_16x16x32_bf16 v[96:99], v[172:175], v[156:159], v[96:99]
	v_mfma_f32_16x16x32_bf16 v[84:87], v[180:183], v[148:151], v[84:87]
	v_mfma_f32_16x16x32_bf16 v[80:83], v[180:183], v[156:159], v[80:83]
	v_mfma_f32_16x16x32_bf16 v[68:71], v[204:207], v[148:151], v[68:71]
	v_mfma_f32_16x16x32_bf16 v[64:67], v[204:207], v[156:159], v[64:67]
	s_barrier
; #define PG8_STAGE(bufoff, gbase, voff) do { _Pragma("unroll") for (int _i = 0; _i < 2; ++_i) \
;         __builtin_amdgcn_global_load_lds((const unsigned*)((const char*)(gbase) + (voff)[_i]), (LAS unsigned*)(lds + (bufoff) + ldsw + _i * 8192), 16, 0, 0); } while (0)
; #define PG8_LDA(dst, b, h) do { _Pragma("unroll") for (int m = 0; m < 4; ++m) _Pragma("unroll") for (int k = 0; k < 2; ++k) dst[m][k] = *(const LAS bf16x8*)(lds + PG8_SA(b, h) + aoff + m * 2048 + k * 1024); } while (0)
; #define PG8_MMA(ai, bj, At, Bt) do { __builtin_amdgcn_s_setprio(1); _Pragma("unroll") for (int m = 0; m < 4; ++m) _Pragma("unroll") for (int n = 0; n < 2; ++n) _Pragma("unroll") for (int k = 0; k < 2; ++k) \
;         acc[ai][bj][m][n] = __builtin_amdgcn_mfma_f32_16x16x32_bf16(Bt[n][k], At[m][k], acc[ai][bj][m][n], 0, 0, 0); __builtin_amdgcn_s_setprio(0); } while (0)
; #define PG8_WAIT_V(n) asm volatile("s_waitcnt vmcnt(" #n ")" ::: "memory")
; #define PG8_WAIT_L(n) asm volatile("s_waitcnt lgkmcnt(" #n ")" ::: "memory")
; #define PG8_BAR __builtin_amdgcn_s_barrier()
; #define PG8_SCHED __builtin_amdgcn_sched_barrier(0)
; template <class Epi, class Sched>
; __device__ __forceinline__ void gemm_phase(LAS unsigned char* lds, const int K, const int lda, const int ldb, const Sched& S, const Epi& E) {
;     ...
;             PG8_LDA(At, 1, 1); PG8_STAGE(PG8_SB(1, 0), b3, voffB); PG8_STAGE(PG8_SB(1, 1), b3 + hB, voffB); PG8_STAGE(PG8_SA(1, 0), a3, voffA);
;             PG8_WAIT_V(8); PG8_WAIT_L(0); PG8_BAR; PG8_MMA(1, 0, At, B0); PG8_MMA(1, 1, At, B1); PG8_BAR; PG8_SCHED;
;         }
;         if (wr == 0) PG8_BAR;
	s_add_i32 s51, s51, s1
	v_lshl_add_u64 v[208:209], v[208:209], 0, s[20:21]
	s_mov_b32 m0, s51
	ds_read_b128 v[160:163], v222 offset:49152
	ds_read_b128 v[164:167], v246 offset:49152
	ds_read_b128 v[168:171], v222 offset:51200
	ds_read_b128 v[172:175], v246 offset:51200
	ds_read_b128 v[176:179], v222 offset:53248
	ds_read_b128 v[180:183], v246 offset:53248
	ds_read_b128 v[200:203], v222 offset:55296
	ds_read_b128 v[204:207], v246 offset:55296
	global_load_lds_dwordx4 v[208:209], off
	s_add_i32 m0, s51, 0x2000
	s_add_u32 s54, s54, 0x80080
	v_lshl_add_u64 v[208:209], v[210:211], 0, s[20:21]
	s_addc_u32 s55, s55, 0
	s_add_i32 s51, s58, s1
	global_load_lds_dwordx4 v[208:209], off
	v_lshl_add_u64 v[208:209], s[54:55], 0, v[186:187]
	s_mov_b32 m0, s51
	s_nop 0
	global_load_lds_dwordx4 v[208:209], off
	v_lshl_add_u64 v[208:209], s[54:55], 0, v[190:191]
	s_add_i32 m0, s51, 0x2000
	s_nop 0
	global_load_lds_dwordx4 v[208:209], off
	v_lshl_add_u64 v[208:209], v[212:213], 0, s[20:21]
	s_mov_b32 m0, s14
	s_nop 0
	global_load_lds_dwordx4 v[208:209], off
	v_lshl_add_u64 v[208:209], v[214:215], 0, s[20:21]
	s_mov_b32 m0, s15
	s_nop 0
	global_load_lds_dwordx4 v[208:209], off
	s_waitcnt vmcnt(8)
	s_waitcnt lgkmcnt(0)
	s_barrier
	s_waitcnt lgkmcnt(0)
	v_mfma_f32_16x16x32_bf16 v[60:63], v[160:163], v[104:107], v[60:63]
	v_mfma_f32_16x16x32_bf16 v[56:59], v[160:163], v[124:127], v[56:59]
	v_mfma_f32_16x16x32_bf16 v[44:47], v[168:171], v[104:107], v[44:47]
	v_mfma_f32_16x16x32_bf16 v[40:43], v[168:171], v[124:127], v[40:43]
	v_mfma_f32_16x16x32_bf16 v[28:31], v[176:179], v[104:107], v[28:31]
	v_mfma_f32_16x16x32_bf16 v[24:27], v[176:179], v[124:127], v[24:27]
	v_mfma_f32_16x16x32_bf16 v[12:15], v[200:203], v[104:107], v[12:15]
	v_mfma_f32_16x16x32_bf16 v[8:11], v[200:203], v[124:127], v[8:11]
	v_mfma_f32_16x16x32_bf16 v[60:63], v[164:167], v[112:115], v[60:63]
	v_mfma_f32_16x16x32_bf16 v[56:59], v[164:167], v[140:143], v[56:59]
	v_mfma_f32_16x16x32_bf16 v[44:47], v[172:175], v[112:115], v[44:47]
	v_mfma_f32_16x16x32_bf16 v[40:43], v[172:175], v[140:143], v[40:43]
	v_mfma_f32_16x16x32_bf16 v[28:31], v[180:183], v[112:115], v[28:31]
	v_mfma_f32_16x16x32_bf16 v[24:27], v[180:183], v[140:143], v[24:27]
	v_mfma_f32_16x16x32_bf16 v[12:15], v[204:207], v[112:115], v[12:15]
	v_mfma_f32_16x16x32_bf16 v[8:11], v[204:207], v[140:143], v[8:11]
	v_mfma_f32_16x16x32_bf16 v[52:55], v[160:163], v[144:147], v[52:55]
	v_mfma_f32_16x16x32_bf16 v[48:51], v[160:163], v[152:155], v[48:51]
	v_mfma_f32_16x16x32_bf16 v[36:39], v[168:171], v[144:147], v[36:39]
	v_mfma_f32_16x16x32_bf16 v[32:35], v[168:171], v[152:155], v[32:35]
	v_mfma_f32_16x16x32_bf16 v[20:23], v[176:179], v[144:147], v[20:23]
	v_mfma_f32_16x16x32_bf16 v[16:19], v[176:179], v[152:155], v[16:19]
	v_mfma_f32_16x16x32_bf16 v[4:7], v[200:203], v[144:147], v[4:7]
	v_mfma_f32_16x16x32_bf16 v[0:3], v[200:203], v[152:155], v[0:3]
	v_mfma_f32_16x16x32_bf16 v[52:55], v[164:167], v[148:151], v[52:55]
	v_mfma_f32_16x16x32_bf16 v[48:51], v[164:167], v[156:159], v[48:51]
	v_mfma_f32_16x16x32_bf16 v[36:39], v[172:175], v[148:151], v[36:39]
	v_mfma_f32_16x16x32_bf16 v[32:35], v[172:175], v[156:159], v[32:35]
	v_mfma_f32_16x16x32_bf16 v[20:23], v[180:183], v[148:151], v[20:23]
	v_mfma_f32_16x16x32_bf16 v[16:19], v[180:183], v[156:159], v[16:19]
	v_mfma_f32_16x16x32_bf16 v[4:7], v[204:207], v[148:151], v[4:7]
	v_mfma_f32_16x16x32_bf16 v[0:3], v[204:207], v[156:159], v[0:3]
	s_barrier
	s_add_i32 s41, s41, 2
	s_add_u32 s38, s38, 0x100
	s_addc_u32 s39, s39, 0
	s_add_u32 s52, s52, 0x100
	s_addc_u32 s53, s53, 0
	s_cmp_gt_u32 s41, 29
	s_cbranch_scc0 .LBB0_1372
	s_and_b64 vcc, exec, s[22:23]
	s_cbranch_vccz .LBB0_1375
	s_barrier

; #define PG8_STAGE(bufoff, gbase, voff) do { _Pragma("unroll") for (int _i = 0; _i < 2; ++_i) \
;         __builtin_amdgcn_global_load_lds((const unsigned*)((const char*)(gbase) + (voff)[_i]), (LAS unsigned*)(lds + (bufoff) + ldsw + _i * 8192), 16, 0, 0); } while (0)
; #define PG8_LDA(dst, b, h) do { _Pragma("unroll") for (int m = 0; m < 4; ++m) _Pragma("unroll") for (int k = 0; k < 2; ++k) dst[m][k] = *(const LAS bf16x8*)(lds + PG8_SA(b, h) + aoff + m * 2048 + k * 1024); } while (0)
; #define PG8_LDB(dst, b, h) do { _Pragma("unroll") for (int n = 0; n < 2; ++n) _Pragma("unroll") for (int k = 0; k < 2; ++k) dst[n][k] = *(const LAS bf16x8*)(lds + PG8_SB(b, h) + boff + n * 2048 + k * 1024); } while (0)
; #define PG8_MMA(ai, bj, At, Bt) do { __builtin_amdgcn_s_setprio(1); _Pragma("unroll") for (int m = 0; m < 4; ++m) _Pragma("unroll") for (int n = 0; n < 2; ++n) _Pragma("unroll") for (int k = 0; k < 2; ++k) \
;         acc[ai][bj][m][n] = __builtin_amdgcn_mfma_f32_16x16x32_bf16(Bt[n][k], At[m][k], acc[ai][bj][m][n], 0, 0, 0); __builtin_amdgcn_s_setprio(0); } while (0)
; #define PG8_WAIT_V(n) asm volatile("s_waitcnt vmcnt(" #n ")" ::: "memory")
; #define PG8_WAIT_L(n) asm volatile("s_waitcnt lgkmcnt(" #n ")" ::: "memory")
; #define PG8_BAR __builtin_amdgcn_s_barrier()
; #define PG8_SCHED __builtin_amdgcn_sched_barrier(0)
; template <class Epi, class Sched>
; __device__ __forceinline__ void gemm_phase(LAS unsigned char* lds, const int K, const int lda, const int ldb, const Sched& S, const Epi& E) {
;     ...
;             PG8_LDB(B0, 0, 0); PG8_LDB(B1, 0, 1); PG8_SCHED; PG8_LDA(At, 0, 0); PG8_STAGE(PG8_SA(1, 1), a1 + hA, voffA);
;             PG8_WAIT_V(8); PG8_WAIT_L(0); PG8_BAR; PG8_MMA(0, 0, At, B0); PG8_MMA(0, 1, At, B1); PG8_BAR; PG8_SCHED;
;             PG8_LDA(At, 0, 1); PG8_STAGE(PG8_SB(0, 0), b2, voffB); PG8_STAGE(PG8_SB(0, 1), b2 + hB, voffB); PG8_STAGE(PG8_SA(0, 0), a2, voffA);
;             PG8_WAIT_V(8); PG8_WAIT_L(0); PG8_BAR; PG8_MMA(1, 0, At, B0); PG8_MMA(1, 1, At, B1); PG8_BAR; PG8_SCHED;
.LBB0_1448:
	s_waitcnt lgkmcnt(0)
	ds_read_b128 v[158:161], v235
	ds_read_b128 v[162:165], v249
	ds_read_b128 v[166:169], v235 offset:2048
	ds_read_b128 v[170:173], v249 offset:2048
	ds_read_b128 v[174:177], v236
	ds_read_b128 v[178:181], v250
	ds_read_b128 v[182:185], v236 offset:2048
	ds_read_b128 v[186:189], v250 offset:2048
	s_add_u32 s56, s52, 0xfff80080
	s_addc_u32 s57, s53, -1
	s_cmp_eq_u32 s55, 28
	s_cselect_b32 s59, s0, s57
	s_cselect_b32 s58, s1, s56
	s_cselect_b32 s57, s11, s47
	s_cselect_b32 s56, s41, s45
	v_lshl_add_u64 v[222:223], s[52:53], 0, v[148:149]
	s_add_i32 m0, s14, 0xc000
	ds_read_b128 v[190:193], v145
	ds_read_b128 v[194:197], v248
	ds_read_b128 v[198:201], v145 offset:2048
	ds_read_b128 v[202:205], v248 offset:2048
	ds_read_b128 v[206:209], v145 offset:4096
	ds_read_b128 v[210:213], v248 offset:4096
	ds_read_b128 v[214:217], v145 offset:6144
	ds_read_b128 v[218:221], v248 offset:6144
	global_load_lds_dwordx4 v[222:223], off
	v_lshl_add_u64 v[222:223], s[52:53], 0, v[146:147]
	s_add_i32 m0, s14, 0xe000
	s_nop 0
	global_load_lds_dwordx4 v[222:223], off
	s_waitcnt vmcnt(8)
	s_waitcnt lgkmcnt(0)
	s_barrier
	s_waitcnt lgkmcnt(0)
	v_mfma_f32_16x16x32_bf16 v[124:127], v[158:161], v[190:193], v[124:127]
	v_mfma_f32_16x16x32_bf16 v[116:119], v[166:169], v[190:193], v[116:119]
	v_mfma_f32_16x16x32_bf16 v[108:111], v[158:161], v[198:201], v[108:111]
	v_mfma_f32_16x16x32_bf16 v[100:103], v[166:169], v[198:201], v[100:103]
	v_mfma_f32_16x16x32_bf16 v[92:95], v[158:161], v[206:209], v[92:95]
	v_mfma_f32_16x16x32_bf16 v[84:87], v[166:169], v[206:209], v[84:87]
	v_mfma_f32_16x16x32_bf16 v[76:79], v[158:161], v[214:217], v[76:79]
	v_mfma_f32_16x16x32_bf16 v[68:71], v[166:169], v[214:217], v[68:71]
	v_mfma_f32_16x16x32_bf16 v[124:127], v[162:165], v[194:197], v[124:127]
	v_mfma_f32_16x16x32_bf16 v[116:119], v[170:173], v[194:197], v[116:119]
	v_mfma_f32_16x16x32_bf16 v[108:111], v[162:165], v[202:205], v[108:111]
	v_mfma_f32_16x16x32_bf16 v[100:103], v[170:173], v[202:205], v[100:103]
	v_mfma_f32_16x16x32_bf16 v[92:95], v[162:165], v[210:213], v[92:95]
	v_mfma_f32_16x16x32_bf16 v[84:87], v[170:173], v[210:213], v[84:87]
	v_mfma_f32_16x16x32_bf16 v[76:79], v[162:165], v[218:221], v[76:79]
	v_mfma_f32_16x16x32_bf16 v[68:71], v[170:173], v[218:221], v[68:71]
	v_mfma_f32_16x16x32_bf16 v[120:123], v[174:177], v[190:193], v[120:123]
	v_mfma_f32_16x16x32_bf16 v[112:115], v[182:185], v[190:193], v[112:115]
	v_mfma_f32_16x16x32_bf16 v[104:107], v[174:177], v[198:201], v[104:107]
	v_mfma_f32_16x16x32_bf16 v[96:99], v[182:185], v[198:201], v[96:99]
	v_mfma_f32_16x16x32_bf16 v[88:91], v[174:177], v[206:209], v[88:91]
	v_mfma_f32_16x16x32_bf16 v[80:83], v[182:185], v[206:209], v[80:83]
	v_mfma_f32_16x16x32_bf16 v[72:75], v[174:177], v[214:217], v[72:75]
	v_mfma_f32_16x16x32_bf16 v[64:67], v[182:185], v[214:217], v[64:67]
	v_mfma_f32_16x16x32_bf16 v[120:123], v[178:181], v[194:197], v[120:123]
	v_mfma_f32_16x16x32_bf16 v[112:115], v[186:189], v[194:197], v[112:115]
	v_mfma_f32_16x16x32_bf16 v[104:107], v[178:181], v[202:205], v[104:107]
	v_mfma_f32_16x16x32_bf16 v[96:99], v[186:189], v[202:205], v[96:99]
	v_mfma_f32_16x16x32_bf16 v[88:91], v[178:181], v[210:213], v[88:91]
	v_mfma_f32_16x16x32_bf16 v[80:83], v[186:189], v[210:213], v[80:83]
	v_mfma_f32_16x16x32_bf16 v[72:75], v[178:181], v[218:221], v[72:75]
	v_mfma_f32_16x16x32_bf16 v[64:67], v[186:189], v[218:221], v[64:67]
	s_barrier
	s_add_i32 s60, s72, s2
	v_lshl_add_u64 v[222:223], s[56:57], 0, v[130:131]
	s_mov_b32 m0, s60
	ds_read_b128 v[190:193], v145 offset:16384
	ds_read_b128 v[194:197], v248 offset:16384
	ds_read_b128 v[198:201], v145 offset:18432
	ds_read_b128 v[202:205], v248 offset:18432
	ds_read_b128 v[206:209], v145 offset:20480
	ds_read_b128 v[210:213], v248 offset:20480
	ds_read_b128 v[214:217], v145 offset:22528
	ds_read_b128 v[218:221], v248 offset:22528
	global_load_lds_dwordx4 v[222:223], off
	s_add_i32 m0, s60, 0x2000
	s_add_u32 s60, s56, 0x80000
	v_lshl_add_u64 v[224:225], s[56:57], 0, v[134:135]
	s_addc_u32 s61, s57, 0
	s_add_i32 s62, s73, s2
	global_load_lds_dwordx4 v[224:225], off
	v_lshl_add_u64 v[226:227], s[60:61], 0, v[130:131]
	s_mov_b32 m0, s62
	v_lshl_add_u64 v[228:229], s[58:59], 0, v[132:133]
	global_load_lds_dwordx4 v[226:227], off
	v_lshl_add_u64 v[226:227], s[60:61], 0, v[134:135]
	s_add_i32 m0, s62, 0x2000
	s_nop 0
	global_load_lds_dwordx4 v[226:227], off
	v_lshl_add_u64 v[226:227], s[58:59], 0, v[128:129]
	s_mov_b32 m0, s14
	s_nop 0
	global_load_lds_dwordx4 v[226:227], off
	s_mov_b32 m0, s15
	s_nop 0
	global_load_lds_dwordx4 v[228:229], off
	s_waitcnt vmcnt(8)
	s_waitcnt lgkmcnt(0)
	s_barrier
; #define PG8_STAGE(bufoff, gbase, voff) do { _Pragma("unroll") for (int _i = 0; _i < 2; ++_i) \
;         __builtin_amdgcn_global_load_lds((const unsigned*)((const char*)(gbase) + (voff)[_i]), (LAS unsigned*)(lds + (bufoff) + ldsw + _i * 8192), 16, 0, 0); } while (0)
; #define PG8_LDA(dst, b, h) do { _Pragma("unroll") for (int m = 0; m < 4; ++m) _Pragma("unroll") for (int k = 0; k < 2; ++k) dst[m][k] = *(const LAS bf16x8*)(lds + PG8_SA(b, h) + aoff + m * 2048 + k * 1024); } while (0)
; #define PG8_LDB(dst, b, h) do { _Pragma("unroll") for (int n = 0; n < 2; ++n) _Pragma("unroll") for (int k = 0; k < 2; ++k) dst[n][k] = *(const LAS bf16x8*)(lds + PG8_SB(b, h) + boff + n * 2048 + k * 1024); } while (0)
; #define PG8_MMA(ai, bj, At, Bt) do { __builtin_amdgcn_s_setprio(1); _Pragma("unroll") for (int m = 0; m < 4; ++m) _Pragma("unroll") for (int n = 0; n < 2; ++n) _Pragma("unroll") for (int k = 0; k < 2; ++k) \
;         acc[ai][bj][m][n] = __builtin_amdgcn_mfma_f32_16x16x32_bf16(Bt[n][k], At[m][k], acc[ai][bj][m][n], 0, 0, 0); __builtin_amdgcn_s_setprio(0); } while (0)
; #define PG8_WAIT_V(n) asm volatile("s_waitcnt vmcnt(" #n ")" ::: "memory")
; #define PG8_WAIT_L(n) asm volatile("s_waitcnt lgkmcnt(" #n ")" ::: "memory")
; #define PG8_BAR __builtin_amdgcn_s_barrier()
; #define PG8_SCHED __builtin_amdgcn_sched_barrier(0)
; template <class Epi, class Sched>
; __device__ __forceinline__ void gemm_phase(LAS unsigned char* lds, const int K, const int lda, const int ldb, const Sched& S, const Epi& E) {
;     ...
;             PG8_WAIT_V(8); PG8_WAIT_L(0); PG8_BAR; PG8_MMA(1, 0, At, B0); PG8_MMA(1, 1, At, B1); PG8_BAR; PG8_SCHED;
;             PG8_LDB(B0, 1, 0); PG8_LDB(B1, 1, 1); PG8_SCHED; PG8_LDA(At, 1, 0); PG8_STAGE(PG8_SA(0, 1), a2 + hA, voffA);
;             PG8_WAIT_V(8); PG8_WAIT_L(0); PG8_BAR; PG8_MMA(0, 0, At, B0); PG8_MMA(0, 1, At, B1); PG8_BAR; PG8_SCHED;
	s_waitcnt lgkmcnt(0)
	v_mfma_f32_16x16x32_bf16 v[60:63], v[158:161], v[190:193], v[60:63]
	v_mfma_f32_16x16x32_bf16 v[52:55], v[166:169], v[190:193], v[52:55]
	v_mfma_f32_16x16x32_bf16 v[44:47], v[158:161], v[198:201], v[44:47]
	v_mfma_f32_16x16x32_bf16 v[36:39], v[166:169], v[198:201], v[36:39]
	v_mfma_f32_16x16x32_bf16 v[28:31], v[158:161], v[206:209], v[28:31]
	v_mfma_f32_16x16x32_bf16 v[20:23], v[166:169], v[206:209], v[20:23]
	v_mfma_f32_16x16x32_bf16 v[12:15], v[158:161], v[214:217], v[12:15]
	v_mfma_f32_16x16x32_bf16 v[4:7], v[166:169], v[214:217], v[4:7]
	v_mfma_f32_16x16x32_bf16 v[60:63], v[162:165], v[194:197], v[60:63]
	v_mfma_f32_16x16x32_bf16 v[52:55], v[170:173], v[194:197], v[52:55]
	v_mfma_f32_16x16x32_bf16 v[44:47], v[162:165], v[202:205], v[44:47]
	v_mfma_f32_16x16x32_bf16 v[36:39], v[170:173], v[202:205], v[36:39]
	v_mfma_f32_16x16x32_bf16 v[28:31], v[162:165], v[210:213], v[28:31]
	v_mfma_f32_16x16x32_bf16 v[20:23], v[170:173], v[210:213], v[20:23]
	v_mfma_f32_16x16x32_bf16 v[12:15], v[162:165], v[218:221], v[12:15]
	v_mfma_f32_16x16x32_bf16 v[4:7], v[170:173], v[218:221], v[4:7]
	v_mfma_f32_16x16x32_bf16 v[56:59], v[174:177], v[190:193], v[56:59]
	v_mfma_f32_16x16x32_bf16 v[48:51], v[182:185], v[190:193], v[48:51]
	v_mfma_f32_16x16x32_bf16 v[40:43], v[174:177], v[198:201], v[40:43]
	v_mfma_f32_16x16x32_bf16 v[32:35], v[182:185], v[198:201], v[32:35]
	v_mfma_f32_16x16x32_bf16 v[24:27], v[174:177], v[206:209], v[24:27]
	v_mfma_f32_16x16x32_bf16 v[16:19], v[182:185], v[206:209], v[16:19]
	v_mfma_f32_16x16x32_bf16 v[8:11], v[174:177], v[214:217], v[8:11]
	v_mfma_f32_16x16x32_bf16 v[0:3], v[182:185], v[214:217], v[0:3]
	v_mfma_f32_16x16x32_bf16 v[56:59], v[178:181], v[194:197], v[56:59]
	v_mfma_f32_16x16x32_bf16 v[48:51], v[186:189], v[194:197], v[48:51]
	v_mfma_f32_16x16x32_bf16 v[40:43], v[178:181], v[202:205], v[40:43]
	v_mfma_f32_16x16x32_bf16 v[32:35], v[186:189], v[202:205], v[32:35]
	v_mfma_f32_16x16x32_bf16 v[24:27], v[178:181], v[210:213], v[24:27]
	v_mfma_f32_16x16x32_bf16 v[16:19], v[186:189], v[210:213], v[16:19]
	v_mfma_f32_16x16x32_bf16 v[8:11], v[178:181], v[218:221], v[8:11]
	v_mfma_f32_16x16x32_bf16 v[0:3], v[186:189], v[218:221], v[0:3]
	s_barrier
	s_add_i32 s60, 0, 0x18000
	v_add_u32_e32 v151, s60, v143
	v_add_u32_e32 v252, s60, v251
	s_add_i32 s61, 0, 0x1c000
	ds_read_b128 v[158:161], v151
	ds_read_b128 v[162:165], v252
	ds_read_b128 v[166:169], v151 offset:2048
	ds_read_b128 v[170:173], v252 offset:2048
	v_add_u32_e32 v151, s61, v143
	v_add_u32_e32 v252, s61, v251
	ds_read_b128 v[174:177], v151
	ds_read_b128 v[178:181], v252
	ds_read_b128 v[182:185], v151 offset:2048
	ds_read_b128 v[186:189], v252 offset:2048
	s_add_u32 s58, s58, 0x80000
	s_addc_u32 s59, s59, 0
	s_mov_b32 m0, s30
	v_lshl_add_u64 v[230:231], s[58:59], 0, v[128:129]
	ds_read_b128 v[190:193], v145 offset:32768
	ds_read_b128 v[194:197], v248 offset:32768
	ds_read_b128 v[198:201], v145 offset:34816
	ds_read_b128 v[202:205], v248 offset:34816
	ds_read_b128 v[206:209], v145 offset:36864
	ds_read_b128 v[210:213], v248 offset:36864
	ds_read_b128 v[214:217], v145 offset:38912
	ds_read_b128 v[218:221], v248 offset:38912
	global_load_lds_dwordx4 v[230:231], off
	v_lshl_add_u64 v[230:231], s[58:59], 0, v[132:133]
	s_mov_b32 m0, s31
	s_nop 0
	global_load_lds_dwordx4 v[230:231], off
	s_waitcnt vmcnt(8)
	s_waitcnt lgkmcnt(0)
	s_barrier
	s_waitcnt lgkmcnt(0)
	v_mfma_f32_16x16x32_bf16 v[124:127], v[158:161], v[190:193], v[124:127]
	v_mfma_f32_16x16x32_bf16 v[116:119], v[166:169], v[190:193], v[116:119]
	v_mfma_f32_16x16x32_bf16 v[108:111], v[158:161], v[198:201], v[108:111]
	v_mfma_f32_16x16x32_bf16 v[100:103], v[166:169], v[198:201], v[100:103]
	v_mfma_f32_16x16x32_bf16 v[92:95], v[158:161], v[206:209], v[92:95]
	v_mfma_f32_16x16x32_bf16 v[84:87], v[166:169], v[206:209], v[84:87]
	v_mfma_f32_16x16x32_bf16 v[76:79], v[158:161], v[214:217], v[76:79]
	v_mfma_f32_16x16x32_bf16 v[68:71], v[166:169], v[214:217], v[68:71]
	v_mfma_f32_16x16x32_bf16 v[124:127], v[162:165], v[194:197], v[124:127]
	v_mfma_f32_16x16x32_bf16 v[116:119], v[170:173], v[194:197], v[116:119]
	v_mfma_f32_16x16x32_bf16 v[108:111], v[162:165], v[202:205], v[108:111]
	v_mfma_f32_16x16x32_bf16 v[100:103], v[170:173], v[202:205], v[100:103]
	v_mfma_f32_16x16x32_bf16 v[92:95], v[162:165], v[210:213], v[92:95]
	v_mfma_f32_16x16x32_bf16 v[84:87], v[170:173], v[210:213], v[84:87]
	v_mfma_f32_16x16x32_bf16 v[76:79], v[162:165], v[218:221], v[76:79]
	v_mfma_f32_16x16x32_bf16 v[68:71], v[170:173], v[218:221], v[68:71]
	v_mfma_f32_16x16x32_bf16 v[120:123], v[174:177], v[190:193], v[120:123]
	v_mfma_f32_16x16x32_bf16 v[112:115], v[182:185], v[190:193], v[112:115]
	v_mfma_f32_16x16x32_bf16 v[104:107], v[174:177], v[198:201], v[104:107]
	v_mfma_f32_16x16x32_bf16 v[96:99], v[182:185], v[198:201], v[96:99]
	v_mfma_f32_16x16x32_bf16 v[88:91], v[174:177], v[206:209], v[88:91]
	v_mfma_f32_16x16x32_bf16 v[80:83], v[182:185], v[206:209], v[80:83]
	v_mfma_f32_16x16x32_bf16 v[72:75], v[174:177], v[214:217], v[72:75]
	v_mfma_f32_16x16x32_bf16 v[64:67], v[182:185], v[214:217], v[64:67]
	v_mfma_f32_16x16x32_bf16 v[120:123], v[178:181], v[194:197], v[120:123]
	v_mfma_f32_16x16x32_bf16 v[112:115], v[186:189], v[194:197], v[112:115]
	v_mfma_f32_16x16x32_bf16 v[104:107], v[178:181], v[202:205], v[104:107]
	v_mfma_f32_16x16x32_bf16 v[96:99], v[186:189], v[202:205], v[96:99]
	v_mfma_f32_16x16x32_bf16 v[88:91], v[178:181], v[210:213], v[88:91]
	v_mfma_f32_16x16x32_bf16 v[80:83], v[186:189], v[210:213], v[80:83]
	v_mfma_f32_16x16x32_bf16 v[72:75], v[178:181], v[218:221], v[72:75]
	v_mfma_f32_16x16x32_bf16 v[64:67], v[186:189], v[218:221], v[64:67]
	s_barrier
; #define PG8_STAGE(bufoff, gbase, voff) do { _Pragma("unroll") for (int _i = 0; _i < 2; ++_i) \
;         __builtin_amdgcn_global_load_lds((const unsigned*)((const char*)(gbase) + (voff)[_i]), (LAS unsigned*)(lds + (bufoff) + ldsw + _i * 8192), 16, 0, 0); } while (0)
; #define PG8_LDA(dst, b, h) do { _Pragma("unroll") for (int m = 0; m < 4; ++m) _Pragma("unroll") for (int k = 0; k < 2; ++k) dst[m][k] = *(const LAS bf16x8*)(lds + PG8_SA(b, h) + aoff + m * 2048 + k * 1024); } while (0)
; #define PG8_MMA(ai, bj, At, Bt) do { __builtin_amdgcn_s_setprio(1); _Pragma("unroll") for (int m = 0; m < 4; ++m) _Pragma("unroll") for (int n = 0; n < 2; ++n) _Pragma("unroll") for (int k = 0; k < 2; ++k) \
;         acc[ai][bj][m][n] = __builtin_amdgcn_mfma_f32_16x16x32_bf16(Bt[n][k], At[m][k], acc[ai][bj][m][n], 0, 0, 0); __builtin_amdgcn_s_setprio(0); } while (0)
; #define PG8_WAIT_V(n) asm volatile("s_waitcnt vmcnt(" #n ")" ::: "memory")
; #define PG8_WAIT_L(n) asm volatile("s_waitcnt lgkmcnt(" #n ")" ::: "memory")
; #define PG8_BAR __builtin_amdgcn_s_barrier()
; #define PG8_SCHED __builtin_amdgcn_sched_barrier(0)
; template <class Epi, class Sched>
; __device__ __forceinline__ void gemm_phase(LAS unsigned char* lds, const int K, const int lda, const int ldb, const Sched& S, const Epi& E) {
;     ...
;             PG8_LDA(At, 1, 1); PG8_STAGE(PG8_SB(1, 0), b3, voffB); PG8_STAGE(PG8_SB(1, 1), b3 + hB, voffB); PG8_STAGE(PG8_SA(1, 0), a3, voffA);
;             PG8_WAIT_V(8); PG8_WAIT_L(0); PG8_BAR; PG8_MMA(1, 0, At, B0); PG8_MMA(1, 1, At, B1); PG8_BAR; PG8_SCHED;
;         }
;         if (wr == 0) PG8_BAR;
	s_add_i32 s58, s60, s2
	v_lshl_add_u64 v[222:223], v[222:223], 0, s[26:27]
	s_mov_b32 m0, s58
	ds_read_b128 v[190:193], v145 offset:49152
	ds_read_b128 v[194:197], v248 offset:49152
	ds_read_b128 v[198:201], v145 offset:51200
	ds_read_b128 v[202:205], v248 offset:51200
	ds_read_b128 v[206:209], v145 offset:53248
	ds_read_b128 v[210:213], v248 offset:53248
	ds_read_b128 v[214:217], v145 offset:55296
	ds_read_b128 v[218:221], v248 offset:55296
	global_load_lds_dwordx4 v[222:223], off
	s_add_i32 m0, s58, 0x2000
	s_add_u32 s56, s56, 0x80080
	v_lshl_add_u64 v[222:223], v[224:225], 0, s[26:27]
	s_addc_u32 s57, s57, 0
	s_add_i32 s58, s61, s2
	global_load_lds_dwordx4 v[222:223], off
	v_lshl_add_u64 v[222:223], s[56:57], 0, v[130:131]
	s_mov_b32 m0, s58
	s_nop 0
	global_load_lds_dwordx4 v[222:223], off
	v_lshl_add_u64 v[222:223], s[56:57], 0, v[134:135]
	s_add_i32 m0, s58, 0x2000
	s_nop 0
	global_load_lds_dwordx4 v[222:223], off
	v_lshl_add_u64 v[222:223], v[226:227], 0, s[26:27]
	s_mov_b32 m0, s35
	s_nop 0
	global_load_lds_dwordx4 v[222:223], off
	v_lshl_add_u64 v[222:223], v[228:229], 0, s[26:27]
	s_mov_b32 m0, s38
	s_nop 0
	global_load_lds_dwordx4 v[222:223], off
	s_waitcnt vmcnt(8)
	s_waitcnt lgkmcnt(0)
	s_barrier
	s_waitcnt lgkmcnt(0)
	v_mfma_f32_16x16x32_bf16 v[60:63], v[158:161], v[190:193], v[60:63]
	v_mfma_f32_16x16x32_bf16 v[52:55], v[166:169], v[190:193], v[52:55]
	v_mfma_f32_16x16x32_bf16 v[44:47], v[158:161], v[198:201], v[44:47]
	v_mfma_f32_16x16x32_bf16 v[36:39], v[166:169], v[198:201], v[36:39]
	v_mfma_f32_16x16x32_bf16 v[28:31], v[158:161], v[206:209], v[28:31]
	v_mfma_f32_16x16x32_bf16 v[20:23], v[166:169], v[206:209], v[20:23]
	v_mfma_f32_16x16x32_bf16 v[12:15], v[158:161], v[214:217], v[12:15]
	v_mfma_f32_16x16x32_bf16 v[4:7], v[166:169], v[214:217], v[4:7]
	v_mfma_f32_16x16x32_bf16 v[60:63], v[162:165], v[194:197], v[60:63]
	v_mfma_f32_16x16x32_bf16 v[52:55], v[170:173], v[194:197], v[52:55]
	v_mfma_f32_16x16x32_bf16 v[44:47], v[162:165], v[202:205], v[44:47]
	v_mfma_f32_16x16x32_bf16 v[36:39], v[170:173], v[202:205], v[36:39]
	v_mfma_f32_16x16x32_bf16 v[28:31], v[162:165], v[210:213], v[28:31]
	v_mfma_f32_16x16x32_bf16 v[20:23], v[170:173], v[210:213], v[20:23]
	v_mfma_f32_16x16x32_bf16 v[12:15], v[162:165], v[218:221], v[12:15]
	v_mfma_f32_16x16x32_bf16 v[4:7], v[170:173], v[218:221], v[4:7]
	v_mfma_f32_16x16x32_bf16 v[56:59], v[174:177], v[190:193], v[56:59]
	v_mfma_f32_16x16x32_bf16 v[48:51], v[182:185], v[190:193], v[48:51]
	v_mfma_f32_16x16x32_bf16 v[40:43], v[174:177], v[198:201], v[40:43]
	v_mfma_f32_16x16x32_bf16 v[32:35], v[182:185], v[198:201], v[32:35]
	v_mfma_f32_16x16x32_bf16 v[24:27], v[174:177], v[206:209], v[24:27]
	v_mfma_f32_16x16x32_bf16 v[16:19], v[182:185], v[206:209], v[16:19]
	v_mfma_f32_16x16x32_bf16 v[8:11], v[174:177], v[214:217], v[8:11]
	v_mfma_f32_16x16x32_bf16 v[0:3], v[182:185], v[214:217], v[0:3]
	v_mfma_f32_16x16x32_bf16 v[56:59], v[178:181], v[194:197], v[56:59]
	v_mfma_f32_16x16x32_bf16 v[48:51], v[186:189], v[194:197], v[48:51]
	v_mfma_f32_16x16x32_bf16 v[40:43], v[178:181], v[202:205], v[40:43]
	v_mfma_f32_16x16x32_bf16 v[32:35], v[186:189], v[202:205], v[32:35]
	v_mfma_f32_16x16x32_bf16 v[24:27], v[178:181], v[210:213], v[24:27]
	v_mfma_f32_16x16x32_bf16 v[16:19], v[186:189], v[210:213], v[16:19]
	v_mfma_f32_16x16x32_bf16 v[8:11], v[178:181], v[218:221], v[8:11]
	v_mfma_f32_16x16x32_bf16 v[0:3], v[186:189], v[218:221], v[0:3]
	s_barrier
	s_add_i32 s55, s55, 2
	s_add_u32 s45, s45, 0x100
	s_addc_u32 s47, s47, 0
	s_add_u32 s52, s52, 0x100
	s_addc_u32 s53, s53, 0
	s_cmp_gt_u32 s55, 29
	s_cbranch_scc0 .LBB0_1448
	s_and_b64 vcc, exec, s[28:29]
	s_cbranch_vccz .LBB0_1451
	s_barrier

; #define PG8_STAGE(bufoff, gbase, voff) do { _Pragma("unroll") for (int _i = 0; _i < 2; ++_i) \
;         __builtin_amdgcn_global_load_lds((const unsigned*)((const char*)(gbase) + (voff)[_i]), (LAS unsigned*)(lds + (bufoff) + ldsw + _i * 8192), 16, 0, 0); } while (0)
; #define PG8_LDA(dst, b, h) do { _Pragma("unroll") for (int m = 0; m < 4; ++m) _Pragma("unroll") for (int k = 0; k < 2; ++k) dst[m][k] = *(const LAS bf16x8*)(lds + PG8_SA(b, h) + aoff + m * 2048 + k * 1024); } while (0)
; #define PG8_LDB(dst, b, h) do { _Pragma("unroll") for (int n = 0; n < 2; ++n) _Pragma("unroll") for (int k = 0; k < 2; ++k) dst[n][k] = *(const LAS bf16x8*)(lds + PG8_SB(b, h) + boff + n * 2048 + k * 1024); } while (0)
; #define PG8_MMA(ai, bj, At, Bt) do { __builtin_amdgcn_s_setprio(1); _Pragma("unroll") for (int m = 0; m < 4; ++m) _Pragma("unroll") for (int n = 0; n < 2; ++n) _Pragma("unroll") for (int k = 0; k < 2; ++k) \
;         acc[ai][bj][m][n] = __builtin_amdgcn_mfma_f32_16x16x32_bf16(Bt[n][k], At[m][k], acc[ai][bj][m][n], 0, 0, 0); __builtin_amdgcn_s_setprio(0); } while (0)
; #define PG8_WAIT_V(n) asm volatile("s_waitcnt vmcnt(" #n ")" ::: "memory")
; #define PG8_WAIT_L(n) asm volatile("s_waitcnt lgkmcnt(" #n ")" ::: "memory")
; #define PG8_BAR __builtin_amdgcn_s_barrier()
; #define PG8_SCHED __builtin_amdgcn_sched_barrier(0)
; template <class Epi, class Sched>
; __device__ __forceinline__ void gemm_phase(LAS unsigned char* lds, const int K, const int lda, const int ldb, const Sched& S, const Epi& E) {
;     ...
;             PG8_LDB(B0, 0, 0); PG8_LDB(B1, 0, 1); PG8_SCHED; PG8_LDA(At, 0, 0); PG8_STAGE(PG8_SA(1, 1), a1 + hA, voffA);
;             PG8_WAIT_V(8); PG8_WAIT_L(0); PG8_BAR; PG8_MMA(0, 0, At, B0); PG8_MMA(0, 1, At, B1); PG8_BAR; PG8_SCHED;
;             PG8_LDA(At, 0, 1); PG8_STAGE(PG8_SB(0, 0), b2, voffB); PG8_STAGE(PG8_SB(0, 1), b2 + hB, voffB); PG8_STAGE(PG8_SA(0, 0), a2, voffA);
;             PG8_WAIT_V(8); PG8_WAIT_L(0); PG8_BAR; PG8_MMA(1, 0, At, B0); PG8_MMA(1, 1, At, B1); PG8_BAR; PG8_SCHED;
.LBB0_1625:
	ds_read_b128 v[128:131], v197
	ds_read_b128 v[132:135], v197 offset:1024
	ds_read_b128 v[136:139], v197 offset:2048
	ds_read_b128 v[140:143], v197 offset:3072
	ds_read_b128 v[144:147], v198
	ds_read_b128 v[148:151], v198 offset:1024
	ds_read_b128 v[152:155], v198 offset:2048
	ds_read_b128 v[156:159], v198 offset:3072
	s_add_u32 s30, s28, 0xfff80080
	s_addc_u32 s31, s29, -1
	s_cmp_eq_u32 s51, 28
	s_cselect_b32 s35, s21, s31
	s_cselect_b32 s34, s47, s30
	s_cselect_b32 s31, s19, s50
	s_cselect_b32 s30, s48, s49
	v_lshl_add_u64 v[192:193], s[28:29], 0, v[174:175]
	s_add_i32 m0, s27, 0xc000
	ds_read_b128 v[160:163], v199
	ds_read_b128 v[180:183], v199 offset:1024
	ds_read_b128 v[184:187], v199 offset:2048
	ds_read_b128 v[188:191], v199 offset:3072
	ds_read_b128 v[200:203], v199 offset:4096
	ds_read_b128 v[204:207], v199 offset:5120
	ds_read_b128 v[208:211], v199 offset:6144
	ds_read_b128 v[212:215], v199 offset:7168
	global_load_lds_dwordx4 v[192:193], off
	v_lshl_add_u64 v[192:193], s[28:29], 0, v[172:173]
	s_add_i32 m0, s27, 0xe000
	s_nop 0
	global_load_lds_dwordx4 v[192:193], off
	s_waitcnt vmcnt(8)
	s_waitcnt lgkmcnt(0)
	s_barrier
	s_waitcnt lgkmcnt(0)
	v_mfma_f32_16x16x32_bf16 v[124:127], v[160:163], v[128:131], v[124:127]
	v_mfma_f32_16x16x32_bf16 v[120:123], v[160:163], v[136:139], v[120:123]
	v_mfma_f32_16x16x32_bf16 v[108:111], v[184:187], v[128:131], v[108:111]
	v_mfma_f32_16x16x32_bf16 v[104:107], v[184:187], v[136:139], v[104:107]
	v_mfma_f32_16x16x32_bf16 v[96:99], v[200:203], v[128:131], v[96:99]
	v_mfma_f32_16x16x32_bf16 v[88:91], v[200:203], v[136:139], v[88:91]
	v_mfma_f32_16x16x32_bf16 v[80:83], v[208:211], v[128:131], v[80:83]
	v_mfma_f32_16x16x32_bf16 v[72:75], v[208:211], v[136:139], v[72:75]
	v_mfma_f32_16x16x32_bf16 v[124:127], v[180:183], v[132:135], v[124:127]
	v_mfma_f32_16x16x32_bf16 v[120:123], v[180:183], v[140:143], v[120:123]
	v_mfma_f32_16x16x32_bf16 v[108:111], v[188:191], v[132:135], v[108:111]
	v_mfma_f32_16x16x32_bf16 v[104:107], v[188:191], v[140:143], v[104:107]
	v_mfma_f32_16x16x32_bf16 v[96:99], v[204:207], v[132:135], v[96:99]
	v_mfma_f32_16x16x32_bf16 v[88:91], v[204:207], v[140:143], v[88:91]
	v_mfma_f32_16x16x32_bf16 v[80:83], v[212:215], v[132:135], v[80:83]
	v_mfma_f32_16x16x32_bf16 v[72:75], v[212:215], v[140:143], v[72:75]
	v_mfma_f32_16x16x32_bf16 v[116:119], v[160:163], v[144:147], v[116:119]
	v_mfma_f32_16x16x32_bf16 v[112:115], v[160:163], v[152:155], v[112:115]
	v_mfma_f32_16x16x32_bf16 v[100:103], v[184:187], v[144:147], v[100:103]
	v_mfma_f32_16x16x32_bf16 v[92:95], v[184:187], v[152:155], v[92:95]
	v_mfma_f32_16x16x32_bf16 v[84:87], v[200:203], v[144:147], v[84:87]
	v_mfma_f32_16x16x32_bf16 v[76:79], v[200:203], v[152:155], v[76:79]
	v_mfma_f32_16x16x32_bf16 v[68:71], v[208:211], v[144:147], v[68:71]
	v_mfma_f32_16x16x32_bf16 v[64:67], v[208:211], v[152:155], v[64:67]
	v_mfma_f32_16x16x32_bf16 v[116:119], v[180:183], v[148:151], v[116:119]
	v_mfma_f32_16x16x32_bf16 v[112:115], v[180:183], v[156:159], v[112:115]
	v_mfma_f32_16x16x32_bf16 v[100:103], v[188:191], v[148:151], v[100:103]
	v_mfma_f32_16x16x32_bf16 v[92:95], v[188:191], v[156:159], v[92:95]
	v_mfma_f32_16x16x32_bf16 v[84:87], v[204:207], v[148:151], v[84:87]
	v_mfma_f32_16x16x32_bf16 v[76:79], v[204:207], v[156:159], v[76:79]
	v_mfma_f32_16x16x32_bf16 v[68:71], v[212:215], v[148:151], v[68:71]
	v_mfma_f32_16x16x32_bf16 v[64:67], v[212:215], v[156:159], v[64:67]
	s_barrier
	s_add_i32 s52, s44, s36
	v_lshl_add_u64 v[192:193], s[30:31], 0, v[166:167]
	s_mov_b32 m0, s52
	ds_read_b128 v[160:163], v199 offset:16384
	ds_read_b128 v[180:183], v199 offset:17408
	ds_read_b128 v[184:187], v199 offset:18432
	ds_read_b128 v[188:191], v199 offset:19456
	ds_read_b128 v[200:203], v199 offset:20480
	ds_read_b128 v[204:207], v199 offset:21504
	ds_read_b128 v[208:211], v199 offset:22528
	ds_read_b128 v[212:215], v199 offset:23552
	global_load_lds_dwordx4 v[192:193], off
	s_add_i32 m0, s52, 0x2000
	s_add_u32 s52, s30, 0x80000
	v_lshl_add_u64 v[216:217], s[30:31], 0, v[170:171]
	s_addc_u32 s53, s31, 0
	s_add_i32 s54, s45, s36
	global_load_lds_dwordx4 v[216:217], off
	v_lshl_add_u64 v[218:219], s[52:53], 0, v[166:167]
	s_mov_b32 m0, s54
	v_lshl_add_u64 v[220:221], s[34:35], 0, v[168:169]
	global_load_lds_dwordx4 v[218:219], off
	v_lshl_add_u64 v[218:219], s[52:53], 0, v[170:171]
	s_add_i32 m0, s54, 0x2000
	s_nop 0
	global_load_lds_dwordx4 v[218:219], off
	v_lshl_add_u64 v[218:219], s[34:35], 0, v[164:165]
	s_mov_b32 m0, s27
	s_nop 0
	global_load_lds_dwordx4 v[218:219], off
	s_mov_b32 m0, s37
	s_nop 0
	global_load_lds_dwordx4 v[220:221], off
	s_waitcnt vmcnt(8)
	s_waitcnt lgkmcnt(0)
	s_barrier
; #define PG8_STAGE(bufoff, gbase, voff) do { _Pragma("unroll") for (int _i = 0; _i < 2; ++_i) \
;         __builtin_amdgcn_global_load_lds((const unsigned*)((const char*)(gbase) + (voff)[_i]), (LAS unsigned*)(lds + (bufoff) + ldsw + _i * 8192), 16, 0, 0); } while (0)
; #define PG8_LDA(dst, b, h) do { _Pragma("unroll") for (int m = 0; m < 4; ++m) _Pragma("unroll") for (int k = 0; k < 2; ++k) dst[m][k] = *(const LAS bf16x8*)(lds + PG8_SA(b, h) + aoff + m * 2048 + k * 1024); } while (0)
; #define PG8_LDB(dst, b, h) do { _Pragma("unroll") for (int n = 0; n < 2; ++n) _Pragma("unroll") for (int k = 0; k < 2; ++k) dst[n][k] = *(const LAS bf16x8*)(lds + PG8_SB(b, h) + boff + n * 2048 + k * 1024); } while (0)
; #define PG8_MMA(ai, bj, At, Bt) do { __builtin_amdgcn_s_setprio(1); _Pragma("unroll") for (int m = 0; m < 4; ++m) _Pragma("unroll") for (int n = 0; n < 2; ++n) _Pragma("unroll") for (int k = 0; k < 2; ++k) \
;         acc[ai][bj][m][n] = __builtin_amdgcn_mfma_f32_16x16x32_bf16(Bt[n][k], At[m][k], acc[ai][bj][m][n], 0, 0, 0); __builtin_amdgcn_s_setprio(0); } while (0)
; #define PG8_WAIT_V(n) asm volatile("s_waitcnt vmcnt(" #n ")" ::: "memory")
; #define PG8_WAIT_L(n) asm volatile("s_waitcnt lgkmcnt(" #n ")" ::: "memory")
; #define PG8_BAR __builtin_amdgcn_s_barrier()
; #define PG8_SCHED __builtin_amdgcn_sched_barrier(0)
; template <class Epi, class Sched>
; __device__ __forceinline__ void gemm_phase(LAS unsigned char* lds, const int K, const int lda, const int ldb, const Sched& S, const Epi& E) {
;     ...
;             PG8_WAIT_V(8); PG8_WAIT_L(0); PG8_BAR; PG8_MMA(1, 0, At, B0); PG8_MMA(1, 1, At, B1); PG8_BAR; PG8_SCHED;
;             PG8_LDB(B0, 1, 0); PG8_LDB(B1, 1, 1); PG8_SCHED; PG8_LDA(At, 1, 0); PG8_STAGE(PG8_SA(0, 1), a2 + hA, voffA);
;             PG8_WAIT_V(8); PG8_WAIT_L(0); PG8_BAR; PG8_MMA(0, 0, At, B0); PG8_MMA(0, 1, At, B1); PG8_BAR; PG8_SCHED;
	s_waitcnt lgkmcnt(0)
	v_mfma_f32_16x16x32_bf16 v[60:63], v[160:163], v[128:131], v[60:63]
	v_mfma_f32_16x16x32_bf16 v[56:59], v[160:163], v[136:139], v[56:59]
	v_mfma_f32_16x16x32_bf16 v[48:51], v[184:187], v[128:131], v[48:51]
	v_mfma_f32_16x16x32_bf16 v[40:43], v[184:187], v[136:139], v[40:43]
	v_mfma_f32_16x16x32_bf16 v[32:35], v[200:203], v[128:131], v[32:35]
	v_mfma_f32_16x16x32_bf16 v[24:27], v[200:203], v[136:139], v[24:27]
	v_mfma_f32_16x16x32_bf16 v[16:19], v[208:211], v[128:131], v[16:19]
	v_mfma_f32_16x16x32_bf16 v[8:11], v[208:211], v[136:139], v[8:11]
	v_mfma_f32_16x16x32_bf16 v[60:63], v[180:183], v[132:135], v[60:63]
	v_mfma_f32_16x16x32_bf16 v[56:59], v[180:183], v[140:143], v[56:59]
	v_mfma_f32_16x16x32_bf16 v[48:51], v[188:191], v[132:135], v[48:51]
	v_mfma_f32_16x16x32_bf16 v[40:43], v[188:191], v[140:143], v[40:43]
	v_mfma_f32_16x16x32_bf16 v[32:35], v[204:207], v[132:135], v[32:35]
	v_mfma_f32_16x16x32_bf16 v[24:27], v[204:207], v[140:143], v[24:27]
	v_mfma_f32_16x16x32_bf16 v[16:19], v[212:215], v[132:135], v[16:19]
	v_mfma_f32_16x16x32_bf16 v[8:11], v[212:215], v[140:143], v[8:11]
	v_mfma_f32_16x16x32_bf16 v[52:55], v[160:163], v[144:147], v[52:55]
	v_mfma_f32_16x16x32_bf16 v[44:47], v[160:163], v[152:155], v[44:47]
	v_mfma_f32_16x16x32_bf16 v[36:39], v[184:187], v[144:147], v[36:39]
	v_mfma_f32_16x16x32_bf16 v[28:31], v[184:187], v[152:155], v[28:31]
	v_mfma_f32_16x16x32_bf16 v[20:23], v[200:203], v[144:147], v[20:23]
	v_mfma_f32_16x16x32_bf16 v[12:15], v[200:203], v[152:155], v[12:15]
	v_mfma_f32_16x16x32_bf16 v[4:7], v[208:211], v[144:147], v[4:7]
	v_mfma_f32_16x16x32_bf16 v[0:3], v[208:211], v[152:155], v[0:3]
	v_mfma_f32_16x16x32_bf16 v[52:55], v[180:183], v[148:151], v[52:55]
	v_mfma_f32_16x16x32_bf16 v[44:47], v[180:183], v[156:159], v[44:47]
	v_mfma_f32_16x16x32_bf16 v[36:39], v[188:191], v[148:151], v[36:39]
	v_mfma_f32_16x16x32_bf16 v[28:31], v[188:191], v[156:159], v[28:31]
	v_mfma_f32_16x16x32_bf16 v[20:23], v[204:207], v[148:151], v[20:23]
	v_mfma_f32_16x16x32_bf16 v[12:15], v[204:207], v[156:159], v[12:15]
	v_mfma_f32_16x16x32_bf16 v[4:7], v[212:215], v[148:151], v[4:7]
	v_mfma_f32_16x16x32_bf16 v[0:3], v[212:215], v[156:159], v[0:3]
	s_barrier
	s_add_i32 s52, 0, 0x18000
	s_add_i32 s53, 0, 0x1c000
	v_add_u32_e32 v140, s52, v195
	v_add_u32_e32 v156, 0x19000, v195
	ds_read_b128 v[128:131], v140
	ds_read_b128 v[132:135], v140 offset:1024
	ds_read_b128 v[136:139], v140 offset:2048
	ds_read_b128 v[140:143], v140 offset:3072
	ds_read_b128 v[144:147], v156
	ds_read_b128 v[148:151], v156 offset:1024
	ds_read_b128 v[152:155], v156 offset:2048
	ds_read_b128 v[156:159], v156 offset:3072
	s_add_u32 s34, s34, 0x80000
	s_addc_u32 s35, s35, 0
	s_mov_b32 m0, s38
	v_lshl_add_u64 v[222:223], s[34:35], 0, v[164:165]
	ds_read_b128 v[160:163], v199 offset:32768
	ds_read_b128 v[180:183], v199 offset:33792
	ds_read_b128 v[184:187], v199 offset:34816
	ds_read_b128 v[188:191], v199 offset:35840
	ds_read_b128 v[200:203], v199 offset:36864
	ds_read_b128 v[204:207], v199 offset:37888
	ds_read_b128 v[208:211], v199 offset:38912
	ds_read_b128 v[212:215], v199 offset:39936
	global_load_lds_dwordx4 v[222:223], off
	v_lshl_add_u64 v[222:223], s[34:35], 0, v[168:169]
	s_mov_b32 m0, s39
	s_nop 0
	global_load_lds_dwordx4 v[222:223], off
	s_waitcnt vmcnt(8)
	s_waitcnt lgkmcnt(0)
	s_barrier
	s_waitcnt lgkmcnt(0)
	v_mfma_f32_16x16x32_bf16 v[124:127], v[160:163], v[128:131], v[124:127]
	v_mfma_f32_16x16x32_bf16 v[120:123], v[160:163], v[136:139], v[120:123]
	v_mfma_f32_16x16x32_bf16 v[108:111], v[184:187], v[128:131], v[108:111]
	v_mfma_f32_16x16x32_bf16 v[104:107], v[184:187], v[136:139], v[104:107]
	v_mfma_f32_16x16x32_bf16 v[96:99], v[200:203], v[128:131], v[96:99]
	v_mfma_f32_16x16x32_bf16 v[88:91], v[200:203], v[136:139], v[88:91]
	v_mfma_f32_16x16x32_bf16 v[80:83], v[208:211], v[128:131], v[80:83]
	v_mfma_f32_16x16x32_bf16 v[72:75], v[208:211], v[136:139], v[72:75]
	v_mfma_f32_16x16x32_bf16 v[124:127], v[180:183], v[132:135], v[124:127]
	v_mfma_f32_16x16x32_bf16 v[120:123], v[180:183], v[140:143], v[120:123]
	v_mfma_f32_16x16x32_bf16 v[108:111], v[188:191], v[132:135], v[108:111]
	v_mfma_f32_16x16x32_bf16 v[104:107], v[188:191], v[140:143], v[104:107]
	v_mfma_f32_16x16x32_bf16 v[96:99], v[204:207], v[132:135], v[96:99]
	v_mfma_f32_16x16x32_bf16 v[88:91], v[204:207], v[140:143], v[88:91]
	v_mfma_f32_16x16x32_bf16 v[80:83], v[212:215], v[132:135], v[80:83]
	v_mfma_f32_16x16x32_bf16 v[72:75], v[212:215], v[140:143], v[72:75]
	v_mfma_f32_16x16x32_bf16 v[116:119], v[160:163], v[144:147], v[116:119]
	v_mfma_f32_16x16x32_bf16 v[112:115], v[160:163], v[152:155], v[112:115]
	v_mfma_f32_16x16x32_bf16 v[100:103], v[184:187], v[144:147], v[100:103]
	v_mfma_f32_16x16x32_bf16 v[92:95], v[184:187], v[152:155], v[92:95]
	v_mfma_f32_16x16x32_bf16 v[84:87], v[200:203], v[144:147], v[84:87]
	v_mfma_f32_16x16x32_bf16 v[76:79], v[200:203], v[152:155], v[76:79]
	v_mfma_f32_16x16x32_bf16 v[68:71], v[208:211], v[144:147], v[68:71]
	v_mfma_f32_16x16x32_bf16 v[64:67], v[208:211], v[152:155], v[64:67]
	v_mfma_f32_16x16x32_bf16 v[116:119], v[180:183], v[148:151], v[116:119]
	v_mfma_f32_16x16x32_bf16 v[112:115], v[180:183], v[156:159], v[112:115]
	v_mfma_f32_16x16x32_bf16 v[100:103], v[188:191], v[148:151], v[100:103]
	v_mfma_f32_16x16x32_bf16 v[92:95], v[188:191], v[156:159], v[92:95]
	v_mfma_f32_16x16x32_bf16 v[84:87], v[204:207], v[148:151], v[84:87]
	v_mfma_f32_16x16x32_bf16 v[76:79], v[204:207], v[156:159], v[76:79]
	v_mfma_f32_16x16x32_bf16 v[68:71], v[212:215], v[148:151], v[68:71]
	v_mfma_f32_16x16x32_bf16 v[64:67], v[212:215], v[156:159], v[64:67]
	s_barrier
; #define PG8_STAGE(bufoff, gbase, voff) do { _Pragma("unroll") for (int _i = 0; _i < 2; ++_i) \
;         __builtin_amdgcn_global_load_lds((const unsigned*)((const char*)(gbase) + (voff)[_i]), (LAS unsigned*)(lds + (bufoff) + ldsw + _i * 8192), 16, 0, 0); } while (0)
; #define PG8_LDA(dst, b, h) do { _Pragma("unroll") for (int m = 0; m < 4; ++m) _Pragma("unroll") for (int k = 0; k < 2; ++k) dst[m][k] = *(const LAS bf16x8*)(lds + PG8_SA(b, h) + aoff + m * 2048 + k * 1024); } while (0)
; #define PG8_MMA(ai, bj, At, Bt) do { __builtin_amdgcn_s_setprio(1); _Pragma("unroll") for (int m = 0; m < 4; ++m) _Pragma("unroll") for (int n = 0; n < 2; ++n) _Pragma("unroll") for (int k = 0; k < 2; ++k) \
;         acc[ai][bj][m][n] = __builtin_amdgcn_mfma_f32_16x16x32_bf16(Bt[n][k], At[m][k], acc[ai][bj][m][n], 0, 0, 0); __builtin_amdgcn_s_setprio(0); } while (0)
; #define PG8_WAIT_V(n) asm volatile("s_waitcnt vmcnt(" #n ")" ::: "memory")
; #define PG8_WAIT_L(n) asm volatile("s_waitcnt lgkmcnt(" #n ")" ::: "memory")
; #define PG8_BAR __builtin_amdgcn_s_barrier()
; #define PG8_SCHED __builtin_amdgcn_sched_barrier(0)
; template <class Epi, class Sched>
; __device__ __forceinline__ void gemm_phase(LAS unsigned char* lds, const int K, const int lda, const int ldb, const Sched& S, const Epi& E) {
;     ...
;             PG8_LDA(At, 1, 1); PG8_STAGE(PG8_SB(1, 0), b3, voffB); PG8_STAGE(PG8_SB(1, 1), b3 + hB, voffB); PG8_STAGE(PG8_SA(1, 0), a3, voffA);
;             PG8_WAIT_V(8); PG8_WAIT_L(0); PG8_BAR; PG8_MMA(1, 0, At, B0); PG8_MMA(1, 1, At, B1); PG8_BAR; PG8_SCHED;
;         }
;         if (wr == 0) PG8_BAR;
	s_add_i32 s34, s52, s36
	v_lshl_add_u64 v[192:193], v[192:193], 0, s[10:11]
	s_mov_b32 m0, s34
	ds_read_b128 v[160:163], v199 offset:49152
	ds_read_b128 v[180:183], v199 offset:50176
	ds_read_b128 v[184:187], v199 offset:51200
	ds_read_b128 v[188:191], v199 offset:52224
	ds_read_b128 v[200:203], v199 offset:53248
	ds_read_b128 v[204:207], v199 offset:54272
	ds_read_b128 v[208:211], v199 offset:55296
	ds_read_b128 v[212:215], v199 offset:56320
	global_load_lds_dwordx4 v[192:193], off
	s_add_i32 m0, s34, 0x2000
	s_add_u32 s30, s30, 0x80080
	v_lshl_add_u64 v[192:193], v[216:217], 0, s[10:11]
	s_addc_u32 s31, s31, 0
	s_add_i32 s34, s53, s36
	global_load_lds_dwordx4 v[192:193], off
	v_lshl_add_u64 v[192:193], s[30:31], 0, v[166:167]
	s_mov_b32 m0, s34
	s_nop 0
	global_load_lds_dwordx4 v[192:193], off
	v_lshl_add_u64 v[192:193], s[30:31], 0, v[170:171]
	s_add_i32 m0, s34, 0x2000
	s_nop 0
	global_load_lds_dwordx4 v[192:193], off
	v_lshl_add_u64 v[192:193], v[218:219], 0, s[10:11]
	s_mov_b32 m0, s41
	s_nop 0
	global_load_lds_dwordx4 v[192:193], off
	v_lshl_add_u64 v[192:193], v[220:221], 0, s[10:11]
	s_mov_b32 m0, s42
	s_nop 0
	global_load_lds_dwordx4 v[192:193], off
	s_waitcnt vmcnt(8)
	s_waitcnt lgkmcnt(0)
	s_barrier
	s_waitcnt lgkmcnt(0)
	v_mfma_f32_16x16x32_bf16 v[60:63], v[160:163], v[128:131], v[60:63]
	v_mfma_f32_16x16x32_bf16 v[56:59], v[160:163], v[136:139], v[56:59]
	v_mfma_f32_16x16x32_bf16 v[48:51], v[184:187], v[128:131], v[48:51]
	v_mfma_f32_16x16x32_bf16 v[40:43], v[184:187], v[136:139], v[40:43]
	v_mfma_f32_16x16x32_bf16 v[32:35], v[200:203], v[128:131], v[32:35]
	v_mfma_f32_16x16x32_bf16 v[24:27], v[200:203], v[136:139], v[24:27]
	v_mfma_f32_16x16x32_bf16 v[16:19], v[208:211], v[128:131], v[16:19]
	v_mfma_f32_16x16x32_bf16 v[8:11], v[208:211], v[136:139], v[8:11]
	v_mfma_f32_16x16x32_bf16 v[60:63], v[180:183], v[132:135], v[60:63]
	v_mfma_f32_16x16x32_bf16 v[56:59], v[180:183], v[140:143], v[56:59]
	v_mfma_f32_16x16x32_bf16 v[48:51], v[188:191], v[132:135], v[48:51]
	v_mfma_f32_16x16x32_bf16 v[40:43], v[188:191], v[140:143], v[40:43]
	v_mfma_f32_16x16x32_bf16 v[32:35], v[204:207], v[132:135], v[32:35]
	v_mfma_f32_16x16x32_bf16 v[24:27], v[204:207], v[140:143], v[24:27]
	v_mfma_f32_16x16x32_bf16 v[16:19], v[212:215], v[132:135], v[16:19]
	v_mfma_f32_16x16x32_bf16 v[8:11], v[212:215], v[140:143], v[8:11]
	v_mfma_f32_16x16x32_bf16 v[52:55], v[160:163], v[144:147], v[52:55]
	v_mfma_f32_16x16x32_bf16 v[44:47], v[160:163], v[152:155], v[44:47]
	v_mfma_f32_16x16x32_bf16 v[36:39], v[184:187], v[144:147], v[36:39]
	v_mfma_f32_16x16x32_bf16 v[28:31], v[184:187], v[152:155], v[28:31]
	v_mfma_f32_16x16x32_bf16 v[20:23], v[200:203], v[144:147], v[20:23]
	v_mfma_f32_16x16x32_bf16 v[12:15], v[200:203], v[152:155], v[12:15]
	v_mfma_f32_16x16x32_bf16 v[4:7], v[208:211], v[144:147], v[4:7]
	v_mfma_f32_16x16x32_bf16 v[0:3], v[208:211], v[152:155], v[0:3]
	v_mfma_f32_16x16x32_bf16 v[52:55], v[180:183], v[148:151], v[52:55]
	v_mfma_f32_16x16x32_bf16 v[44:47], v[180:183], v[156:159], v[44:47]
	v_mfma_f32_16x16x32_bf16 v[36:39], v[188:191], v[148:151], v[36:39]
	v_mfma_f32_16x16x32_bf16 v[28:31], v[188:191], v[156:159], v[28:31]
	v_mfma_f32_16x16x32_bf16 v[20:23], v[204:207], v[148:151], v[20:23]
	v_mfma_f32_16x16x32_bf16 v[12:15], v[204:207], v[156:159], v[12:15]
	v_mfma_f32_16x16x32_bf16 v[4:7], v[212:215], v[148:151], v[4:7]
	v_mfma_f32_16x16x32_bf16 v[0:3], v[212:215], v[156:159], v[0:3]
	s_barrier
	s_add_i32 s51, s51, 2
	s_add_u32 s49, s49, 0x100
	s_addc_u32 s50, s50, 0
	s_add_u32 s28, s28, 0x100
	s_addc_u32 s29, s29, 0
	s_cmp_gt_u32 s51, 29
	s_cbranch_scc0 .LBB0_1625
	s_and_b64 vcc, exec, s[14:15]
	s_cbranch_vccz .LBB0_1628
	s_barrier
